# kargpre: kernel arguments parked in v255 lanes at entry; all 47 later kernarg s_loads (phase tops, epilogue pointer chains) replaced by v_readlane; on top of xbpre
# baseline (speedup 1.0000x reference)
_ZN12_GLOBAL__N_12mkENS_6ParamsE:
	s_mov_b64 s[26:27], s[0:1]
	s_load_dwordx16 s[60:75], s[0:1], 0x0
	s_load_dwordx16 s[76:91], s[0:1], 0x40
	s_load_dwordx16 s[4:19], s[0:1], 0x80
	s_load_dwordx8 s[28:35], s[0:1], 0xc0
	s_waitcnt lgkmcnt(0)
	v_writelane_b32 v255, s60, 6
	v_writelane_b32 v255, s61, 7
	v_writelane_b32 v255, s62, 8
	v_writelane_b32 v255, s63, 9
	v_writelane_b32 v255, s64, 10
	v_writelane_b32 v255, s65, 11
	v_writelane_b32 v255, s66, 12
	v_writelane_b32 v255, s67, 13
	v_writelane_b32 v255, s68, 14
	v_writelane_b32 v255, s69, 15
	v_writelane_b32 v255, s70, 16
	v_writelane_b32 v255, s71, 17
	v_writelane_b32 v255, s72, 18
	v_writelane_b32 v255, s73, 19
	v_writelane_b32 v255, s74, 20
	v_writelane_b32 v255, s75, 21
	v_writelane_b32 v255, s76, 22
	v_writelane_b32 v255, s77, 23
	v_writelane_b32 v255, s78, 24
	v_writelane_b32 v255, s79, 25
	v_writelane_b32 v255, s80, 26
	v_writelane_b32 v255, s81, 27
	v_writelane_b32 v255, s82, 28
	v_writelane_b32 v255, s83, 29
	v_writelane_b32 v255, s84, 30
	v_writelane_b32 v255, s85, 31
	v_writelane_b32 v255, s86, 32
	v_writelane_b32 v255, s87, 33
	v_writelane_b32 v255, s88, 34
	v_writelane_b32 v255, s89, 35
	v_writelane_b32 v255, s90, 36
	v_writelane_b32 v255, s91, 37
	v_writelane_b32 v255, s4, 38
	v_writelane_b32 v255, s5, 39
	v_writelane_b32 v255, s6, 40
	v_writelane_b32 v255, s7, 41
	v_writelane_b32 v255, s8, 42
	v_writelane_b32 v255, s9, 43
	v_writelane_b32 v255, s10, 44
	v_writelane_b32 v255, s11, 45
	v_writelane_b32 v255, s12, 46
	v_writelane_b32 v255, s13, 47
	v_writelane_b32 v255, s14, 48
	v_writelane_b32 v255, s15, 49
	v_writelane_b32 v255, s16, 50
	v_writelane_b32 v255, s17, 51
	v_writelane_b32 v255, s18, 52
	v_writelane_b32 v255, s19, 53
	v_writelane_b32 v255, s28, 54
	v_writelane_b32 v255, s29, 55
	v_writelane_b32 v255, s30, 56
	v_writelane_b32 v255, s31, 57
	v_writelane_b32 v255, s32, 58
	v_writelane_b32 v255, s33, 59
	v_writelane_b32 v255, s34, 60
	v_writelane_b32 v255, s35, 61
	s_load_dwordx4 s[56:59], s[0:1], 0xd8
	s_load_dwordx2 s[46:47], s[0:1], 0xe8
	s_add_u32 s0, s26, 0xe8
	s_addc_u32 s1, s27, 0
	v_and_b32_e32 v244, 0x3ff, v0
	v_writelane_b32 v254, s0, 0
	s_mov_b32 s78, s2
	v_cmp_gt_u32_e32 vcc, 16, v244
	v_writelane_b32 v254, s1, 1
	s_and_saveexec_b64 s[0:1], vcc
	v_lshl_add_u32 v1, v244, 2, 0
	v_add_u32_e32 v1, 0x23fc0, v1
	v_mov_b32_e32 v2, 0
	ds_write_b32 v1, v2
	s_or_b64 exec, exec, s[0:1]
	s_waitcnt lgkmcnt(0)
	s_barrier
	s_add_u32 s0, s56, 0xf500000
	s_getreg_b32 s2, hwreg(HW_REG_XCC_ID, 0, 4)
	s_addc_u32 s1, s57, 0
	s_and_b32 s6, s2, 15
	v_cmp_eq_u32_e64 s[22:23], 0, v244
	s_and_saveexec_b64 s[2:3], s[22:23]
	s_cbranch_execz .LBB0_5
	s_mov_b64 s[4:5], exec
	v_mbcnt_lo_u32_b32 v1, s4, 0
	v_mbcnt_hi_u32_b32 v1, s5, v1
	v_cmp_eq_u32_e32 vcc, 0, v1
	s_and_b64 s[8:9], exec, vcc
	s_mov_b64 exec, s[8:9]
	s_cbranch_execz .LBB0_5
	s_lshl_b32 s7, s6, 8
	s_bcnt1_i32_b64 s4, s[4:5]
	v_mov_b32_e32 v1, s7
	v_mov_b32_e32 v2, s4
	global_atomic_add v1, v2, s[0:1] offset:1024

.LBB0_18:
	s_and_b64 vcc, exec, s[4:5]
	s_cbranch_vccz .LBB0_10
	v_readlane_b32 s96, v255, 60
	v_readlane_b32 s97, v255, 61
	s_nop 4
	s_mul_i32 s4, s58, 0x440
	s_mov_b64 s[8:9], -1
	s_waitcnt lgkmcnt(0)
	s_add_u32 s6, s96, 0xf514000
	s_addc_u32 s7, s97, 0
	s_ashr_i32 s5, s4, 31
	s_lshl_b64 s[4:5], s[4:5], 2
	v_writelane_b32 v254, s6, 21
	s_add_u32 s6, s6, s4
	v_writelane_b32 v254, s7, 22
	s_addc_u32 s7, s7, s5
	s_and_b64 vcc, exec, s[2:3]
	s_mov_b64 s[2:3], -1
	s_cbranch_vccz .LBB0_21
	s_cmp_lg_u32 s58, 0
	s_cselect_b64 s[2:3], -1, 0
	v_writelane_b32 v254, s2, 23
	s_add_i32 s16, s58, -2
	s_nop 0
	v_writelane_b32 v254, s3, 24
	s_mov_b64 s[2:3], 0

.LBB0_28:
	s_add_u32 s68, s96, 0x100000
	v_writelane_b32 v254, s2, 25
	s_addc_u32 s69, s97, 0
	s_mov_b32 s60, s46
	v_writelane_b32 v254, s3, 26
	s_add_u32 s2, s96, 0x188000
	v_writelane_b32 v254, s8, 27
	s_addc_u32 s3, s97, 0
	s_add_u32 s92, s96, 0x5400000
	v_writelane_b32 v254, s9, 28
	v_writelane_b32 v254, s6, 29
	s_addc_u32 s93, s97, 0
	s_add_u32 s64, s96, 0x1c0000
	v_writelane_b32 v254, s7, 30
	v_writelane_b32 v254, s2, 31
	s_addc_u32 s65, s97, 0
	s_mov_b32 s94, s78
	v_writelane_b32 v254, s3, 32
	s_add_u32 s2, s96, 0x400000
	s_addc_u32 s3, s97, 0
	v_writelane_b32 v254, s2, 33
	s_mov_b64 s[6:7], -1
	s_mov_b64 s[4:5], 0
	v_writelane_b32 v254, s3, 34
	s_add_u32 s2, s96, 0x182000
	s_addc_u32 s3, s97, 0
	v_writelane_b32 v254, s2, 35
	s_cmp_lt_i32 s58, 1
	s_nop 0
	v_writelane_b32 v254, s3, 36
	s_mov_b64 s[2:3], 0
	s_cbranch_scc1 .LBB0_41
	s_cmp_eq_u32 s58, 1
	s_mov_b64 s[4:5], -1
	s_cbranch_scc0 .LBB0_40
	s_waitcnt vmcnt(0)
	v_mov_b32_e32 v2, v244
	s_mov_b32 s4, s78
	s_mov_b32 s5, s46
	s_lshl_b32 s5, s5, 3
	s_abs_i32 s6, s5
	v_cvt_f32_u32_e32 v0, s6
	v_readfirstlane_b32 s7, v2
	s_sub_i32 s8, 0, s6
	s_lshl_b32 s4, s4, 3
	v_rcp_iflag_f32_e32 v0, v0
	s_ashr_i32 s7, s7, 6
	s_add_i32 s4, s4, s7
	s_add_i32 s7, s5, 0x41ff
	v_mul_f32_e32 v0, 0x4f7ffffe, v0
	v_cvt_u32_f32_e32 v0, v0
	s_xor_b32 s5, s7, s5
	s_abs_i32 s7, s7
	s_ashr_i32 s5, s5, 31
	v_readfirstlane_b32 s9, v0
	s_mul_i32 s8, s8, s9
	s_mul_hi_u32 s8, s9, s8
	s_add_i32 s9, s9, s8
	s_mul_hi_u32 s8, s7, s9
	s_mul_i32 s9, s8, s6
	s_sub_i32 s7, s7, s9
	s_add_i32 s9, s8, 1
	s_sub_i32 s10, s7, s6
	s_cmp_ge_u32 s7, s6
	s_cselect_b32 s8, s9, s8
	s_cselect_b32 s7, s10, s7
	s_add_i32 s9, s8, 1
	s_cmp_ge_u32 s7, s6
	s_cselect_b32 s6, s9, s8
	s_xor_b32 s6, s6, s5
	s_sub_i32 s5, s6, s5
	s_mul_i32 s4, s4, s5
	s_add_i32 s5, s4, s5
	s_min_i32 s17, s5, 0x4200
	s_cmp_ge_i32 s4, s17
	s_cbranch_scc1 .LBB0_39
	v_readlane_b32 s8, v255, 6
	v_readlane_b32 s9, v255, 7
	s_nop 4
	v_readlane_b32 s6, v255, 18
	v_readlane_b32 s7, v255, 19
	s_nop 4
	v_readlane_b32 s10, v255, 10
	v_readlane_b32 s11, v255, 11
	s_nop 4
	v_lshlrev_b32_e32 v0, 2, v2
	v_and_b32_e32 v16, 0xfc, v0
	v_lshlrev_b32_e32 v0, 2, v16
	s_ashr_i32 s5, s4, 31
	s_waitcnt lgkmcnt(0)
	v_lshl_add_u64 v[66:67], s[6:7], 0, v[0:1]
	v_lshlrev_b32_e32 v0, 1, v16
	s_lshl_b64 s[6:7], s[4:5], 11
	v_lshl_add_u64 v[74:75], s[92:93], 0, v[0:1]
	v_and_b32_e32 v0, 63, v2
	s_add_u32 s6, s92, s6
	v_lshlrev_b32_e32 v0, 3, v0
	s_addc_u32 s7, s93, s7
	v_mov_b32_e32 v2, v1
	v_mov_b32_e32 v3, v1
	v_mov_b32_e32 v4, v1
	v_mov_b32_e32 v5, v1
	v_mov_b32_e32 v6, v1
	v_mov_b32_e32 v7, v1
	v_mov_b32_e32 v8, v1
	v_mov_b32_e32 v9, v1
	v_mov_b32_e32 v10, v1
	v_mov_b32_e32 v11, v1
	v_mov_b32_e32 v12, v1
	v_mov_b32_e32 v13, v1
	v_mov_b32_e32 v14, v1
	v_mov_b32_e32 v15, v1
	v_or_b32_e32 v68, 0x100, v16
	v_or_b32_e32 v70, 0x200, v16
	v_or_b32_e32 v72, 0x300, v16
	v_lshl_add_u64 v[76:77], s[6:7], 0, v[0:1]
	v_mov_b32_e32 v0, v1
	v_mov_b32_e32 v18, 0
	v_lshlrev_b32_e32 v69, 2, v16
	v_mov_b64_e32 v[16:17], v[14:15]
	s_mov_b32 s18, -1
	v_mov_b64_e32 v[14:15], v[12:13]
	v_mov_b64_e32 v[12:13], v[10:11]
	v_mov_b64_e32 v[10:11], v[8:9]
	v_mov_b64_e32 v[8:9], v[6:7]
	v_mov_b64_e32 v[6:7], v[4:5]
	v_mov_b64_e32 v[4:5], v[2:3]
	v_mov_b64_e32 v[2:3], v[0:1]
	v_mov_b32_e32 v19, v18
	v_mov_b32_e32 v20, v18
	v_mov_b32_e32 v21, v18
	v_mov_b32_e32 v22, v18
	v_mov_b32_e32 v23, v18
	v_mov_b32_e32 v24, v18
	v_mov_b32_e32 v25, v18
	v_mov_b32_e32 v26, v18
	v_mov_b32_e32 v27, v18
	v_mov_b32_e32 v28, v18
	v_mov_b32_e32 v29, v18
	v_mov_b32_e32 v46, v18
	v_mov_b32_e32 v47, v18
	v_mov_b32_e32 v48, v18
	v_mov_b32_e32 v49, v18
	s_branch .LBB0_34

.LBB0_43:
	s_andn2_b64 vcc, exec, s[4:5]
	s_mov_b64 s[4:5], 0
	v_writelane_b32 v254, s4, 37
	s_nop 1
	v_writelane_b32 v254, s5, 38
	s_cbranch_vccnz .LBB0_1018
	s_add_u32 s82, s96, 0x7500000
	s_mul_hi_i32 s2, s16, 0x2aaaaaab
	s_addc_u32 s83, s97, 0
	s_lshr_b32 s3, s2, 31
	s_ashr_i32 s2, s2, 1
	s_add_i32 s2, s2, s3
	s_mul_i32 s3, s2, 12
	s_sub_i32 s52, s16, s3
	s_cmp_lt_i32 s58, 14
	s_cselect_b64 s[4:5], -1, 0
	v_writelane_b32 v254, s4, 39
	s_cmp_gt_i32 s58, 13
	s_mul_i32 s6, s2, 0x2800000
	v_writelane_b32 v254, s5, 40
	s_cselect_b64 s[4:5], -1, 0
	v_readlane_b32 s8, v254, 33
	s_mul_hi_i32 s3, s2, 0x2800000
	v_readlane_b32 s9, v254, 34
	s_add_u32 s8, s8, s6
	s_addc_u32 s9, s9, s3
	s_lshl_b32 s6, s2, 8
	s_ashr_i32 s7, s6, 31
	s_add_u32 s48, s96, 0xd000000
	s_addc_u32 s49, s97, 0
	s_lshl_b32 s12, s2, 3
	v_writelane_b32 v254, s6, 41
	s_ashr_i32 s13, s12, 31
	v_readlane_b32 s40, v255, 10
	v_readlane_b32 s41, v255, 11
	s_nop 4
	v_writelane_b32 v254, s7, 42
	s_add_u32 s6, s8, 0x1080000
	s_addc_u32 s7, s9, 0
	v_writelane_b32 v254, s6, 43
	s_mov_b64 s[50:51], 0
	s_mov_b64 s[28:29], 0
	v_writelane_b32 v254, s7, 44
	s_add_u32 s6, s8, 0x1780000
	s_addc_u32 s7, s9, 0
	v_writelane_b32 v254, s6, 45
	s_nop 1
	v_writelane_b32 v254, s7, 46
	s_add_u32 s6, s8, 0x2280000
	s_addc_u32 s7, s9, 0
	v_writelane_b32 v254, s6, 47
	s_nop 1
	v_writelane_b32 v254, s7, 48
	s_add_u32 s6, s8, 0xb00000
	v_writelane_b32 v254, s8, 49
	s_addc_u32 s7, s9, 0
	s_cmp_lt_i32 s52, 5
	v_writelane_b32 v254, s9, 50
	v_writelane_b32 v254, s6, 51
	s_mov_b64 s[8:9], 0
	s_nop 0
	v_writelane_b32 v254, s7, 52
	v_writelane_b32 v254, s8, 37
	s_mov_b64 s[6:7], -1
	s_nop 0
	v_writelane_b32 v254, s9, 38
	s_mov_b64 s[8:9], 0
	v_writelane_b32 v254, s8, 53
	s_nop 1
	v_writelane_b32 v254, s9, 54
	v_writelane_b32 v254, s52, 55
	s_cbranch_scc1 .LBB0_335
	s_mov_b64 s[8:9], 0
	v_writelane_b32 v254, s8, 37
	s_cmp_gt_i32 s52, 6
	s_nop 0
	v_writelane_b32 v254, s9, 38
	s_mov_b64 s[8:9], 0
	v_writelane_b32 v254, s8, 53
	s_nop 1
	v_writelane_b32 v254, s9, 54
	s_cbranch_scc0 .LBB0_53
	s_cmp_gt_i32 s52, 8
	s_cbranch_scc0 .LBB0_49
	s_mov_b64 s[6:7], 0
	s_mov_b64 s[8:9], -1
	s_cmp_gt_i32 s52, 9
	s_cbranch_scc0 .LBB0_50
	s_cmp_eq_u32 s52, 10
	s_mov_b64 s[8:9], 0
	s_cselect_b64 s[28:29], -1, 0
	s_branch .LBB0_50

.LBB0_79:
	v_readlane_b32 s12, v255, 34
	v_readlane_b32 s13, v255, 35
	s_nop 4
	v_writelane_b32 v254, s28, 62
	s_mov_b32 s95, s78
	s_andn2_b64 vcc, exec, s[14:15]
	v_writelane_b32 v254, s29, 63
	v_writelane_b32 v254, s79, 37
	s_cbranch_vccnz .LBB0_81
	s_sub_i32 s11, 0x7f, s18
	v_mov_b32_e32 v0, s11
	v_mov_b32_e32 v2, s18
	v_cndmask_b32_e64 v0, v0, v2, s[6:7]
	v_add_u32_e32 v6, 4, v0

.LBB0_122:
	v_readlane_b32 s40, v255, 10
	v_readlane_b32 s41, v255, 11
	s_nop 4
	v_readlane_b32 s26, v254, 15
	v_readlane_b32 s28, v254, 62
	v_readlane_b32 s48, v255, 0
	v_readlane_b32 s12, v254, 56
	s_mov_b32 s78, s95
	v_readlane_b32 s27, v254, 16
	v_readlane_b32 s46, v254, 17
	v_readlane_b32 s79, v254, 37
	s_mov_b32 s73, 0xf700000
	s_mov_b32 s45, 0x12000
	s_mov_b32 s38, 0x63000
	s_mov_b32 s39, 0xc6000
	s_mov_b32 s72, 0x24000
	v_readlane_b32 s29, v254, 63
	s_mov_b64 s[50:51], 0
	v_readlane_b32 s49, v255, 1
	v_readlane_b32 s13, v254, 57
	v_readlane_b32 s47, v254, 18

.LBB0_298:
	s_or_b64 s[4:5], s[8:9], s[6:7]
	s_mov_b64 s[6:7], 0
	v_writelane_b32 v254, s6, 37
	s_and_b64 vcc, exec, s[4:5]
	s_nop 0
	v_writelane_b32 v254, s7, 38
	s_cbranch_vccnz .LBB0_334
	v_readlane_b32 s4, v255, 30
	v_readlane_b32 s5, v255, 31
	s_nop 4
	s_lshl_b64 s[6:7], s[12:13], 2
	s_waitcnt vmcnt(0)
	v_mov_b32_e32 v187, v244
	s_waitcnt lgkmcnt(0)
	s_add_u32 s4, s4, s6
	s_addc_u32 s5, s5, s7
	s_bfe_u32 s17, s94, 0x60001
	s_and_b32 s11, s94, 1
	s_lshl_b32 s8, s11, 2
	s_add_i32 s19, s17, -1
	s_cmp_gt_u32 s19, 63
	v_readfirstlane_b32 s3, v187
	s_cselect_b64 s[6:7], -1, 0
	s_ashr_i32 s18, s3, 6
	s_and_b32 s9, s18, 3
	s_or_b32 s10, s9, s8
	s_lshl_b32 s8, s10, 2
	v_mov_b32_e32 v0, s8
	global_load_dword v2, v0, s[4:5]
	v_cndmask_b32_e64 v0, 0, 1, s[6:7]
	s_xor_b32 s4, s17, 63
	v_readfirstlane_b32 s14, v0
	v_cmp_lt_u32_e64 s[6:7], s4, v0
	s_mov_b32 s21, s14

.LBB0_335:
	s_lshl_b32 s4, s2, 10
	s_ashr_i32 s5, s4, 31
	v_writelane_b32 v254, s4, 56
	s_ashr_i32 s3, s2, 31
	s_and_b64 vcc, exec, s[6:7]
	v_writelane_b32 v254, s5, 57
	s_mul_hi_i32 s4, s2, 0x1600000
	v_writelane_b32 v254, s4, 58
	s_mul_i32 s4, s2, 0x1600000
	v_writelane_b32 v254, s4, 59
	s_mul_hi_i32 s4, s2, 0xb00000
	v_writelane_b32 v254, s4, 60
	s_mul_i32 s4, s2, 0xb00000
	v_writelane_b32 v254, s4, 61
	s_cbranch_vccz .LBB0_720
	s_cmp_gt_i32 s52, 2
	s_mov_b64 s[4:5], -1
	s_cbranch_scc0 .LBB0_717
	s_waitcnt lgkmcnt(0)
	s_lshl_b32 s40, s2, 9
	s_ashr_i32 s41, s40, 31
	s_cmp_gt_i32 s52, 3
	s_cbranch_scc0 .LBB0_456
	s_cmp_lt_i32 s94, 64
	s_cselect_b64 s[10:11], -1, 0
	s_cmp_gt_i32 s94, 63
	s_cselect_b64 s[4:5], -1, 0
	s_add_i32 s6, s60, -2
	s_cmp_lt_i32 s94, s6
	s_cselect_b64 s[6:7], -1, 0
	v_writelane_b32 v254, s28, 62
	s_and_b64 s[42:43], s[4:5], s[6:7]
	s_and_b64 vcc, exec, s[42:43]
	v_writelane_b32 v254, s29, 63
	s_cbranch_vccnz .LBB0_411
	v_readlane_b32 s4, v255, 30
	v_readlane_b32 s5, v255, 31
	s_nop 4
	s_lshl_b64 s[6:7], s[12:13], 2
	s_waitcnt vmcnt(0)
	v_mov_b32_e32 v201, v244
	s_waitcnt lgkmcnt(0)
	s_add_u32 s12, s4, s6
	s_addc_u32 s13, s5, s7
	s_ashr_i32 s8, s94, 7
	s_bfe_u32 s30, s94, 0x60001
	s_and_b32 s19, s94, 1
	s_ashr_i32 s9, s8, 31
	s_lshr_b32 s22, s94, 1
	s_lshl_b32 s23, s19, 2
	s_lshl_b32 s31, s30, 7
	s_lshl_b64 s[4:5], s[8:9], 13
	s_add_i32 s36, s30, -1
	s_cmp_gt_u32 s36, 63
	s_cselect_b64 s[6:7], -1, 0
	s_lshl_b32 s9, s36, 7
	s_add_u32 s14, s4, s9
	v_readfirstlane_b32 s21, v201
	s_addc_u32 s15, s5, 0
	s_ashr_i32 s29, s21, 6
	s_and_b32 s9, s29, 3
	s_or_b32 s18, s9, s23
	s_lshl_b32 s9, s18, 2
	v_mov_b32_e32 v0, s9
	global_load_dword v2, v0, s[12:13]
	v_cmp_lt_i64_e64 s[14:15], s[14:15], 0
	s_lshl_b32 s37, s8, 8
	s_or_b64 s[6:7], s[6:7], s[14:15]
	s_ashr_i32 s38, s37, 31
	s_cmp_lt_u32 s8, 0xffffffc0
	s_cselect_b32 s16, 5, 3
	s_cmp_lt_i32 s8, 0
	s_cselect_b64 s[8:9], -1, 0
	s_and_b64 s[14:15], s[8:9], exec
	s_cselect_b32 s16, s16, 1
	s_and_b64 s[14:15], s[6:7], exec
	s_cselect_b32 s20, s16, 0
	s_max_u32 s25, s20, 4
	s_lshl_b32 s24, s20, 7
	s_add_i32 s25, s25, 1
	s_mov_b32 s28, s24
	s_mov_b32 s34, s20
	s_branch .LBB0_342

.LBB0_411:
	v_readlane_b32 s28, v255, 36
	v_readlane_b32 s29, v255, 37
	v_readlane_b32 s30, v255, 38
	v_readlane_b32 s31, v255, 39
	s_nop 4
	v_readlane_b32 s4, v255, 42
	v_readlane_b32 s5, v255, 43
	s_nop 4
	v_readlane_b32 s36, v255, 46
	v_readlane_b32 s37, v255, 47
	v_readlane_b32 s38, v255, 48
	v_readlane_b32 s39, v255, 49
	s_nop 4
	s_mov_b64 s[6:7], -1
	s_and_b64 vcc, exec, s[42:43]
	s_cbranch_vccz .LBB0_413
	v_readlane_b32 s6, v254, 39
	v_readlane_b32 s7, v254, 40
	s_and_b64 s[6:7], s[6:7], exec
	s_movk_i32 s7, 0x2e8
	s_movk_i32 s6, 0x8e
	s_cselect_b32 s6, 0x7c, s6
	s_cselect_b32 s7, s7, 0x2d6
	s_add_i32 s8, s7, s6
	s_mul_i32 s9, s94, 12
	s_add_i32 s8, s8, s9
	s_sub_i32 s9, s94, 64
	s_cmp_lt_u32 s9, s6
	s_mul_i32 s13, s9, 5
	s_cselect_b32 s12, 6, 5
	s_add_i32 s7, s13, s7
	s_min_u32 s6, s9, s6
	s_add_i32 s6, s7, s6
	s_add_i32 s7, s6, s12
	s_add_i32 s9, s8, 0xfffff8f4
	s_addk_i32 s8, 0xf900
	s_cmpk_lt_u32 s94, 0xd4
	s_cselect_b32 s34, s7, s8
	s_cselect_b32 s51, s6, s9
	s_mov_b64 s[6:7], 0

.LBB0_707:
	s_abs_i32 s4, s60
	v_cvt_f32_u32_e32 v0, s4
	s_sub_i32 s5, 0, s4
	v_rcp_iflag_f32_e32 v0, v0
	s_nop 0
	v_mul_f32_e32 v0, 0x4f7ffffe, v0
	v_cvt_u32_f32_e32 v0, v0
	s_nop 0
	v_readfirstlane_b32 s6, v0
	s_mul_i32 s5, s5, s6
	s_mul_hi_u32 s5, s6, s5
	s_add_i32 s6, s6, s5
	s_mul_hi_u32 s5, s6, 0x294
	s_mul_i32 s5, s5, s4
	s_sub_i32 s5, 0x294, s5
	s_sub_i32 s6, s5, s4
	s_cmp_ge_u32 s5, s4
	s_cselect_b32 s5, s6, s5
	s_sub_i32 s6, s5, s4
	s_cmp_ge_u32 s5, s4
	s_cselect_b32 s4, s6, s5
	s_cmp_eq_u32 s4, 0
	s_cselect_b64 s[6:7], -1, 0
	s_cmp_lt_i32 s94, s4
	s_cselect_b64 s[8:9], -1, 0
	s_or_b64 s[6:7], s[6:7], s[8:9]
	s_and_b64 vcc, exec, s[6:7]
	s_cbranch_vccnz .LBB0_715
	v_mov_b32_e32 v0, v244
	v_mov_b32_e32 v2, v244
	v_readlane_b32 s40, v255, 10
	v_readlane_b32 s41, v255, 11
	s_nop 4
	s_sub_i32 s6, s94, s4
	v_readfirstlane_b32 s7, v0
	s_lshl_b32 s5, s6, 3
	s_ashr_i32 s8, s7, 6
	s_sub_i32 s4, s60, s4
	s_add_i32 s8, s8, s5
	s_lshl_b32 s7, s4, 3
	s_cmpk_gt_i32 s8, 0xaff
	v_readfirstlane_b32 s4, v2
	s_cbranch_scc1 .LBB0_1178
	s_lshr_b32 s4, s4, 6
	v_lshlrev_b32_e32 v4, 3, v2
	s_mulk_i32 s4, 0x2100
	v_lshlrev_b32_e32 v0, 2, v2
	v_bfe_u32 v13, v2, 3, 3
	v_and_b32_e32 v4, 56, v4
	s_add_i32 s4, s4, 0
	v_and_b32_e32 v0, 0x7c, v0
	v_mul_u32_u24_e32 v5, 0x84, v4
	v_lshlrev_b32_e32 v6, 2, v13
	v_add_u32_e32 v10, s4, v0
	s_waitcnt vmcnt(0)
	v_add3_u32 v14, s4, v5, v6
	v_readlane_b32 s4, v255, 52
	v_readlane_b32 s5, v255, 53
	s_nop 4
	v_and_b32_e32 v3, 63, v2
	v_bfe_u32 v12, v2, 5, 1
	v_or_b32_e32 v15, 8, v13
	v_lshrrev_b32_e32 v2, 2, v2
	s_add_i32 s9, s8, 0xb00
	v_bfe_u32 v3, v3, 3, 2
	v_and_b32_e32 v2, 8, v2
	v_lshlrev_b32_e32 v5, 1, v15
	s_mul_i32 s11, s2, 0x1600000
	v_or_b32_e32 v17, 24, v13
	v_or_b32_e32 v18, v2, v3
	v_and_or_b32 v19, v5, 24, v3
	v_or_b32_e32 v3, 4, v13
	s_waitcnt lgkmcnt(0)
	s_add_u32 s4, s4, s11
	s_mul_hi_i32 s10, s2, 0x1600000
	v_or_b32_e32 v20, v2, v3
	v_lshlrev_b32_e32 v2, 1, v17
	s_addc_u32 s5, s5, s10
	v_and_or_b32 v21, v2, 24, v3
	v_lshl_add_u64 v[2:3], s[4:5], 0, v[0:1]
	v_readlane_b32 s4, v254, 45
	v_lshlrev_b32_e32 v8, 1, v4
	v_mov_b32_e32 v9, v1
	v_readlane_b32 s5, v254, 46
	v_mul_u32_u24_e32 v11, 0x84, v12
	v_or_b32_e32 v16, 16, v13
	v_lshl_add_u64 v[4:5], s[4:5], 0, v[8:9]
	v_readlane_b32 s4, v255, 20
	v_readlane_b32 s5, v255, 21
	s_nop 4
	v_add_u32_e32 v22, v10, v11
	s_waitcnt lgkmcnt(0)
	s_add_u32 s4, s4, s11
	s_addc_u32 s5, s5, s10
	v_lshl_add_u64 v[6:7], s[4:5], 0, v[0:1]
	v_readlane_b32 s4, v254, 49
	v_readlane_b32 s5, v254, 50
	s_lshl_b32 s10, s9, 5
	s_lshl_b32 s11, s7, 5
	v_lshl_add_u64 v[8:9], s[4:5], 0, v[8:9]
	s_branch .LBB0_711

.LBB0_715:
	v_readlane_b32 s40, v255, 10
	v_readlane_b32 s41, v255, 11
	s_nop 4

.LBB0_720:
	s_add_i32 s4, s2, 1
	v_writelane_b32 v254, s4, 62
	s_and_b64 vcc, exec, s[28:29]
	s_cbranch_vccz .LBB0_982
	s_cmp_eq_u32 s52, 1
	s_cselect_b64 s[4:5], -1, 0
	s_cmp_eq_u32 s52, 7
	s_cselect_b64 s[10:11], -1, 0
	s_cmp_lg_u32 s52, 7
	s_cselect_b64 s[8:9], -1, 0
	s_cmp_eq_u32 s52, 10
	s_cselect_b64 s[30:31], -1, 0
	s_cmp_lg_u32 s52, 1
	s_mov_b64 s[6:7], -1
	s_cbranch_scc0 .LBB0_731
	s_and_b64 vcc, exec, s[8:9]
	s_cbranch_vccz .LBB0_728
	v_readlane_b32 s6, v254, 62
	s_cmp_eq_u32 s6, 2
	s_cselect_b64 s[6:7], -1, 0
	s_and_b64 s[6:7], s[30:31], s[6:7]
	s_andn2_b64 vcc, exec, s[6:7]
	s_mov_b64 s[6:7], -1
	s_cbranch_vccz .LBB0_725
	v_readlane_b32 s6, v255, 18
	v_readlane_b32 s7, v255, 19
	s_nop 4
	v_readlane_b32 s8, v254, 62
	s_lshl_b32 s8, s8, 10
	s_ashr_i32 s9, s8, 31
	s_lshl_b64 s[8:9], s[8:9], 2
	s_waitcnt lgkmcnt(0)
	s_add_u32 s14, s6, s8
	s_addc_u32 s15, s7, s9
	s_mov_b64 s[6:7], 0
.LBB0_725:
	s_andn2_b64 vcc, exec, s[6:7]
	s_cbranch_vccnz .LBB0_727
	v_readlane_b32 s14, v255, 56
	v_readlane_b32 s15, v255, 57
	s_nop 4

.LBB0_728:
	s_andn2_b64 vcc, exec, s[6:7]
	s_cbranch_vccnz .LBB0_730
	v_readlane_b32 s6, v255, 50
	v_readlane_b32 s7, v255, 51
	s_nop 4
	v_readlane_b32 s8, v254, 56
	v_readlane_b32 s9, v254, 57
	s_lshl_b64 s[8:9], s[8:9], 2
	s_waitcnt lgkmcnt(0)
	s_add_u32 s14, s6, s8
	s_addc_u32 s15, s7, s9

.LBB0_731:
	s_andn2_b64 vcc, exec, s[6:7]
	s_cbranch_vccnz .LBB0_733
	v_readlane_b32 s6, v255, 24
	v_readlane_b32 s7, v255, 25
	s_nop 4
	v_readlane_b32 s8, v254, 56
	v_readlane_b32 s9, v254, 57
	s_lshl_b64 s[8:9], s[8:9], 2
	s_waitcnt lgkmcnt(0)
	s_add_u32 s14, s6, s8
	s_addc_u32 s15, s7, s9

.LBB0_766:
	s_mov_b64 s[4:5], s[0:1]
	s_barrier
	v_readlane_b32 s16, v255, 58
	v_readlane_b32 s17, v255, 59
	v_readlane_b32 s18, v255, 60
	v_readlane_b32 s19, v255, 61
	s_nop 4
	s_add_i32 s7, s58, -14
	v_readlane_b32 s52, v254, 55
	s_mov_b32 s78, s26
	s_mov_b32 s79, s27
	s_mov_b32 s53, s14
	s_mov_b32 s61, s15
	s_cmp_gt_u32 s7, 11
	v_readlane_b32 s26, v254, 15
	v_readlane_b32 s14, v255, 2
	s_mov_b32 s86, 0x800000
	s_mov_b32 s87, 0x9000
	s_movk_i32 s90, 0x800
	s_mov_b32 s91, 0x129000
	s_mov_b64 s[50:51], s[46:47]
	s_cselect_b64 s[10:11], -1, 0
	s_mov_b64 s[40:41], -1
	s_mov_b64 s[8:9], 0
	s_cmp_lt_i32 s52, 7
	s_mov_b64 s[12:13], 0
	v_readlane_b32 s27, v254, 16
	v_readlane_b32 s15, v255, 3
	s_cbranch_scc1 .LBB0_776
	s_cmp_eq_u32 s52, 7
	s_mov_b64 s[12:13], -1
	s_cbranch_scc0 .LBB0_769
	v_readlane_b32 s12, v255, 50
	v_readlane_b32 s13, v255, 51
	s_nop 4
	v_readlane_b32 s34, v254, 56
	v_readlane_b32 s35, v254, 57
	s_lshl_b64 s[34:35], s[34:35], 2
	s_waitcnt lgkmcnt(0)
	s_add_u32 s36, s12, s34
	s_addc_u32 s37, s13, s35
	s_mov_b64 s[12:13], 0

.LBB0_771:
	s_mov_b64 s[8:9], -1
	s_and_b64 vcc, exec, s[30:31]
	s_cbranch_vccz .LBB0_773
	v_readlane_b32 s8, v255, 18
	v_readlane_b32 s9, v255, 19
	s_nop 4
	v_readlane_b32 s10, v254, 56
	v_readlane_b32 s11, v254, 57
	s_addk_i32 s10, 0x400
	s_ashr_i32 s11, s10, 31
	s_lshl_b64 s[10:11], s[10:11], 2
	s_waitcnt lgkmcnt(0)
	s_add_u32 s36, s8, s10
	s_addc_u32 s37, s9, s11
	s_mov_b64 s[8:9], 0
.LBB0_773:
	s_andn2_b64 vcc, exec, s[8:9]
	s_cbranch_vccnz .LBB0_775
	v_readlane_b32 s36, v255, 56
	v_readlane_b32 s37, v255, 57
	s_nop 4

.LBB0_779:
	v_readlane_b32 s8, v255, 24
	v_readlane_b32 s9, v255, 25
	s_nop 4
	v_readlane_b32 s10, v254, 56
	v_readlane_b32 s11, v254, 57
	s_lshl_b64 s[10:11], s[10:11], 2
	s_waitcnt lgkmcnt(0)
	s_add_u32 s36, s8, s10
	s_addc_u32 s37, s9, s11
.LBB0_780:
	s_lshl_b32 s70, s6, 8
	s_add_i32 s8, s70, s80
	s_lshl_b32 s7, s45, 5
	v_or_b32_e32 v130, s8, v164
	s_lshl_b32 s8, s28, 8
	v_lshrrev_b32_e32 v0, 1, v163
	s_or_b32 s7, s8, s7
	v_and_or_b32 v148, v0, 24, s7
	v_ashrrev_i32_e32 v131, 31, v130
	v_lshlrev_b64 v[130:131], 10, v[130:131]
	v_ashrrev_i32_e32 v149, 31, v148
	v_readlane_b32 s8, v255, 6
	v_readlane_b32 s9, v255, 7
	s_nop 4
	v_lshl_add_u64 v[152:153], v[130:131], 0, v[148:149]
	s_waitcnt lgkmcnt(0)
	v_lshl_add_u64 v[130:131], v[152:153], 1, s[18:19]
	s_mov_b64 s[4:5], 0x10000000
	v_lshl_add_u64 v[150:151], v[130:131], 0, s[4:5]
	s_lshl_b32 s4, s29, 14
	v_cndmask_b32_e64 v0, 0, 1, s[38:39]
	s_add_i32 s7, s4, 0
	v_cmp_ne_u32_e64 s[10:11], 1, v0
	s_andn2_b64 vcc, exec, s[38:39]
	s_cbranch_vccnz .LBB0_782

.LBB0_1009:
	s_abs_i32 s6, s60
	v_cvt_f32_u32_e32 v0, s6
	s_sub_i32 s7, 0, s6
	v_rcp_iflag_f32_e32 v0, v0
	s_nop 0
	v_mul_f32_e32 v0, 0x4f7ffffe, v0
	v_cvt_u32_f32_e32 v0, v0
	s_nop 0
	v_readfirstlane_b32 s8, v0
	s_mul_i32 s7, s7, s8
	s_mul_hi_u32 s7, s8, s7
	s_add_i32 s8, s8, s7
	s_mul_hi_u32 s7, s80, s8
	s_mul_i32 s7, s7, s6
	s_sub_i32 s7, s80, s7
	s_sub_i32 s8, s7, s6
	s_cmp_ge_u32 s7, s6
	s_cselect_b32 s7, s8, s7
	s_sub_i32 s8, s7, s6
	s_cmp_ge_u32 s7, s6
	s_cselect_b32 s6, s8, s7
	s_cmp_eq_u32 s6, 0
	s_cselect_b64 s[8:9], -1, 0
	s_cmp_lt_i32 s94, s6
	s_cselect_b64 s[10:11], -1, 0
	s_or_b64 s[8:9], s[8:9], s[10:11]
	s_and_b64 vcc, exec, s[8:9]
	s_cbranch_vccnz .LBB0_1016
	v_mov_b32_e32 v0, v244
	s_waitcnt lgkmcnt(0)
	s_sub_i32 s14, s94, s6
	s_lshl_b32 s7, s14, 3
	v_readfirstlane_b32 s8, v0
	s_ashr_i32 s16, s8, 6
	s_sub_i32 s6, s60, s6
	v_readlane_b32 s22, v254, 19
	s_add_i32 s16, s16, s7
	s_lshl_b32 s15, s6, 3
	s_and_b64 vcc, exec, s[4:5]
	v_readlane_b32 s23, v254, 20
	s_cbranch_vccz .LBB0_1112
	v_readlane_b32 s6, v254, 39
	v_readlane_b32 s7, v254, 40
	s_mov_b64 s[4:5], 0
	s_and_b64 vcc, exec, s[6:7]
	s_mov_b64 s[6:7], 0
	s_cbranch_vccz .LBB0_1037
	v_mov_b32_e32 v2, v244
	s_cmpk_gt_i32 s16, 0xaff
	v_readfirstlane_b32 s6, v2
	s_cbranch_scc1 .LBB0_1015
	v_readlane_b32 s17, v254, 62
	s_mul_i32 s8, s17, 0x2800000
	v_readlane_b32 s10, v254, 33
	s_mul_hi_i32 s7, s17, 0x2800000
	v_readlane_b32 s11, v254, 34
	s_add_u32 s8, s10, s8
	s_addc_u32 s9, s11, s7
	s_lshr_b32 s6, s6, 6
	v_lshlrev_b32_e32 v4, 3, v2
	s_mulk_i32 s6, 0x2100
	v_lshlrev_b32_e32 v0, 2, v2
	v_bfe_u32 v9, v2, 3, 3
	v_and_b32_e32 v4, 56, v4
	s_add_i32 s6, s6, 0
	v_and_b32_e32 v0, 0x7c, v0
	v_mul_u32_u24_e32 v5, 0x84, v4
	v_lshlrev_b32_e32 v10, 2, v9
	v_add_u32_e32 v6, s6, v0
	v_add3_u32 v10, s6, v5, v10
	v_readlane_b32 s6, v255, 20
	v_readlane_b32 s7, v255, 21
	s_nop 4
	v_and_b32_e32 v3, 63, v2
	v_bfe_u32 v8, v2, 5, 1
	v_or_b32_e32 v11, 8, v9
	v_lshrrev_b32_e32 v2, 2, v2
	s_mul_i32 s11, s17, 0x1600000
	v_bfe_u32 v3, v3, 3, 2
	v_and_b32_e32 v2, 8, v2
	v_lshlrev_b32_e32 v5, 1, v11
	s_mul_hi_i32 s10, s17, 0x1600000
	v_or_b32_e32 v13, 24, v9
	v_or_b32_e32 v14, v2, v3
	v_and_or_b32 v15, v5, 24, v3
	v_or_b32_e32 v3, 4, v9
	s_waitcnt lgkmcnt(0)
	s_add_u32 s6, s6, s11
	v_or_b32_e32 v16, v2, v3
	v_lshlrev_b32_e32 v2, 1, v13
	s_addc_u32 s7, s7, s10
	v_mul_u32_u24_e32 v7, 0x84, v8
	v_and_or_b32 v17, v2, 24, v3
	v_lshl_add_u64 v[2:3], s[6:7], 0, v[0:1]
	v_lshlrev_b32_e32 v0, 1, v4
	v_or_b32_e32 v12, 16, v9
	v_lshl_add_u64 v[4:5], s[8:9], 0, v[0:1]
	s_lshl_b32 s8, s16, 5
	s_lshl_b32 s9, s15, 5
	v_add_u32_e32 v0, v6, v7
	s_mov_b32 s10, s16

.LBB0_1018:
	s_and_b64 vcc, exec, s[2:3]
	s_cbranch_vccz .LBB0_1086
	s_waitcnt vmcnt(0)
	v_mov_b32_e32 v2, v244
	s_cmpk_gt_i32 s94, 0xff
	v_ashrrev_i32_e32 v4, 6, v2
	v_readfirstlane_b32 s16, v2
	v_readfirstlane_b32 s6, v4
	s_cbranch_scc1 .LBB0_1027
	s_movk_i32 s2, 0xc00
	v_cmp_gt_i32_e32 vcc, s2, v2
	s_waitcnt lgkmcnt(0)
	s_barrier
	s_and_saveexec_b64 s[2:3], vcc
	s_cbranch_execz .LBB0_1023
	v_readlane_b32 s10, v255, 8
	v_readlane_b32 s11, v255, 9
	s_nop 4
	v_readlane_b32 s8, v255, 12
	v_readlane_b32 s9, v255, 13
	s_nop 4
	v_lshlrev_b32_e32 v5, 2, v2
	s_waitcnt lgkmcnt(0)
	s_add_u32 s98, s10, 0x1000
	s_addc_u32 s99, s11, 0
	global_load_dword v0, v5, s[10:11]
	global_load_dword v3, v5, s[10:11] offset:2048
	global_load_dword v6, v5, s[98:99]
	global_load_dword v7, v5, s[98:99] offset:2048
	global_load_dword v38, v5, s[8:9]
	global_load_dword v39, v5, s[8:9] offset:2048
	s_waitcnt vmcnt(0)
	v_mul_f32_e32 v8, 0xbfb8aa3b, v0
	v_exp_f32_e32 v8, v8
	s_nop 0
	v_add_f32_e32 v8, 1.0, v8
	v_div_scale_f32 v9, s[8:9], v8, v8, v0
	v_rcp_f32_e32 v10, v9
	v_div_scale_f32 v11, vcc, v0, v8, v0
	v_fma_f32 v12, -v9, v10, 1.0
	v_fmac_f32_e32 v10, v12, v10
	v_mul_f32_e32 v12, v11, v10
	v_fma_f32 v13, -v9, v12, v11
	v_fmac_f32_e32 v12, v13, v10
	v_fma_f32 v9, -v9, v12, v11
	v_div_fmas_f32 v9, v9, v10, v12
	v_div_fixup_f32 v0, v9, v8, v0
	ds_write_b32 v5, v0
	v_mul_f32_e32 v8, 0xbfb8aa3b, v3
	v_exp_f32_e32 v8, v8
	s_nop 0
	v_add_f32_e32 v8, 1.0, v8
	v_div_scale_f32 v9, s[8:9], v8, v8, v3
	v_rcp_f32_e32 v10, v9
	v_div_scale_f32 v11, vcc, v3, v8, v3
	v_fma_f32 v12, -v9, v10, 1.0
	v_fmac_f32_e32 v10, v12, v10
	v_mul_f32_e32 v12, v11, v10
	v_fma_f32 v13, -v9, v12, v11
	v_fmac_f32_e32 v12, v13, v10
	v_fma_f32 v9, -v9, v12, v11
	v_div_fmas_f32 v9, v9, v10, v12
	v_div_fixup_f32 v3, v9, v8, v3
	ds_write_b32 v5, v3 offset:2048
	v_mul_f32_e32 v8, 0xbfb8aa3b, v6
	v_exp_f32_e32 v8, v8
	s_nop 0
	v_add_f32_e32 v8, 1.0, v8
	v_div_scale_f32 v9, s[8:9], v8, v8, v6
	v_rcp_f32_e32 v10, v9
	v_div_scale_f32 v11, vcc, v6, v8, v6
	v_fma_f32 v12, -v9, v10, 1.0
	v_fmac_f32_e32 v10, v12, v10
	v_mul_f32_e32 v12, v11, v10
	v_fma_f32 v13, -v9, v12, v11
	v_fmac_f32_e32 v12, v13, v10
	v_fma_f32 v9, -v9, v12, v11
	v_div_fmas_f32 v9, v9, v10, v12
	v_div_fixup_f32 v6, v9, v8, v6
	ds_write_b32 v5, v6 offset:4096
	v_mul_f32_e32 v8, 0xbfb8aa3b, v7
	v_exp_f32_e32 v8, v8
	s_nop 0
	v_add_f32_e32 v8, 1.0, v8
	v_div_scale_f32 v9, s[8:9], v8, v8, v7
	v_rcp_f32_e32 v10, v9
	v_div_scale_f32 v11, vcc, v7, v8, v7
	v_fma_f32 v12, -v9, v10, 1.0
	v_fmac_f32_e32 v10, v12, v10
	v_mul_f32_e32 v12, v11, v10
	v_fma_f32 v13, -v9, v12, v11
	v_fmac_f32_e32 v12, v13, v10
	v_fma_f32 v9, -v9, v12, v11
	v_div_fmas_f32 v9, v9, v10, v12
	v_div_fixup_f32 v7, v9, v8, v7
	ds_write_b32 v5, v7 offset:6144
	v_mul_f32_e32 v8, 0xbfb8aa3b, v38
	v_exp_f32_e32 v8, v8
	s_nop 0
	v_add_f32_e32 v8, 1.0, v8
	v_div_scale_f32 v9, s[8:9], v8, v8, v38
	v_rcp_f32_e32 v10, v9
	v_div_scale_f32 v11, vcc, v38, v8, v38
	v_fma_f32 v12, -v9, v10, 1.0
	v_fmac_f32_e32 v10, v12, v10
	v_mul_f32_e32 v12, v11, v10
	v_fma_f32 v13, -v9, v12, v11
	v_fmac_f32_e32 v12, v13, v10
	v_fma_f32 v9, -v9, v12, v11
	v_div_fmas_f32 v9, v9, v10, v12
	v_div_fixup_f32 v38, v9, v8, v38
	ds_write_b32 v5, v38 offset:8192
	v_mul_f32_e32 v8, 0xbfb8aa3b, v39
	v_exp_f32_e32 v8, v8
	s_nop 0
	v_add_f32_e32 v8, 1.0, v8
	v_div_scale_f32 v9, s[8:9], v8, v8, v39
	v_rcp_f32_e32 v10, v9
	v_div_scale_f32 v11, vcc, v39, v8, v39
	v_fma_f32 v12, -v9, v10, 1.0
	v_fmac_f32_e32 v10, v12, v10
	v_mul_f32_e32 v12, v11, v10
	v_fma_f32 v13, -v9, v12, v11
	v_fmac_f32_e32 v12, v13, v10
	v_fma_f32 v9, -v9, v12, v11
	v_div_fmas_f32 v9, v9, v10, v12
	v_div_fixup_f32 v39, v9, v8, v39
	ds_write_b32 v5, v39 offset:10240
.LBB0_1023:
	s_or_b64 exec, exec, s[2:3]
	s_waitcnt lgkmcnt(0)
	s_barrier
	v_readlane_b32 s8, v255, 14
	v_readlane_b32 s9, v255, 15
	v_readlane_b32 s10, v255, 16
	v_readlane_b32 s11, v255, 17
	s_nop 4
	s_lshl_b32 s2, s6, 7
	s_mul_i32 s3, s6, 0x480000
	s_mul_hi_i32 s2, s2, 0x9000
	v_and_b32_e32 v6, 63, v2
	s_waitcnt lgkmcnt(0)
	s_add_u32 s8, s8, s3
	s_addc_u32 s9, s9, s2
	s_lshl_b32 s2, s6, 9
	s_mulk_i32 s6, 0x300
	s_add_i32 s12, s2, 0
	s_add_i32 s2, s6, 0
	v_lshlrev_b32_e32 v5, 2, v6
	v_add_u32_e32 v3, s2, v5
	s_movk_i32 s2, 0xc0
	v_cmp_gt_u32_e32 vcc, 36, v6
	v_min_u32_e32 v0, 35, v6
	v_cmp_gt_i32_e64 s[6:7], s2, v2
	v_add_u32_e32 v5, 0, v5
	v_lshlrev_b32_e32 v7, 8, v4
	s_and_b64 s[2:3], s[6:7], vcc
	v_lshlrev_b32_e32 v0, 2, v0
	v_add_u32_e32 v5, v5, v7
	v_lshlrev_b32_e32 v8, 2, v6
	s_mov_b32 s6, s94
	s_branch .LBB0_1025

.LBB0_1038:
	v_mov_b32_e32 v2, v244
	s_cmpk_gt_i32 s16, 0x57f
	v_readfirstlane_b32 s4, v2
	s_cbranch_scc1 .LBB0_1114
	s_lshr_b32 s4, s4, 6
	s_mulk_i32 s4, 0x2100
	v_bfe_u32 v16, v2, 5, 1
	v_lshlrev_b32_e32 v0, 2, v2
	s_add_i32 s4, s4, 0
	v_and_b32_e32 v0, 0x7c, v0
	v_mul_u32_u24_e32 v4, 0x84, v16
	v_readlane_b32 s8, v255, 20
	v_readlane_b32 s9, v255, 21
	v_readlane_b32 s10, v255, 22
	v_readlane_b32 s11, v255, 23
	s_nop 4
	v_add3_u32 v17, s4, v0, v4
	v_lshlrev_b32_e32 v4, 3, v2
	v_bfe_u32 v18, v2, 3, 3
	v_and_b32_e32 v4, 56, v4
	v_and_b32_e32 v3, 63, v2
	v_mul_u32_u24_e32 v5, 0x84, v4
	v_lshlrev_b32_e32 v6, 2, v18
	v_or_b32_e32 v20, 8, v18
	v_lshrrev_b32_e32 v2, 2, v2
	s_add_i32 s6, s16, 0x1600
	v_add3_u32 v19, s4, v5, v6
	v_bfe_u32 v3, v3, 3, 2
	v_and_b32_e32 v2, 8, v2
	v_lshlrev_b32_e32 v5, 1, v20
	s_mul_i32 s4, s2, 0xb00000
	v_or_b32_e32 v22, 24, v18
	v_or_b32_e32 v23, v2, v3
	v_and_or_b32 v24, v5, 24, v3
	v_or_b32_e32 v3, 4, v18
	s_waitcnt lgkmcnt(0)
	s_add_u32 s4, s10, s4
	s_mul_hi_i32 s5, s2, 0xb00000
	v_or_b32_e32 v25, v2, v3
	v_lshlrev_b32_e32 v2, 1, v22
	s_addc_u32 s5, s11, s5
	v_and_or_b32 v26, v2, 24, v3
	v_lshl_add_u64 v[2:3], s[4:5], 0, v[0:1]
	v_readlane_b32 s4, v254, 51
	v_lshlrev_b32_e32 v12, 1, v4
	v_mov_b32_e32 v13, v1
	v_readlane_b32 s5, v254, 52
	s_mul_i32 s10, s2, 0x1600000
	s_mul_hi_i32 s7, s2, 0x1600000
	v_lshl_add_u64 v[4:5], s[4:5], 0, v[12:13]
	v_readlane_b32 s4, v255, 52
	v_readlane_b32 s5, v255, 53
	s_nop 4
	v_or_b32_e32 v21, 16, v18
	s_waitcnt lgkmcnt(0)
	s_add_u32 s4, s4, s10
	s_addc_u32 s5, s5, s7
	v_lshl_add_u64 v[6:7], s[4:5], 0, v[0:1]
	v_readlane_b32 s4, v254, 45
	v_readlane_b32 s5, v254, 46
	s_nop 1
	v_lshl_add_u64 v[8:9], s[4:5], 0, v[12:13]
	s_add_u32 s4, s8, s10
	s_addc_u32 s5, s9, s7
	v_lshl_add_u64 v[10:11], s[4:5], 0, v[0:1]
	v_readlane_b32 s4, v254, 49
	v_readlane_b32 s5, v254, 50
	s_lshl_b32 s7, s6, 5
	s_lshl_b32 s8, s15, 5
	v_lshl_add_u64 v[12:13], s[4:5], 0, v[12:13]
	s_lshl_b32 s4, s6, 1
	s_add_i32 s9, s4, 0x1d400
	s_lshl_b32 s10, s15, 1
	s_branch .LBB0_1041

.LBB0_1071:
	s_or_b64 exec, exec, s[2:3]
	s_movk_i32 s2, 0x200
	v_cmp_gt_i32_e32 vcc, s2, v2
	s_and_saveexec_b64 s[2:3], vcc
	s_cbranch_execz .LBB0_1073
	v_readlane_b32 s4, v255, 32
	v_readlane_b32 s5, v255, 33
	s_nop 4
	v_lshlrev_b64 v[4:5], 2, v[2:3]
	s_waitcnt lgkmcnt(0)
	v_lshl_add_u64 v[6:7], s[4:5], 0, v[4:5]
	global_load_dword v0, v[6:7], off offset:2048
	global_load_dword v3, v[6:7], off
	s_mov_b32 s4, 0x3fb8aa3b
	s_waitcnt vmcnt(1)
	v_max_f32_e32 v6, v0, v0
	s_waitcnt vmcnt(0)
	v_max_f32_e32 v7, v3, v3
	v_max_f32_e32 v6, v7, v6
	v_sub_f32_e32 v3, v3, v6
	v_sub_f32_e32 v0, v0, v6
	v_mul_f32_e32 v6, 0x3fb8aa3b, v3
	v_mul_f32_e32 v7, 0x3fb8aa3b, v0
	v_fma_f32 v8, v3, s4, -v6
	v_rndne_f32_e32 v9, v6
	v_fma_f32 v10, v0, s4, -v7
	v_rndne_f32_e32 v11, v7
	v_fmac_f32_e32 v8, 0x32a5705f, v3
	v_sub_f32_e32 v6, v6, v9
	v_fmac_f32_e32 v10, 0x32a5705f, v0
	v_sub_f32_e32 v7, v7, v11
	v_add_f32_e32 v6, v6, v8
	v_cvt_i32_f32_e32 v9, v9
	v_add_f32_e32 v7, v7, v10
	v_exp_f32_e32 v6, v6
	v_cvt_i32_f32_e32 v11, v11
	v_exp_f32_e32 v7, v7
	v_readlane_b32 s4, v254, 31
	v_readlane_b32 s5, v254, 32
	v_ldexp_f32 v6, v6, v9
	v_ldexp_f32 v7, v7, v11
	v_lshl_add_u64 v[4:5], s[4:5], 0, v[4:5]
	s_mov_b32 s4, 0xc2ce8ed0
	v_cmp_ngt_f32_e32 vcc, s4, v3
	global_store_dword v[4:5], v1, off
	s_nop 0
	v_cndmask_b32_e32 v6, 0, v6, vcc
	v_cmp_ngt_f32_e32 vcc, s4, v0
	s_mov_b32 s4, 0x42b17218
	s_nop 0
	v_cndmask_b32_e32 v7, 0, v7, vcc
	v_cmp_nlt_f32_e32 vcc, s4, v3
	s_nop 1
	v_cndmask_b32_e32 v3, v219, v6, vcc
	v_cmp_nlt_f32_e32 vcc, s4, v0
	s_nop 1
	v_cndmask_b32_e32 v0, v219, v7, vcc
	v_add_f32_e32 v3, v3, v0
	v_div_scale_f32 v6, s[4:5], v3, v3, v0
	v_rcp_f32_e32 v7, v6
	v_div_scale_f32 v8, vcc, v0, v3, v0
	v_fma_f32 v9, -v6, v7, 1.0
	v_fmac_f32_e32 v7, v9, v7
	v_mul_f32_e32 v9, v8, v7
	v_fma_f32 v10, -v6, v9, v8
	v_fmac_f32_e32 v9, v10, v7
	v_fma_f32 v6, -v6, v9, v8
	v_div_fmas_f32 v6, v6, v7, v9
	v_div_fixup_f32 v0, v6, v3, v0
	global_store_dword v[4:5], v0, off offset:2048

.LBB0_1074:
	v_lshl_add_u32 v2, s94, 9, v2
	s_mov_b32 s2, 0x20000
	v_cmp_gt_i32_e32 vcc, s2, v2
	s_and_saveexec_b64 s[2:3], vcc
	s_cbranch_execz .LBB0_1082
	s_lshl_b32 s4, s60, 9
	v_cvt_f32_u32_e32 v0, s4
	s_sub_i32 s5, 0, s4
	v_add_u32_e32 v3, s4, v2
	s_mov_b32 s6, 0x20000
	v_rcp_iflag_f32_e32 v0, v0
	v_max_i32_e32 v4, 0x20000, v3
	v_cmp_gt_i32_e32 vcc, s6, v3
	v_readlane_b32 s8, v255, 40
	v_readlane_b32 s9, v255, 41
	s_nop 4
	v_readlane_b32 s10, v255, 44
	v_readlane_b32 s11, v255, 45
	s_nop 4
	v_mul_f32_e32 v0, 0x4f7ffffe, v0
	v_cvt_u32_f32_e32 v0, v0
	v_cndmask_b32_e64 v5, 1, 2, vcc
	v_subb_co_u32_e32 v4, vcc, v4, v3, vcc
	v_mul_lo_u32 v6, s5, v0
	v_mul_hi_u32 v6, v0, v6
	v_add_u32_e32 v0, v0, v6
	v_mul_hi_u32 v0, v4, v0
	v_mul_lo_u32 v6, v0, s4
	v_sub_u32_e32 v4, v4, v6
	v_add_u32_e32 v6, 1, v0
	v_cmp_le_u32_e32 vcc, s4, v4
	s_mov_b64 s[6:7], -1
	s_nop 0
	v_cndmask_b32_e32 v0, v0, v6, vcc
	v_subrev_u32_e32 v6, s4, v4
	v_cndmask_b32_e32 v4, v4, v6, vcc
	v_add_u32_e32 v6, 1, v0
	v_cmp_le_u32_e32 vcc, s4, v4
	s_nop 1
	v_cndmask_b32_e32 v0, v0, v6, vcc
	v_add_u32_e32 v6, v5, v0
	v_cmp_lt_u32_e32 vcc, 1, v6
	s_and_saveexec_b64 s[12:13], vcc
	s_cbranch_execz .LBB0_1079
	v_and_b32_e32 v7, -2, v6
	s_lshl_b32 s20, s60, 10
	s_waitcnt lgkmcnt(0)
	s_mov_b32 s5, s8
	s_mov_b32 s17, s9
	s_mov_b32 s18, s10
	s_mov_b32 s19, s11
	s_mov_b32 s21, s20
	s_mov_b64 s[14:15], 0
	v_mov_b32_e32 v8, v7
	v_mov_b64_e32 v[4:5], v[2:3]

.LBB0_1082:
	s_or_b64 exec, exec, s[2:3]
	s_ashr_i32 s2, s16, 6
	s_lshl_b32 s3, s94, 3
	s_add_i32 s2, s2, s3
	v_mov_b32_e32 v2, v244
	s_waitcnt lgkmcnt(0)
	s_barrier
	s_cmpk_gt_i32 s2, 0xaff
	v_readfirstlane_b32 s4, v2
	s_cbranch_scc1 .LBB0_1085
	s_lshr_b32 s4, s4, 6
	v_lshlrev_b32_e32 v4, 3, v2
	s_mulk_i32 s4, 0x2100
	v_bfe_u32 v7, v2, 3, 3
	v_and_b32_e32 v4, 56, v4
	v_readlane_b32 s0, v255, 20
	v_readlane_b32 s1, v255, 21
	s_nop 4
	s_add_i32 s4, s4, 0
	v_and_b32_e32 v3, 63, v2
	v_bfe_u32 v6, v2, 5, 1
	v_lshlrev_b32_e32 v0, 2, v2
	v_mul_u32_u24_e32 v5, 0x84, v4
	v_lshlrev_b32_e32 v8, 2, v7
	v_or_b32_e32 v9, 8, v7
	v_lshrrev_b32_e32 v2, 2, v2
	v_add3_u32 v8, s4, v5, v8
	v_bfe_u32 v3, v3, 3, 2
	v_and_b32_e32 v2, 8, v2
	v_lshlrev_b32_e32 v5, 1, v9
	v_or_b32_e32 v11, 24, v7
	v_or_b32_e32 v12, v2, v3
	v_and_or_b32 v13, v5, 24, v3
	v_or_b32_e32 v3, 4, v7
	v_and_b32_e32 v0, 0x7c, v0
	v_or_b32_e32 v14, v2, v3
	v_lshlrev_b32_e32 v2, 1, v11
	v_and_or_b32 v15, v2, 24, v3
	s_waitcnt lgkmcnt(0)
	v_lshl_add_u64 v[2:3], s[0:1], 0, v[0:1]
	v_readlane_b32 s0, v254, 33
	v_add_u32_e32 v16, s4, v0
	v_mul_u32_u24_e32 v17, 0x84, v6
	v_lshlrev_b32_e32 v0, 1, v4
	v_readlane_b32 s1, v254, 34
	s_lshl_b32 s3, s60, 3
	v_or_b32_e32 v10, 16, v7
	v_lshl_add_u64 v[4:5], s[0:1], 0, v[0:1]
	s_lshl_b32 s4, s2, 5
	s_lshl_b32 s5, s60, 8
	v_add_u32_e32 v0, v16, v17

.LBB0_1114:
	v_mov_b32_e32 v12, v244
	s_cmpk_gt_i32 s16, 0x6ff
	v_readfirstlane_b32 s5, v12
	s_cbranch_scc1 .LBB0_1137
	s_add_i32 s4, s16, 0x2100
	v_readlane_b32 s8, v255, 20
	v_readlane_b32 s9, v255, 21
	v_readlane_b32 s10, v255, 22
	v_readlane_b32 s11, v255, 23
	s_nop 4
	v_readlane_b32 s16, v255, 26
	v_readlane_b32 s17, v255, 27
	v_readlane_b32 s18, v255, 28
	v_readlane_b32 s19, v255, 29
	s_nop 4
	s_lshl_b64 s[6:7], s[2:3], 22
	s_mul_hi_i32 s20, s2, 0xa00000
	s_mul_i32 s21, s2, 0xa00000
	s_lshr_b32 s2, s5, 6
	s_mulk_i32 s2, 0x2100
	s_add_i32 s5, s2, 0
	v_bfe_u32 v28, v12, 5, 1
	v_lshlrev_b32_e32 v0, 2, v12
	s_waitcnt lgkmcnt(0)
	s_add_u32 s2, s18, s6
	v_and_b32_e32 v0, 0x7c, v0
	v_mul_u32_u24_e32 v4, 0x84, v28
	s_addc_u32 s3, s19, s7
	v_add3_u32 v29, s5, v0, v4
	v_lshlrev_b32_e32 v4, 3, v12
	v_lshl_add_u64 v[2:3], s[2:3], 0, v[0:1]
	v_and_b32_e32 v4, 56, v4
	v_readlane_b32 s2, v254, 49
	v_lshlrev_b32_e32 v22, 1, v4
	v_mov_b32_e32 v23, v1
	v_readlane_b32 s3, v254, 50
	v_mul_u32_u24_e32 v8, 0x84, v4
	v_bfe_u32 v30, v12, 3, 3
	v_lshl_add_u64 v[4:5], s[2:3], 0, v[22:23]
	s_mov_b64 s[2:3], 0x1580000
	v_lshl_add_u64 v[6:7], v[4:5], 0, s[2:3]
	s_add_u32 s2, s16, s21
	s_addc_u32 s3, s17, s20
	v_readlane_b32 s16, v255, 52
	v_readlane_b32 s17, v255, 53
	v_readlane_b32 s18, v255, 54
	v_readlane_b32 s19, v255, 55
	s_nop 4
	v_lshlrev_b32_e32 v9, 2, v30
	v_and_b32_e32 v10, 63, v12
	v_add3_u32 v31, s5, v8, v9
	v_or_b32_e32 v32, 8, v30
	v_lshl_add_u64 v[8:9], s[2:3], 0, v[0:1]
	v_readlane_b32 s2, v254, 43
	v_lshrrev_b32_e32 v12, 2, v12
	v_bfe_u32 v13, v10, 3, 2
	v_readlane_b32 s3, v254, 44
	v_and_b32_e32 v12, 8, v12
	v_lshlrev_b32_e32 v14, 1, v32
	v_readlane_b32 s6, v254, 61
	v_or_b32_e32 v34, 24, v30
	v_lshl_add_u64 v[10:11], s[2:3], 0, v[22:23]
	v_or_b32_e32 v35, v12, v13
	v_and_or_b32 v36, v14, 24, v13
	v_or_b32_e32 v13, 4, v30
	s_waitcnt lgkmcnt(0)
	s_add_u32 s2, s18, s6
	v_readlane_b32 s5, v254, 60
	v_or_b32_e32 v37, v12, v13
	v_lshlrev_b32_e32 v12, 1, v34
	s_addc_u32 s3, s19, s5
	v_and_or_b32 v38, v12, 24, v13
	v_lshl_add_u64 v[12:13], s[2:3], 0, v[0:1]
	v_readlane_b32 s2, v254, 47
	v_readlane_b32 s3, v254, 48
	v_or_b32_e32 v33, 16, v30
	s_nop 0
	v_lshl_add_u64 v[14:15], s[2:3], 0, v[22:23]
	s_add_u32 s2, s10, s6
	s_addc_u32 s3, s11, s5
	v_lshl_add_u64 v[16:17], s[2:3], 0, v[0:1]
	v_readlane_b32 s2, v254, 51
	v_readlane_b32 s3, v254, 52
	v_readlane_b32 s6, v254, 59
	v_readlane_b32 s5, v254, 58
	v_lshl_add_u64 v[18:19], s[2:3], 0, v[22:23]
	s_add_u32 s2, s16, s6
	s_addc_u32 s3, s17, s5
	v_lshl_add_u64 v[20:21], s[2:3], 0, v[0:1]
	v_readlane_b32 s2, v254, 45
	v_readlane_b32 s3, v254, 46
	s_nop 1
	v_lshl_add_u64 v[22:23], s[2:3], 0, v[22:23]
	s_add_u32 s2, s8, s6
	s_addc_u32 s3, s9, s5
	v_lshl_add_u64 v[24:25], s[2:3], 0, v[0:1]
	s_lshl_b32 s5, s4, 5
	s_lshl_b32 s6, s15, 5
	s_lshl_b32 s7, s4, 1
	s_lshl_b32 s8, s15, 1
	s_branch .LBB0_1117

.LBB0_1138:
	v_readlane_b32 s2, v254, 39
	v_readlane_b32 s3, v254, 40
	s_and_b64 vcc, exec, s[2:3]
	s_cbranch_vccz .LBB0_1017
	s_and_b64 s[2:3], s[12:13], exec
	s_cselect_b32 s2, 0, 0xc0
	s_movk_i32 s3, 0x54
	s_cselect_b32 s3, s3, 0x100
	s_add_i32 s14, s14, s2
	s_cmp_lt_i32 s14, s3
	s_waitcnt vmcnt(0)
	s_barrier
	s_cbranch_scc0 .LBB0_1017
	v_mov_b32_e32 v4, v244
	s_movk_i32 s2, 0xc00
	v_ashrrev_i32_e32 v2, 6, v4
	v_cmp_gt_i32_e32 vcc, s2, v4
	v_readfirstlane_b32 s6, v2
	s_barrier
	s_and_saveexec_b64 s[2:3], vcc
	s_cbranch_execz .LBB0_1143
	v_readlane_b32 s10, v255, 8
	v_readlane_b32 s11, v255, 9
	s_nop 4
	v_readlane_b32 s8, v255, 12
	v_readlane_b32 s9, v255, 13
	s_nop 4
	v_lshlrev_b32_e32 v3, 2, v4
	s_waitcnt lgkmcnt(0)
	s_add_u32 s98, s10, 0x1000
	s_addc_u32 s99, s11, 0
	global_load_dword v0, v3, s[10:11]
	global_load_dword v5, v3, s[10:11] offset:2048
	global_load_dword v6, v3, s[98:99]
	global_load_dword v7, v3, s[98:99] offset:2048
	global_load_dword v34, v3, s[8:9]
	global_load_dword v35, v3, s[8:9] offset:2048
	s_waitcnt vmcnt(0)
	v_mul_f32_e32 v8, 0xbfb8aa3b, v0
	v_exp_f32_e32 v8, v8
	s_nop 0
	v_add_f32_e32 v8, 1.0, v8
	v_div_scale_f32 v9, s[8:9], v8, v8, v0
	v_rcp_f32_e32 v10, v9
	v_div_scale_f32 v11, vcc, v0, v8, v0
	v_fma_f32 v12, -v9, v10, 1.0
	v_fmac_f32_e32 v10, v12, v10
	v_mul_f32_e32 v12, v11, v10
	v_fma_f32 v13, -v9, v12, v11
	v_fmac_f32_e32 v12, v13, v10
	v_fma_f32 v9, -v9, v12, v11
	v_div_fmas_f32 v9, v9, v10, v12
	v_div_fixup_f32 v0, v9, v8, v0
	ds_write_b32 v3, v0
	v_mul_f32_e32 v8, 0xbfb8aa3b, v5
	v_exp_f32_e32 v8, v8
	s_nop 0
	v_add_f32_e32 v8, 1.0, v8
	v_div_scale_f32 v9, s[8:9], v8, v8, v5
	v_rcp_f32_e32 v10, v9
	v_div_scale_f32 v11, vcc, v5, v8, v5
	v_fma_f32 v12, -v9, v10, 1.0
	v_fmac_f32_e32 v10, v12, v10
	v_mul_f32_e32 v12, v11, v10
	v_fma_f32 v13, -v9, v12, v11
	v_fmac_f32_e32 v12, v13, v10
	v_fma_f32 v9, -v9, v12, v11
	v_div_fmas_f32 v9, v9, v10, v12
	v_div_fixup_f32 v5, v9, v8, v5
	ds_write_b32 v3, v5 offset:2048
	v_mul_f32_e32 v8, 0xbfb8aa3b, v6
	v_exp_f32_e32 v8, v8
	s_nop 0
	v_add_f32_e32 v8, 1.0, v8
	v_div_scale_f32 v9, s[8:9], v8, v8, v6
	v_rcp_f32_e32 v10, v9
	v_div_scale_f32 v11, vcc, v6, v8, v6
	v_fma_f32 v12, -v9, v10, 1.0
	v_fmac_f32_e32 v10, v12, v10
	v_mul_f32_e32 v12, v11, v10
	v_fma_f32 v13, -v9, v12, v11
	v_fmac_f32_e32 v12, v13, v10
	v_fma_f32 v9, -v9, v12, v11
	v_div_fmas_f32 v9, v9, v10, v12
	v_div_fixup_f32 v6, v9, v8, v6
	ds_write_b32 v3, v6 offset:4096
	v_mul_f32_e32 v8, 0xbfb8aa3b, v7
	v_exp_f32_e32 v8, v8
	s_nop 0
	v_add_f32_e32 v8, 1.0, v8
	v_div_scale_f32 v9, s[8:9], v8, v8, v7
	v_rcp_f32_e32 v10, v9
	v_div_scale_f32 v11, vcc, v7, v8, v7
	v_fma_f32 v12, -v9, v10, 1.0
	v_fmac_f32_e32 v10, v12, v10
	v_mul_f32_e32 v12, v11, v10
	v_fma_f32 v13, -v9, v12, v11
	v_fmac_f32_e32 v12, v13, v10
	v_fma_f32 v9, -v9, v12, v11
	v_div_fmas_f32 v9, v9, v10, v12
	v_div_fixup_f32 v7, v9, v8, v7
	ds_write_b32 v3, v7 offset:6144
	v_mul_f32_e32 v8, 0xbfb8aa3b, v34
	v_exp_f32_e32 v8, v8
	s_nop 0
	v_add_f32_e32 v8, 1.0, v8
	v_div_scale_f32 v9, s[8:9], v8, v8, v34
	v_rcp_f32_e32 v10, v9
	v_div_scale_f32 v11, vcc, v34, v8, v34
	v_fma_f32 v12, -v9, v10, 1.0
	v_fmac_f32_e32 v10, v12, v10
	v_mul_f32_e32 v12, v11, v10
	v_fma_f32 v13, -v9, v12, v11
	v_fmac_f32_e32 v12, v13, v10
	v_fma_f32 v9, -v9, v12, v11
	v_div_fmas_f32 v9, v9, v10, v12
	v_div_fixup_f32 v34, v9, v8, v34
	ds_write_b32 v3, v34 offset:8192
	v_mul_f32_e32 v8, 0xbfb8aa3b, v35
	v_exp_f32_e32 v8, v8
	s_nop 0
	v_add_f32_e32 v8, 1.0, v8
	v_div_scale_f32 v9, s[8:9], v8, v8, v35
	v_rcp_f32_e32 v10, v9
	v_div_scale_f32 v11, vcc, v35, v8, v35
	v_fma_f32 v12, -v9, v10, 1.0
	v_fmac_f32_e32 v10, v12, v10
	v_mul_f32_e32 v12, v11, v10
	v_fma_f32 v13, -v9, v12, v11
	v_fmac_f32_e32 v12, v13, v10
	v_fma_f32 v9, -v9, v12, v11
	v_div_fmas_f32 v9, v9, v10, v12
	v_div_fixup_f32 v35, v9, v8, v35
	ds_write_b32 v3, v35 offset:10240
.LBB0_1143:
	s_or_b64 exec, exec, s[2:3]
	s_waitcnt lgkmcnt(0)
	s_barrier
	v_readlane_b32 s8, v255, 14
	v_readlane_b32 s9, v255, 15
	v_readlane_b32 s10, v255, 16
	v_readlane_b32 s11, v255, 17
	s_nop 4
	v_readlane_b32 s2, v254, 41
	v_readlane_b32 s3, v254, 42
	s_add_i32 s2, s2, s14
	s_add_i32 s5, s2, 0x100
	s_lshl_b32 s2, s6, 7
	s_mul_i32 s3, s6, 0x480000
	s_mul_hi_i32 s2, s2, 0x9000
	s_waitcnt lgkmcnt(0)
	s_add_u32 s8, s8, s3
	s_addc_u32 s9, s9, s2
	s_lshl_b32 s2, s6, 9
	s_mulk_i32 s6, 0x300
	v_and_b32_e32 v3, 63, v4
	s_add_i32 s4, s2, 0
	s_add_i32 s2, s6, 0
	v_lshl_add_u32 v6, v3, 2, s2
	s_movk_i32 s2, 0xc0
	v_cmp_gt_u32_e32 vcc, 36, v3
	v_cmp_gt_i32_e64 s[6:7], s2, v4
	s_and_b64 s[2:3], s[6:7], vcc
	s_ashr_i32 s6, s5, 8
	s_and_b32 s7, s14, 0xff
	s_mul_i32 s12, s6, 0x2400000
	s_mul_i32 s7, s7, 36
	s_mul_hi_i32 s5, s6, 0x2400000
	s_add_u32 s8, s8, s12
	s_addc_u32 s5, s9, s5
	s_lshl_b32 s80, s7, 2
	v_min_u32_e32 v0, 35, v3
	s_add_u32 s8, s8, s80
	s_addc_u32 s9, s5, 0
	v_lshlrev_b32_e32 v0, 2, v0
	v_lshl_add_u64 v[4:5], s[8:9], 0, v[0:1]
	v_add_co_u32_e32 v8, vcc, s87, v4
	global_load_dword v34, v0, s[8:9] nt
	s_nop 0
	v_addc_co_u32_e32 v9, vcc, 0, v5, vcc
	global_load_dword v35, v[8:9], off nt
	v_add_co_u32_e32 v8, vcc, s45, v4
	s_mov_b32 s5, 0x1b000
	s_nop 0
	v_addc_co_u32_e32 v9, vcc, 0, v5, vcc
	global_load_dword v36, v[8:9], off nt
	v_add_co_u32_e32 v8, vcc, s5, v4
	s_mov_b32 s5, 0x2d000
	s_nop 0
	v_addc_co_u32_e32 v9, vcc, 0, v5, vcc
	global_load_dword v37, v[8:9], off nt
	v_add_co_u32_e32 v8, vcc, s72, v4
	s_nop 1
	v_addc_co_u32_e32 v9, vcc, 0, v5, vcc
	global_load_dword v38, v[8:9], off nt
	v_add_co_u32_e32 v8, vcc, s5, v4
	s_mov_b32 s5, 0x36000
	s_nop 0
	v_addc_co_u32_e32 v9, vcc, 0, v5, vcc
	global_load_dword v39, v[8:9], off nt
	v_add_co_u32_e32 v8, vcc, s5, v4
	s_mov_b32 s5, 0x3f000
	s_nop 0
	v_addc_co_u32_e32 v9, vcc, 0, v5, vcc
	global_load_dword v40, v[8:9], off nt
	v_add_co_u32_e32 v8, vcc, s5, v4
	s_mov_b32 s5, 0x48000
	s_nop 0
	v_addc_co_u32_e32 v9, vcc, 0, v5, vcc
	global_load_dword v41, v[8:9], off nt
	v_add_co_u32_e32 v8, vcc, s5, v4
	s_mov_b32 s5, 0x51000
	s_nop 0
	v_addc_co_u32_e32 v9, vcc, 0, v5, vcc
	global_load_dword v42, v[8:9], off nt
	v_add_co_u32_e32 v8, vcc, s5, v4
	s_mov_b32 s5, 0x5a000
	s_nop 0
	v_addc_co_u32_e32 v9, vcc, 0, v5, vcc
	global_load_dword v43, v[8:9], off nt
	v_add_co_u32_e32 v8, vcc, s5, v4
	s_mov_b32 s5, 0x6c000
	s_nop 0
	v_addc_co_u32_e32 v9, vcc, 0, v5, vcc
	global_load_dword v44, v[8:9], off nt
	v_add_co_u32_e32 v8, vcc, s38, v4
	s_nop 1
	v_addc_co_u32_e32 v9, vcc, 0, v5, vcc
	global_load_dword v45, v[8:9], off nt
	v_add_co_u32_e32 v8, vcc, s5, v4
	s_mov_b32 s5, 0x75000
	s_nop 0
	v_addc_co_u32_e32 v9, vcc, 0, v5, vcc
	global_load_dword v46, v[8:9], off nt
	v_add_co_u32_e32 v8, vcc, s5, v4
	s_mov_b32 s5, 0x7e000
	s_nop 0
	v_addc_co_u32_e32 v9, vcc, 0, v5, vcc
	global_load_dword v47, v[8:9], off nt
	v_add_co_u32_e32 v8, vcc, s5, v4
	s_mov_b32 s5, 0x87000
	s_nop 0
	v_addc_co_u32_e32 v9, vcc, 0, v5, vcc
	global_load_dword v48, v[8:9], off nt
	v_add_co_u32_e32 v8, vcc, s5, v4
	s_mov_b32 s5, 0x90000
	s_nop 0
	v_addc_co_u32_e32 v9, vcc, 0, v5, vcc
	global_load_dword v49, v[8:9], off nt
	v_add_co_u32_e32 v8, vcc, s5, v4
	s_mov_b32 s5, 0x99000
	s_nop 0
	v_addc_co_u32_e32 v9, vcc, 0, v5, vcc
	global_load_dword v50, v[8:9], off nt
	v_add_co_u32_e32 v8, vcc, s5, v4
	s_mov_b32 s5, 0xa2000
	s_nop 0
	v_addc_co_u32_e32 v9, vcc, 0, v5, vcc
	global_load_dword v51, v[8:9], off nt
	v_add_co_u32_e32 v8, vcc, s5, v4
	s_mov_b32 s5, 0xab000
	s_nop 0
	v_addc_co_u32_e32 v9, vcc, 0, v5, vcc
	global_load_dword v52, v[8:9], off nt
	v_add_co_u32_e32 v8, vcc, s5, v4
	s_mov_b32 s5, 0xb4000
	s_nop 0
	v_addc_co_u32_e32 v9, vcc, 0, v5, vcc
	global_load_dword v53, v[8:9], off nt
	v_add_co_u32_e32 v8, vcc, s5, v4
	s_mov_b32 s5, 0xbd000
	s_nop 0
	v_addc_co_u32_e32 v9, vcc, 0, v5, vcc
	global_load_dword v54, v[8:9], off nt
	v_add_co_u32_e32 v8, vcc, s5, v4
	s_mov_b32 s5, 0xcf000
	s_nop 0
	v_addc_co_u32_e32 v9, vcc, 0, v5, vcc
	global_load_dword v55, v[8:9], off nt
	v_add_co_u32_e32 v8, vcc, s39, v4
	s_nop 1
	v_addc_co_u32_e32 v9, vcc, 0, v5, vcc
	global_load_dword v56, v[8:9], off nt
	v_add_co_u32_e32 v8, vcc, s5, v4
	s_mov_b32 s5, 0xd8000
	s_nop 0
	v_addc_co_u32_e32 v9, vcc, 0, v5, vcc
	global_load_dword v57, v[8:9], off nt
	v_add_co_u32_e32 v8, vcc, s5, v4
	s_mov_b32 s5, 0xe1000
	s_nop 0
	v_addc_co_u32_e32 v9, vcc, 0, v5, vcc
	global_load_dword v58, v[8:9], off nt
	v_add_co_u32_e32 v8, vcc, s5, v4
	s_mov_b32 s5, 0xea000
	s_nop 0
	v_addc_co_u32_e32 v9, vcc, 0, v5, vcc
	global_load_dword v59, v[8:9], off nt
	v_add_co_u32_e32 v8, vcc, s5, v4
	s_mov_b32 s5, 0xf3000
	s_nop 0
	v_addc_co_u32_e32 v9, vcc, 0, v5, vcc
	global_load_dword v60, v[8:9], off nt
	v_add_co_u32_e32 v8, vcc, s5, v4
	s_mov_b32 s5, 0xfc000
	s_nop 0
	v_addc_co_u32_e32 v9, vcc, 0, v5, vcc
	global_load_dword v61, v[8:9], off nt
	v_add_co_u32_e32 v8, vcc, s5, v4
	s_mov_b32 s5, 0x105000
	s_nop 0
	v_addc_co_u32_e32 v9, vcc, 0, v5, vcc
	global_load_dword v62, v[8:9], off nt
	v_add_co_u32_e32 v8, vcc, s5, v4
	s_mov_b32 s5, 0x10e000
	s_nop 0
	v_addc_co_u32_e32 v9, vcc, 0, v5, vcc
	global_load_dword v63, v[8:9], off nt
	v_add_co_u32_e32 v8, vcc, s5, v4
	s_mov_b32 s5, 0x117000
	s_nop 0
	v_addc_co_u32_e32 v9, vcc, 0, v5, vcc
	global_load_dword v64, v[8:9], off nt
	v_add_co_u32_e32 v8, vcc, s5, v4
	s_nop 1
	v_addc_co_u32_e32 v9, vcc, 0, v5, vcc
	global_load_dword v65, v[8:9], off nt
	v_mov_b32_e32 v9, s4
	ds_read_b128 v[10:13], v9
	ds_read_b128 v[14:17], v9 offset:16
	ds_read_b128 v[18:21], v9 offset:32
	ds_read_b128 v[22:25], v9 offset:48
	ds_read_b128 v[26:29], v9 offset:4096
	s_waitcnt vmcnt(31) lgkmcnt(4)
	v_fma_f32 v0, v34, v10, 0
	s_waitcnt vmcnt(30)
	v_fmac_f32_e32 v0, v35, v11
	s_waitcnt vmcnt(29)
	v_fmac_f32_e32 v0, v36, v12
	s_waitcnt vmcnt(28)
	v_fmac_f32_e32 v0, v37, v13
	ds_read_b128 v[10:13], v9 offset:4112
	s_waitcnt lgkmcnt(1)
	v_fma_f32 v7, v34, v26, 0
	v_fmac_f32_e32 v7, v35, v27
	v_fmac_f32_e32 v7, v36, v28
	v_fmac_f32_e32 v7, v37, v29
	s_waitcnt vmcnt(27) lgkmcnt(0)
	v_fmac_f32_e32 v7, v38, v10
	s_waitcnt vmcnt(26)
	v_fmac_f32_e32 v7, v39, v11
	ds_read_b128 v[30:33], v9 offset:8192
	s_waitcnt vmcnt(25)
	v_fmac_f32_e32 v7, v40, v12
	s_waitcnt vmcnt(24)
	v_fmac_f32_e32 v7, v41, v13
	ds_read_b128 v[10:13], v9 offset:4128
	ds_read_b128 v[26:29], v9 offset:8208
	s_waitcnt lgkmcnt(2)
	v_fma_f32 v8, v34, v30, 0
	v_fmac_f32_e32 v0, v38, v14
	v_fmac_f32_e32 v8, v35, v31
	v_fmac_f32_e32 v0, v39, v15
	s_waitcnt vmcnt(23) lgkmcnt(1)
	v_fmac_f32_e32 v7, v42, v10
	v_fmac_f32_e32 v8, v36, v32
	v_fmac_f32_e32 v0, v40, v16
	s_waitcnt vmcnt(22)
	v_fmac_f32_e32 v7, v43, v11
	v_fmac_f32_e32 v8, v37, v33
	v_fmac_f32_e32 v0, v41, v17
	ds_read_b128 v[14:17], v9 offset:8224
	s_waitcnt vmcnt(21)
	v_fmac_f32_e32 v7, v44, v12
	s_waitcnt vmcnt(20)
	v_fmac_f32_e32 v7, v45, v13
	ds_read_b128 v[10:13], v9 offset:4144
	s_waitcnt lgkmcnt(2)
	v_fmac_f32_e32 v8, v38, v26
	v_fmac_f32_e32 v8, v39, v27
	v_fmac_f32_e32 v0, v42, v18
	v_fmac_f32_e32 v8, v40, v28
	v_fmac_f32_e32 v0, v43, v19
	v_fmac_f32_e32 v8, v41, v29
	v_fmac_f32_e32 v0, v44, v20
	v_fmac_f32_e32 v0, v45, v21
	ds_read_b128 v[18:21], v9 offset:8256
	s_waitcnt lgkmcnt(2)
	v_fmac_f32_e32 v8, v42, v14
	v_fmac_f32_e32 v8, v43, v15
	v_fmac_f32_e32 v8, v44, v16
	v_fmac_f32_e32 v8, v45, v17
	s_waitcnt vmcnt(19) lgkmcnt(1)
	v_fmac_f32_e32 v7, v46, v10
	ds_read_b128 v[14:17], v9 offset:8240
	s_waitcnt vmcnt(18)
	v_fmac_f32_e32 v7, v47, v11
	s_waitcnt vmcnt(17)
	v_fmac_f32_e32 v7, v48, v12
	s_waitcnt vmcnt(16)
	v_fmac_f32_e32 v7, v49, v13
	ds_read_b128 v[10:13], v9 offset:64
	v_fmac_f32_e32 v0, v46, v22
	s_waitcnt lgkmcnt(1)
	v_fmac_f32_e32 v8, v46, v14
	v_fmac_f32_e32 v0, v47, v23
	v_fmac_f32_e32 v8, v47, v15
	v_fmac_f32_e32 v0, v48, v24
	v_fmac_f32_e32 v8, v48, v16
	v_fmac_f32_e32 v0, v49, v25
	v_fmac_f32_e32 v8, v49, v17
	ds_read_b128 v[14:17], v9 offset:4160
	s_waitcnt vmcnt(15) lgkmcnt(1)
	v_fmac_f32_e32 v0, v50, v10
	s_waitcnt vmcnt(14)
	v_fmac_f32_e32 v0, v51, v11
	s_waitcnt vmcnt(13)
	v_fmac_f32_e32 v0, v52, v12
	s_waitcnt vmcnt(12)
	v_fmac_f32_e32 v0, v53, v13
	ds_read_b128 v[10:13], v9 offset:80
	s_waitcnt lgkmcnt(1)
	v_fmac_f32_e32 v7, v50, v14
	v_fmac_f32_e32 v7, v51, v15
	v_fmac_f32_e32 v7, v52, v16
	v_fmac_f32_e32 v7, v53, v17
	ds_read_b128 v[14:17], v9 offset:4176
	s_waitcnt vmcnt(11) lgkmcnt(1)
	v_fmac_f32_e32 v0, v54, v10
	s_waitcnt vmcnt(10)
	v_fmac_f32_e32 v0, v55, v11
	s_waitcnt vmcnt(9)
	v_fmac_f32_e32 v0, v56, v12
	s_waitcnt vmcnt(8)
	v_fmac_f32_e32 v0, v57, v13
	ds_read_b128 v[10:13], v9 offset:96
	s_waitcnt lgkmcnt(1)
	v_fmac_f32_e32 v7, v54, v14
	v_fmac_f32_e32 v7, v55, v15
	v_fmac_f32_e32 v7, v56, v16
	v_fmac_f32_e32 v7, v57, v17
	ds_read_b128 v[14:17], v9 offset:4192
	s_waitcnt vmcnt(7) lgkmcnt(1)
	v_fmac_f32_e32 v0, v58, v10
	s_waitcnt vmcnt(6)
	v_fmac_f32_e32 v0, v59, v11
	s_waitcnt vmcnt(5)
	v_fmac_f32_e32 v0, v60, v12
	s_waitcnt vmcnt(4)
	v_fmac_f32_e32 v0, v61, v13
	ds_read_b128 v[10:13], v9 offset:112
	s_waitcnt lgkmcnt(1)
	v_fmac_f32_e32 v7, v58, v14
	v_fmac_f32_e32 v7, v59, v15
	v_fmac_f32_e32 v7, v60, v16
	s_mov_b32 s4, 0x120000
	v_fmac_f32_e32 v7, v61, v17
	ds_read_b128 v[14:17], v9 offset:4208
	s_waitcnt vmcnt(3) lgkmcnt(1)
	v_fmac_f32_e32 v0, v62, v10
	v_add_co_u32_e32 v10, vcc, s4, v4
	s_waitcnt vmcnt(2)
	v_fmac_f32_e32 v0, v63, v11
	v_addc_co_u32_e32 v11, vcc, 0, v5, vcc
	global_load_dword v22, v[10:11], off nt
	v_add_co_u32_e32 v10, vcc, s91, v4
	s_mov_b32 s4, 0x132000
	s_nop 0
	v_addc_co_u32_e32 v11, vcc, 0, v5, vcc
	global_load_dword v23, v[10:11], off nt
	v_add_co_u32_e32 v10, vcc, s4, v4
	s_mov_b32 s4, 0x13b000
	s_nop 0
	v_addc_co_u32_e32 v11, vcc, 0, v5, vcc
	global_load_dword v24, v[10:11], off nt
	v_add_co_u32_e32 v10, vcc, s4, v4
	s_mov_b32 s4, 0x144000
	s_nop 0
	v_addc_co_u32_e32 v11, vcc, 0, v5, vcc
	global_load_dword v25, v[10:11], off nt
	v_add_co_u32_e32 v10, vcc, s4, v4
	s_mov_b32 s4, 0x14d000
	s_nop 0
	v_addc_co_u32_e32 v11, vcc, 0, v5, vcc
	global_load_dword v26, v[10:11], off nt
	v_add_co_u32_e32 v10, vcc, s4, v4
	s_mov_b32 s4, 0x156000
	s_nop 0
	v_addc_co_u32_e32 v11, vcc, 0, v5, vcc
	global_load_dword v27, v[10:11], off nt
	v_add_co_u32_e32 v10, vcc, s4, v4
	s_mov_b32 s4, 0x15f000
	s_nop 0
	v_addc_co_u32_e32 v11, vcc, 0, v5, vcc
	global_load_dword v28, v[10:11], off nt
	v_add_co_u32_e32 v10, vcc, s4, v4
	s_mov_b32 s4, 0x168000
	s_nop 0
	v_addc_co_u32_e32 v11, vcc, 0, v5, vcc
	global_load_dword v29, v[10:11], off nt
	v_add_co_u32_e32 v10, vcc, s4, v4
	s_mov_b32 s4, 0x171000
	s_nop 0
	v_addc_co_u32_e32 v11, vcc, 0, v5, vcc
	global_load_dword v30, v[10:11], off nt
	v_add_co_u32_e32 v10, vcc, s4, v4
	s_mov_b32 s4, 0x17a000
	s_nop 0
	v_addc_co_u32_e32 v11, vcc, 0, v5, vcc
	global_load_dword v31, v[10:11], off nt
	v_add_co_u32_e32 v10, vcc, s4, v4
	s_mov_b32 s4, 0x183000
	s_nop 0
	v_addc_co_u32_e32 v11, vcc, 0, v5, vcc
	global_load_dword v32, v[10:11], off nt
	v_add_co_u32_e32 v10, vcc, s4, v4
	s_mov_b32 s4, 0x18c000
	s_nop 0
	v_addc_co_u32_e32 v11, vcc, 0, v5, vcc
	global_load_dword v33, v[10:11], off nt
	v_add_co_u32_e32 v10, vcc, s4, v4
	s_mov_b32 s4, 0x195000
	s_nop 0
	v_addc_co_u32_e32 v11, vcc, 0, v5, vcc
	global_load_dword v34, v[10:11], off nt
	v_add_co_u32_e32 v10, vcc, s4, v4
	s_mov_b32 s4, 0x19e000
	s_nop 0
	v_addc_co_u32_e32 v11, vcc, 0, v5, vcc
	global_load_dword v35, v[10:11], off nt
	v_add_co_u32_e32 v10, vcc, s4, v4
	s_mov_b32 s4, 0x1a7000
	s_nop 0
	v_addc_co_u32_e32 v11, vcc, 0, v5, vcc
	global_load_dword v36, v[10:11], off nt
	v_add_co_u32_e32 v10, vcc, s4, v4
	s_mov_b32 s4, 0x1b0000
	s_nop 0
	v_addc_co_u32_e32 v11, vcc, 0, v5, vcc
	global_load_dword v37, v[10:11], off nt
	v_add_co_u32_e32 v10, vcc, s4, v4
	s_mov_b32 s4, 0x1b9000
	s_nop 0
	v_addc_co_u32_e32 v11, vcc, 0, v5, vcc
	global_load_dword v38, v[10:11], off nt
	v_add_co_u32_e32 v10, vcc, s4, v4
	s_mov_b32 s4, 0x1c2000
	s_nop 0
	v_addc_co_u32_e32 v11, vcc, 0, v5, vcc
	global_load_dword v39, v[10:11], off nt
	v_add_co_u32_e32 v10, vcc, s4, v4
	s_mov_b32 s4, 0x1cb000
	s_nop 0
	v_addc_co_u32_e32 v11, vcc, 0, v5, vcc
	global_load_dword v40, v[10:11], off nt
	v_add_co_u32_e32 v10, vcc, s4, v4
	s_mov_b32 s4, 0x1d4000
	s_nop 0
	v_addc_co_u32_e32 v11, vcc, 0, v5, vcc
	global_load_dword v41, v[10:11], off nt
	v_add_co_u32_e32 v10, vcc, s4, v4
	s_mov_b32 s4, 0x1dd000
	s_nop 0
	v_addc_co_u32_e32 v11, vcc, 0, v5, vcc
	global_load_dword v42, v[10:11], off nt
	v_add_co_u32_e32 v10, vcc, s4, v4
	s_mov_b32 s4, 0x1e6000
	s_nop 0
	v_addc_co_u32_e32 v11, vcc, 0, v5, vcc
	global_load_dword v43, v[10:11], off nt
	v_add_co_u32_e32 v10, vcc, s4, v4
	s_mov_b32 s4, 0x1ef000
	s_nop 0
	v_addc_co_u32_e32 v11, vcc, 0, v5, vcc
	global_load_dword v44, v[10:11], off nt
	v_add_co_u32_e32 v10, vcc, s4, v4
	s_mov_b32 s4, 0x1f8000
	s_nop 0
	v_addc_co_u32_e32 v11, vcc, 0, v5, vcc
	global_load_dword v45, v[10:11], off nt
	v_add_co_u32_e32 v10, vcc, s4, v4
	s_mov_b32 s4, 0x201000
	s_nop 0
	v_addc_co_u32_e32 v11, vcc, 0, v5, vcc
	global_load_dword v46, v[10:11], off nt
	v_add_co_u32_e32 v10, vcc, s4, v4
	s_mov_b32 s4, 0x20a000
	s_nop 0
	v_addc_co_u32_e32 v11, vcc, 0, v5, vcc
	global_load_dword v47, v[10:11], off nt
	v_add_co_u32_e32 v10, vcc, s4, v4
	s_mov_b32 s4, 0x213000
	s_nop 0
	v_addc_co_u32_e32 v11, vcc, 0, v5, vcc
	global_load_dword v48, v[10:11], off nt
	v_add_co_u32_e32 v10, vcc, s4, v4
	s_mov_b32 s4, 0x21c000
	s_nop 0
	v_addc_co_u32_e32 v11, vcc, 0, v5, vcc
	global_load_dword v49, v[10:11], off nt
	v_add_co_u32_e32 v10, vcc, s4, v4
	s_mov_b32 s4, 0x225000
	s_nop 0
	v_addc_co_u32_e32 v11, vcc, 0, v5, vcc
	v_fmac_f32_e32 v8, v50, v18
	global_load_dword v50, v[10:11], off nt
	v_add_co_u32_e32 v10, vcc, s4, v4
	v_fmac_f32_e32 v8, v51, v19
	s_nop 0
	v_addc_co_u32_e32 v11, vcc, 0, v5, vcc
	global_load_dword v51, v[10:11], off nt
	s_mov_b32 s4, 0x22e000
	v_add_co_u32_e32 v10, vcc, s4, v4
	s_mov_b32 s4, 0x237000
	s_nop 0
	v_addc_co_u32_e32 v11, vcc, 0, v5, vcc
	v_fmac_f32_e32 v8, v52, v20
	global_load_dword v52, v[10:11], off nt
	v_add_co_u32_e32 v10, vcc, s4, v4
	s_waitcnt vmcnt(32)
	v_fmac_f32_e32 v0, v64, v12
	v_addc_co_u32_e32 v11, vcc, 0, v5, vcc
	v_fmac_f32_e32 v8, v53, v21
	s_waitcnt vmcnt(31)
	v_fmac_f32_e32 v0, v65, v13
	global_load_dword v53, v[10:11], off nt
	ds_read_b128 v[10:13], v9 offset:128
	s_waitcnt lgkmcnt(1)
	v_fmac_f32_e32 v7, v62, v14
	v_fmac_f32_e32 v7, v63, v15
	v_fmac_f32_e32 v7, v64, v16
	v_fmac_f32_e32 v7, v65, v17
	ds_read_b128 v[14:17], v9 offset:4224
	s_waitcnt vmcnt(31) lgkmcnt(1)
	v_fmac_f32_e32 v0, v22, v10
	s_waitcnt vmcnt(30)
	v_fmac_f32_e32 v0, v23, v11
	s_waitcnt vmcnt(29)
	v_fmac_f32_e32 v0, v24, v12
	s_waitcnt vmcnt(28)
	v_fmac_f32_e32 v0, v25, v13
	ds_read_b128 v[10:13], v9 offset:144
	s_waitcnt lgkmcnt(1)
	v_fmac_f32_e32 v7, v22, v14
	v_fmac_f32_e32 v7, v23, v15
	v_fmac_f32_e32 v7, v24, v16
	v_fmac_f32_e32 v7, v25, v17
	ds_read_b128 v[14:17], v9 offset:4240
	s_waitcnt vmcnt(27) lgkmcnt(1)
	v_fmac_f32_e32 v0, v26, v10
	s_waitcnt vmcnt(26)
	v_fmac_f32_e32 v0, v27, v11
	s_waitcnt vmcnt(25)
	v_fmac_f32_e32 v0, v28, v12
	s_waitcnt vmcnt(24)
	v_fmac_f32_e32 v0, v29, v13
	ds_read_b128 v[10:13], v9 offset:160
	s_waitcnt lgkmcnt(1)
	v_fmac_f32_e32 v7, v26, v14
	v_fmac_f32_e32 v7, v27, v15
	v_fmac_f32_e32 v7, v28, v16
	v_fmac_f32_e32 v7, v29, v17
	ds_read_b128 v[14:17], v9 offset:4256
	s_waitcnt vmcnt(23) lgkmcnt(1)
	v_fmac_f32_e32 v0, v30, v10
	s_waitcnt vmcnt(22)
	v_fmac_f32_e32 v0, v31, v11
	s_waitcnt vmcnt(21)
	v_fmac_f32_e32 v0, v32, v12
	s_waitcnt vmcnt(20)
	v_fmac_f32_e32 v0, v33, v13
	ds_read_b128 v[10:13], v9 offset:176
	s_waitcnt lgkmcnt(1)
	v_fmac_f32_e32 v7, v30, v14
	v_fmac_f32_e32 v7, v31, v15
	v_fmac_f32_e32 v7, v32, v16
	v_fmac_f32_e32 v7, v33, v17
	ds_read_b128 v[14:17], v9 offset:4272
	s_waitcnt vmcnt(19) lgkmcnt(1)
	v_fmac_f32_e32 v0, v34, v10
	s_waitcnt vmcnt(18)
	v_fmac_f32_e32 v0, v35, v11
	s_waitcnt vmcnt(17)
	v_fmac_f32_e32 v0, v36, v12
	s_waitcnt vmcnt(16)
	v_fmac_f32_e32 v0, v37, v13
	ds_read_b128 v[10:13], v9 offset:192
	ds_read_b128 v[18:21], v9 offset:8272
	s_waitcnt lgkmcnt(2)
	v_fmac_f32_e32 v7, v34, v14
	v_fmac_f32_e32 v7, v35, v15
	v_fmac_f32_e32 v7, v36, v16
	v_fmac_f32_e32 v7, v37, v17
	ds_read_b128 v[14:17], v9 offset:4288
	s_waitcnt vmcnt(15) lgkmcnt(2)
	v_fmac_f32_e32 v0, v38, v10
	s_waitcnt vmcnt(14)
	v_fmac_f32_e32 v0, v39, v11
	s_waitcnt lgkmcnt(1)
	v_fmac_f32_e32 v8, v54, v18
	s_waitcnt vmcnt(13)
	v_fmac_f32_e32 v0, v40, v12
	v_fmac_f32_e32 v8, v55, v19
	s_waitcnt vmcnt(12)
	v_fmac_f32_e32 v0, v41, v13
	ds_read_b128 v[10:13], v9 offset:208
	v_fmac_f32_e32 v8, v56, v20
	v_fmac_f32_e32 v8, v57, v21
	ds_read_b128 v[18:21], v9 offset:8288
	s_waitcnt lgkmcnt(2)
	v_fmac_f32_e32 v7, v38, v14
	v_fmac_f32_e32 v7, v39, v15
	v_fmac_f32_e32 v7, v40, v16
	v_fmac_f32_e32 v7, v41, v17
	ds_read_b128 v[14:17], v9 offset:4304
	s_waitcnt vmcnt(11) lgkmcnt(2)
	v_fmac_f32_e32 v0, v42, v10
	s_waitcnt vmcnt(10)
	v_fmac_f32_e32 v0, v43, v11
	s_waitcnt lgkmcnt(1)
	v_fmac_f32_e32 v8, v58, v18
	s_waitcnt vmcnt(9)
	v_fmac_f32_e32 v0, v44, v12
	v_fmac_f32_e32 v8, v59, v19
	s_waitcnt vmcnt(8)
	v_fmac_f32_e32 v0, v45, v13
	ds_read_b128 v[10:13], v9 offset:224
	v_fmac_f32_e32 v8, v60, v20
	v_fmac_f32_e32 v8, v61, v21
	ds_read_b128 v[18:21], v9 offset:8304
	s_waitcnt lgkmcnt(2)
	v_fmac_f32_e32 v7, v42, v14
	v_fmac_f32_e32 v7, v43, v15
	v_fmac_f32_e32 v7, v44, v16
	v_fmac_f32_e32 v7, v45, v17
	ds_read_b128 v[14:17], v9 offset:4320
	s_waitcnt vmcnt(7) lgkmcnt(2)
	v_fmac_f32_e32 v0, v46, v10
	s_waitcnt vmcnt(6)
	v_fmac_f32_e32 v0, v47, v11
	s_waitcnt lgkmcnt(1)
	v_fmac_f32_e32 v8, v62, v18
	s_waitcnt vmcnt(5)
	v_fmac_f32_e32 v0, v48, v12
	v_fmac_f32_e32 v8, v63, v19
	s_waitcnt vmcnt(4)
	v_fmac_f32_e32 v0, v49, v13
	ds_read_b128 v[10:13], v9 offset:240
	v_fmac_f32_e32 v8, v64, v20
	v_fmac_f32_e32 v8, v65, v21
	ds_read_b128 v[18:21], v9 offset:8320
	s_waitcnt lgkmcnt(2)
	v_fmac_f32_e32 v7, v46, v14
	v_fmac_f32_e32 v7, v47, v15
	v_fmac_f32_e32 v7, v48, v16
	s_mov_b32 s4, 0x240000
	v_fmac_f32_e32 v7, v49, v17
	ds_read_b128 v[14:17], v9 offset:4336
	s_waitcnt vmcnt(3) lgkmcnt(2)
	v_fmac_f32_e32 v0, v50, v10
	v_add_co_u32_e32 v10, vcc, s4, v4
	s_waitcnt vmcnt(2)
	v_fmac_f32_e32 v0, v51, v11
	v_addc_co_u32_e32 v11, vcc, 0, v5, vcc
	s_mov_b32 s4, 0x249000
	s_waitcnt lgkmcnt(1)
	v_fmac_f32_e32 v8, v22, v18
	global_load_dword v22, v[10:11], off nt
	v_add_co_u32_e32 v10, vcc, s4, v4
	v_fmac_f32_e32 v8, v23, v19
	s_nop 0
	v_addc_co_u32_e32 v11, vcc, 0, v5, vcc
	s_mov_b32 s4, 0x252000
	v_fmac_f32_e32 v8, v24, v20
	global_load_dword v23, v[10:11], off nt
	v_add_co_u32_e32 v10, vcc, s4, v4
	v_fmac_f32_e32 v8, v25, v21
	ds_read_b128 v[18:21], v9 offset:8336
	v_addc_co_u32_e32 v11, vcc, 0, v5, vcc
	s_mov_b32 s4, 0x25b000
	global_load_dword v24, v[10:11], off nt
	v_add_co_u32_e32 v10, vcc, s4, v4
	s_mov_b32 s4, 0x264000
	s_nop 0
	v_addc_co_u32_e32 v11, vcc, 0, v5, vcc
	global_load_dword v25, v[10:11], off nt
	v_add_co_u32_e32 v10, vcc, s4, v4
	s_mov_b32 s4, 0x26d000
	s_nop 0
	v_addc_co_u32_e32 v11, vcc, 0, v5, vcc
	s_waitcnt lgkmcnt(0)
	v_fmac_f32_e32 v8, v26, v18
	global_load_dword v26, v[10:11], off nt
	v_add_co_u32_e32 v10, vcc, s4, v4
	v_fmac_f32_e32 v8, v27, v19
	s_nop 0
	v_addc_co_u32_e32 v11, vcc, 0, v5, vcc
	s_mov_b32 s4, 0x276000
	v_fmac_f32_e32 v8, v28, v20
	global_load_dword v27, v[10:11], off nt
	v_add_co_u32_e32 v10, vcc, s4, v4
	v_fmac_f32_e32 v8, v29, v21
	ds_read_b128 v[18:21], v9 offset:8352
	v_addc_co_u32_e32 v11, vcc, 0, v5, vcc
	s_mov_b32 s4, 0x27f000
	global_load_dword v28, v[10:11], off nt
	v_add_co_u32_e32 v10, vcc, s4, v4
	s_mov_b32 s4, 0x288000
	s_nop 0
	v_addc_co_u32_e32 v11, vcc, 0, v5, vcc
	global_load_dword v29, v[10:11], off nt
	v_add_co_u32_e32 v10, vcc, s4, v4
	s_mov_b32 s4, 0x291000
	s_nop 0
	v_addc_co_u32_e32 v11, vcc, 0, v5, vcc
	s_waitcnt lgkmcnt(0)
	v_fmac_f32_e32 v8, v30, v18
	global_load_dword v30, v[10:11], off nt
	v_add_co_u32_e32 v10, vcc, s4, v4
	v_fmac_f32_e32 v8, v31, v19
	s_nop 0
	v_addc_co_u32_e32 v11, vcc, 0, v5, vcc
	s_mov_b32 s4, 0x29a000
	v_fmac_f32_e32 v8, v32, v20
	global_load_dword v31, v[10:11], off nt
	v_add_co_u32_e32 v10, vcc, s4, v4
	v_fmac_f32_e32 v8, v33, v21
	ds_read_b128 v[18:21], v9 offset:8368
	v_addc_co_u32_e32 v11, vcc, 0, v5, vcc
	s_mov_b32 s4, 0x2a3000
	global_load_dword v32, v[10:11], off nt
	v_add_co_u32_e32 v10, vcc, s4, v4
	s_mov_b32 s4, 0x2ac000
	s_nop 0
	v_addc_co_u32_e32 v11, vcc, 0, v5, vcc
	global_load_dword v33, v[10:11], off nt
	v_add_co_u32_e32 v10, vcc, s4, v4
	s_mov_b32 s4, 0x2b5000
	s_nop 0
	v_addc_co_u32_e32 v11, vcc, 0, v5, vcc
	s_waitcnt lgkmcnt(0)
	v_fmac_f32_e32 v8, v34, v18
	global_load_dword v34, v[10:11], off nt
	v_add_co_u32_e32 v10, vcc, s4, v4
	v_fmac_f32_e32 v8, v35, v19
	s_nop 0
	v_addc_co_u32_e32 v11, vcc, 0, v5, vcc
	s_mov_b32 s4, 0x2be000
	v_fmac_f32_e32 v8, v36, v20
	global_load_dword v35, v[10:11], off nt
	v_add_co_u32_e32 v10, vcc, s4, v4
	v_fmac_f32_e32 v8, v37, v21
	ds_read_b128 v[18:21], v9 offset:8384
	v_addc_co_u32_e32 v11, vcc, 0, v5, vcc
	s_mov_b32 s4, 0x2c7000
	global_load_dword v36, v[10:11], off nt
	v_add_co_u32_e32 v10, vcc, s4, v4
	s_mov_b32 s4, 0x2d0000
	s_nop 0
	v_addc_co_u32_e32 v11, vcc, 0, v5, vcc
	global_load_dword v37, v[10:11], off nt
	v_add_co_u32_e32 v10, vcc, s4, v4
	s_mov_b32 s4, 0x2d9000
	s_nop 0
	v_addc_co_u32_e32 v11, vcc, 0, v5, vcc
	s_waitcnt lgkmcnt(0)
	v_fmac_f32_e32 v8, v38, v18
	global_load_dword v38, v[10:11], off nt
	v_add_co_u32_e32 v10, vcc, s4, v4
	v_fmac_f32_e32 v8, v39, v19
	s_nop 0
	v_addc_co_u32_e32 v11, vcc, 0, v5, vcc
	s_mov_b32 s4, 0x2e2000
	v_fmac_f32_e32 v8, v40, v20
	global_load_dword v39, v[10:11], off nt
	v_add_co_u32_e32 v10, vcc, s4, v4
	v_fmac_f32_e32 v8, v41, v21
	ds_read_b128 v[18:21], v9 offset:8400
	v_addc_co_u32_e32 v11, vcc, 0, v5, vcc
	s_mov_b32 s4, 0x2eb000
	global_load_dword v40, v[10:11], off nt
	v_add_co_u32_e32 v10, vcc, s4, v4
	s_mov_b32 s4, 0x2f4000
	s_nop 0
	v_addc_co_u32_e32 v11, vcc, 0, v5, vcc
	global_load_dword v41, v[10:11], off nt
	v_add_co_u32_e32 v10, vcc, s4, v4
	s_mov_b32 s4, 0x2fd000
	s_nop 0
	v_addc_co_u32_e32 v11, vcc, 0, v5, vcc
	s_waitcnt lgkmcnt(0)
	v_fmac_f32_e32 v8, v42, v18
	global_load_dword v42, v[10:11], off nt
	v_add_co_u32_e32 v10, vcc, s4, v4
	v_fmac_f32_e32 v8, v43, v19
	s_nop 0
	v_addc_co_u32_e32 v11, vcc, 0, v5, vcc
	s_mov_b32 s4, 0x306000
	v_fmac_f32_e32 v8, v44, v20
	global_load_dword v43, v[10:11], off nt
	v_add_co_u32_e32 v10, vcc, s4, v4
	v_fmac_f32_e32 v8, v45, v21
	ds_read_b128 v[18:21], v9 offset:8416
	v_addc_co_u32_e32 v11, vcc, 0, v5, vcc
	s_mov_b32 s4, 0x30f000
	global_load_dword v44, v[10:11], off nt
	v_add_co_u32_e32 v10, vcc, s4, v4
	s_mov_b32 s4, 0x318000
	s_nop 0
	v_addc_co_u32_e32 v11, vcc, 0, v5, vcc
	global_load_dword v45, v[10:11], off nt
	v_add_co_u32_e32 v10, vcc, s4, v4
	s_mov_b32 s4, 0x321000
	s_nop 0
	v_addc_co_u32_e32 v11, vcc, 0, v5, vcc
	s_waitcnt lgkmcnt(0)
	v_fmac_f32_e32 v8, v46, v18
	global_load_dword v46, v[10:11], off nt
	v_add_co_u32_e32 v10, vcc, s4, v4
	s_mov_b32 s4, 0x32a000
	s_nop 0
	v_addc_co_u32_e32 v11, vcc, 0, v5, vcc
	v_fmac_f32_e32 v8, v47, v19
	global_load_dword v47, v[10:11], off nt
	v_add_co_u32_e32 v10, vcc, s4, v4
	s_mov_b32 s4, 0x333000
	s_nop 0
	v_addc_co_u32_e32 v11, vcc, 0, v5, vcc
	v_fmac_f32_e32 v8, v48, v20
	global_load_dword v48, v[10:11], off nt
	v_add_co_u32_e32 v10, vcc, s4, v4
	v_fmac_f32_e32 v8, v49, v21
	ds_read_b128 v[18:21], v9 offset:8432
	v_addc_co_u32_e32 v11, vcc, 0, v5, vcc
	global_load_dword v49, v[10:11], off nt
	s_mov_b32 s4, 0x33c000
	v_add_co_u32_e32 v10, vcc, s4, v4
	s_mov_b32 s4, 0x345000
	s_nop 0
	v_addc_co_u32_e32 v11, vcc, 0, v5, vcc
	v_fmac_f32_e32 v7, v50, v14
	s_waitcnt lgkmcnt(0)
	v_fmac_f32_e32 v8, v50, v18
	global_load_dword v50, v[10:11], off nt
	v_add_co_u32_e32 v10, vcc, s4, v4
	v_fmac_f32_e32 v7, v51, v15
	s_nop 0
	v_addc_co_u32_e32 v11, vcc, 0, v5, vcc
	v_fmac_f32_e32 v8, v51, v19
	global_load_dword v51, v[10:11], off nt
	s_mov_b32 s4, 0x34e000
	v_add_co_u32_e32 v10, vcc, s4, v4
	s_mov_b32 s4, 0x357000
	s_nop 0
	v_addc_co_u32_e32 v11, vcc, 0, v5, vcc
	s_waitcnt vmcnt(31)
	v_fmac_f32_e32 v0, v52, v12
	v_fmac_f32_e32 v7, v52, v16
	v_fmac_f32_e32 v8, v52, v20
	global_load_dword v52, v[10:11], off nt
	v_add_co_u32_e32 v10, vcc, s4, v4
	s_waitcnt vmcnt(31)
	v_fmac_f32_e32 v0, v53, v13
	v_addc_co_u32_e32 v11, vcc, 0, v5, vcc
	v_fmac_f32_e32 v7, v53, v17
	v_fmac_f32_e32 v8, v53, v21
	global_load_dword v53, v[10:11], off nt
	ds_read_b128 v[10:13], v9 offset:256
	ds_read_b128 v[14:17], v9 offset:4352
	ds_read_b128 v[18:21], v9 offset:8448
	s_mov_b32 s4, 0x360000
	s_waitcnt vmcnt(31) lgkmcnt(2)
	v_fmac_f32_e32 v0, v22, v10
	s_waitcnt vmcnt(30)
	v_fmac_f32_e32 v0, v23, v11
	s_waitcnt vmcnt(29)
	v_fmac_f32_e32 v0, v24, v12
	s_waitcnt vmcnt(28)
	v_fmac_f32_e32 v0, v25, v13
	ds_read_b128 v[10:13], v9 offset:272
	s_waitcnt lgkmcnt(2)
	v_fmac_f32_e32 v7, v22, v14
	v_fmac_f32_e32 v7, v23, v15
	v_fmac_f32_e32 v7, v24, v16
	v_fmac_f32_e32 v7, v25, v17
	ds_read_b128 v[14:17], v9 offset:4368
	s_waitcnt vmcnt(27) lgkmcnt(1)
	v_fmac_f32_e32 v0, v26, v10
	s_waitcnt vmcnt(26)
	v_fmac_f32_e32 v0, v27, v11
	s_waitcnt vmcnt(25)
	v_fmac_f32_e32 v0, v28, v12
	s_waitcnt vmcnt(24)
	v_fmac_f32_e32 v0, v29, v13
	ds_read_b128 v[10:13], v9 offset:288
	s_waitcnt lgkmcnt(1)
	v_fmac_f32_e32 v7, v26, v14
	v_fmac_f32_e32 v7, v27, v15
	v_fmac_f32_e32 v7, v28, v16
	v_fmac_f32_e32 v7, v29, v17
	ds_read_b128 v[14:17], v9 offset:4384
	s_waitcnt vmcnt(23) lgkmcnt(1)
	v_fmac_f32_e32 v0, v30, v10
	s_waitcnt vmcnt(22)
	v_fmac_f32_e32 v0, v31, v11
	s_waitcnt vmcnt(21)
	v_fmac_f32_e32 v0, v32, v12
	s_waitcnt vmcnt(20)
	v_fmac_f32_e32 v0, v33, v13
	ds_read_b128 v[10:13], v9 offset:304
	s_waitcnt lgkmcnt(1)
	v_fmac_f32_e32 v7, v30, v14
	v_fmac_f32_e32 v7, v31, v15
	v_fmac_f32_e32 v7, v32, v16
	v_fmac_f32_e32 v7, v33, v17
	ds_read_b128 v[14:17], v9 offset:4400
	s_waitcnt vmcnt(19) lgkmcnt(1)
	v_fmac_f32_e32 v0, v34, v10
	s_waitcnt vmcnt(18)
	v_fmac_f32_e32 v0, v35, v11
	s_waitcnt vmcnt(17)
	v_fmac_f32_e32 v0, v36, v12
	s_waitcnt vmcnt(16)
	v_fmac_f32_e32 v0, v37, v13
	ds_read_b128 v[10:13], v9 offset:320
	v_fmac_f32_e32 v8, v22, v18
	v_fmac_f32_e32 v8, v23, v19
	s_waitcnt lgkmcnt(1)
	v_fmac_f32_e32 v7, v34, v14
	v_fmac_f32_e32 v8, v24, v20
	v_fmac_f32_e32 v7, v35, v15
	v_fmac_f32_e32 v8, v25, v21
	ds_read_b128 v[18:21], v9 offset:8464
	v_fmac_f32_e32 v7, v36, v16
	v_fmac_f32_e32 v7, v37, v17
	ds_read_b128 v[14:17], v9 offset:4416
	s_waitcnt vmcnt(15) lgkmcnt(2)
	v_fmac_f32_e32 v0, v38, v10
	s_waitcnt vmcnt(14)
	v_fmac_f32_e32 v0, v39, v11
	s_waitcnt vmcnt(13)
	v_fmac_f32_e32 v0, v40, v12
	s_waitcnt vmcnt(12)
	v_fmac_f32_e32 v0, v41, v13
	ds_read_b128 v[10:13], v9 offset:336
	s_waitcnt lgkmcnt(2)
	v_fmac_f32_e32 v8, v26, v18
	v_fmac_f32_e32 v8, v27, v19
	s_waitcnt lgkmcnt(1)
	v_fmac_f32_e32 v7, v38, v14
	v_fmac_f32_e32 v8, v28, v20
	v_fmac_f32_e32 v7, v39, v15
	v_fmac_f32_e32 v8, v29, v21
	ds_read_b128 v[18:21], v9 offset:8480
	v_fmac_f32_e32 v7, v40, v16
	v_fmac_f32_e32 v7, v41, v17
	ds_read_b128 v[14:17], v9 offset:4432
	s_waitcnt vmcnt(11) lgkmcnt(2)
	v_fmac_f32_e32 v0, v42, v10
	s_waitcnt vmcnt(10)
	v_fmac_f32_e32 v0, v43, v11
	s_waitcnt vmcnt(9)
	v_fmac_f32_e32 v0, v44, v12
	s_waitcnt vmcnt(8)
	v_fmac_f32_e32 v0, v45, v13
	ds_read_b128 v[10:13], v9 offset:352
	s_waitcnt lgkmcnt(2)
	v_fmac_f32_e32 v8, v30, v18
	v_fmac_f32_e32 v8, v31, v19
	s_waitcnt lgkmcnt(1)
	v_fmac_f32_e32 v7, v42, v14
	v_fmac_f32_e32 v8, v32, v20
	v_fmac_f32_e32 v7, v43, v15
	v_fmac_f32_e32 v8, v33, v21
	ds_read_b128 v[18:21], v9 offset:8496
	v_fmac_f32_e32 v7, v44, v16
	v_fmac_f32_e32 v7, v45, v17
	ds_read_b128 v[14:17], v9 offset:4448
	s_waitcnt vmcnt(7) lgkmcnt(2)
	v_fmac_f32_e32 v0, v46, v10
	s_waitcnt vmcnt(6)
	v_fmac_f32_e32 v0, v47, v11
	s_waitcnt vmcnt(5)
	v_fmac_f32_e32 v0, v48, v12
	s_waitcnt vmcnt(4)
	v_fmac_f32_e32 v0, v49, v13
	ds_read_b128 v[10:13], v9 offset:368
	s_waitcnt lgkmcnt(2)
	v_fmac_f32_e32 v8, v34, v18
	v_fmac_f32_e32 v8, v35, v19
	s_waitcnt lgkmcnt(1)
	v_fmac_f32_e32 v7, v46, v14
	v_fmac_f32_e32 v8, v36, v20
	v_fmac_f32_e32 v7, v47, v15
	v_fmac_f32_e32 v8, v37, v21
	ds_read_b128 v[18:21], v9 offset:8512
	v_fmac_f32_e32 v7, v48, v16
	v_fmac_f32_e32 v7, v49, v17
	ds_read_b128 v[14:17], v9 offset:4464
	s_waitcnt vmcnt(3) lgkmcnt(2)
	v_fmac_f32_e32 v0, v50, v10
	v_add_co_u32_e32 v10, vcc, s4, v4
	s_waitcnt vmcnt(2)
	v_fmac_f32_e32 v0, v51, v11
	v_addc_co_u32_e32 v11, vcc, 0, v5, vcc
	s_mov_b32 s4, 0x369000
	global_load_dword v37, v[10:11], off nt
	v_add_co_u32_e32 v10, vcc, s4, v4
	s_mov_b32 s4, 0x372000
	s_nop 0
	v_addc_co_u32_e32 v11, vcc, 0, v5, vcc
	s_waitcnt lgkmcnt(1)
	v_fmac_f32_e32 v8, v38, v18
	global_load_dword v38, v[10:11], off nt
	v_add_co_u32_e32 v10, vcc, s4, v4
	s_mov_b32 s4, 0x37b000
	s_nop 0
	v_addc_co_u32_e32 v11, vcc, 0, v5, vcc
	v_fmac_f32_e32 v8, v39, v19
	global_load_dword v39, v[10:11], off nt
	v_add_co_u32_e32 v10, vcc, s4, v4
	v_fmac_f32_e32 v8, v40, v20
	s_nop 0
	v_addc_co_u32_e32 v11, vcc, 0, v5, vcc
	global_load_dword v40, v[10:11], off nt
	s_mov_b32 s4, 0x384000
	v_add_co_u32_e32 v10, vcc, s4, v4
	s_mov_b32 s4, 0x38d000
	s_nop 0
	v_addc_co_u32_e32 v11, vcc, 0, v5, vcc
	global_load_dword v25, v[10:11], off nt
	v_add_co_u32_e32 v10, vcc, s4, v4
	s_mov_b32 s4, 0x396000
	s_nop 0
	v_addc_co_u32_e32 v11, vcc, 0, v5, vcc
	global_load_dword v26, v[10:11], off nt
	v_add_co_u32_e32 v10, vcc, s4, v4
	s_mov_b32 s4, 0x39f000
	s_nop 0
	v_addc_co_u32_e32 v11, vcc, 0, v5, vcc
	global_load_dword v28, v[10:11], off nt
	v_add_co_u32_e32 v10, vcc, s4, v4
	s_mov_b32 s4, 0x3a8000
	s_nop 0
	v_addc_co_u32_e32 v11, vcc, 0, v5, vcc
	global_load_dword v30, v[10:11], off nt
	v_add_co_u32_e32 v10, vcc, s4, v4
	s_mov_b32 s4, 0x3b1000
	s_nop 0
	v_addc_co_u32_e32 v11, vcc, 0, v5, vcc
	global_load_dword v24, v[10:11], off nt
	v_add_co_u32_e32 v10, vcc, s4, v4
	s_mov_b32 s4, 0x3ba000
	s_nop 0
	v_addc_co_u32_e32 v11, vcc, 0, v5, vcc
	global_load_dword v27, v[10:11], off nt
	v_add_co_u32_e32 v10, vcc, s4, v4
	s_mov_b32 s4, 0x3c3000
	s_nop 0
	v_addc_co_u32_e32 v11, vcc, 0, v5, vcc
	global_load_dword v29, v[10:11], off nt
	v_add_co_u32_e32 v10, vcc, s4, v4
	v_fmac_f32_e32 v8, v41, v21
	ds_read_b128 v[18:21], v9 offset:8528
	v_addc_co_u32_e32 v11, vcc, 0, v5, vcc
	s_mov_b32 s4, 0x3cc000
	global_load_dword v32, v[10:11], off nt
	v_add_co_u32_e32 v10, vcc, s4, v4
	s_waitcnt vmcnt(13)
	v_fmac_f32_e32 v0, v52, v12
	v_addc_co_u32_e32 v11, vcc, 0, v5, vcc
	s_mov_b32 s4, 0x3d5000
	s_waitcnt vmcnt(12)
	v_fmac_f32_e32 v0, v53, v13
	global_load_dword v13, v[10:11], off nt
	v_add_co_u32_e32 v10, vcc, s4, v4
	s_mov_b32 s4, 0x3de000
	s_nop 0
	v_addc_co_u32_e32 v11, vcc, 0, v5, vcc
	s_waitcnt lgkmcnt(0)
	v_fmac_f32_e32 v8, v42, v18
	v_fmac_f32_e32 v7, v50, v14
	global_load_dword v14, v[10:11], off nt
	v_add_co_u32_e32 v10, vcc, s4, v4
	v_fmac_f32_e32 v8, v43, v19
	s_nop 0
	v_addc_co_u32_e32 v11, vcc, 0, v5, vcc
	s_mov_b32 s4, 0x3e7000
	v_fmac_f32_e32 v8, v44, v20
	v_fmac_f32_e32 v7, v51, v15
	global_load_dword v15, v[10:11], off nt
	v_add_co_u32_e32 v10, vcc, s4, v4
	v_fmac_f32_e32 v8, v45, v21
	ds_read_b128 v[18:21], v9 offset:8544
	v_addc_co_u32_e32 v11, vcc, 0, v5, vcc
	s_mov_b32 s4, 0x3f0000
	global_load_dword v34, v[10:11], off nt
	v_add_co_u32_e32 v10, vcc, s4, v4
	s_mov_b32 s4, 0x3f9000
	s_nop 0
	v_addc_co_u32_e32 v11, vcc, 0, v5, vcc
	global_load_dword v31, v[10:11], off nt
	v_add_co_u32_e32 v10, vcc, s4, v4
	s_mov_b32 s4, 0x402000
	s_nop 0
	v_addc_co_u32_e32 v11, vcc, 0, v5, vcc
	s_waitcnt lgkmcnt(0)
	v_fmac_f32_e32 v8, v46, v18
	global_load_dword v33, v[10:11], off nt
	v_add_co_u32_e32 v10, vcc, s4, v4
	v_fmac_f32_e32 v8, v47, v19
	s_nop 0
	v_addc_co_u32_e32 v11, vcc, 0, v5, vcc
	s_mov_b32 s4, 0x40b000
	v_fmac_f32_e32 v8, v48, v20
	global_load_dword v35, v[10:11], off nt
	v_add_co_u32_e32 v10, vcc, s4, v4
	v_fmac_f32_e32 v8, v49, v21
	ds_read_b128 v[18:21], v9 offset:8560
	v_addc_co_u32_e32 v11, vcc, 0, v5, vcc
	s_mov_b32 s4, 0x414000
	global_load_dword v36, v[10:11], off nt
	v_add_co_u32_e32 v10, vcc, s4, v4
	v_fmac_f32_e32 v7, v52, v16
	s_nop 0
	v_addc_co_u32_e32 v11, vcc, 0, v5, vcc
	s_mov_b32 s4, 0x41d000
	v_fmac_f32_e32 v7, v53, v17
	global_load_dword v17, v[10:11], off nt
	v_add_co_u32_e32 v10, vcc, s4, v4
	s_mov_b32 s4, 0x426000
	s_nop 0
	v_addc_co_u32_e32 v11, vcc, 0, v5, vcc
	s_waitcnt lgkmcnt(0)
	v_fmac_f32_e32 v8, v50, v18
	global_load_dword v18, v[10:11], off nt
	v_add_co_u32_e32 v10, vcc, s4, v4
	v_fmac_f32_e32 v8, v51, v19
	s_nop 0
	v_addc_co_u32_e32 v11, vcc, 0, v5, vcc
	s_mov_b32 s4, 0x42f000
	v_fmac_f32_e32 v8, v52, v20
	global_load_dword v20, v[10:11], off nt
	v_add_co_u32_e32 v10, vcc, s4, v4
	s_mov_b32 s4, 0x438000
	s_nop 0
	v_addc_co_u32_e32 v11, vcc, 0, v5, vcc
	global_load_dword v22, v[10:11], off nt
	v_add_co_u32_e32 v10, vcc, s4, v4
	s_mov_b32 s4, 0x441000
	s_nop 0
	v_addc_co_u32_e32 v11, vcc, 0, v5, vcc
	global_load_dword v16, v[10:11], off nt
	v_add_co_u32_e32 v10, vcc, s4, v4
	s_mov_b32 s4, 0x44a000
	s_nop 0
	v_addc_co_u32_e32 v11, vcc, 0, v5, vcc
	global_load_dword v19, v[10:11], off nt
	v_add_co_u32_e32 v10, vcc, s4, v4
	s_mov_b32 s4, 0x453000
	s_nop 0
	v_addc_co_u32_e32 v11, vcc, 0, v5, vcc
	v_fmac_f32_e32 v8, v53, v21
	global_load_dword v21, v[10:11], off nt
	v_add_co_u32_e32 v10, vcc, s4, v4
	s_mov_b32 s4, 0x45c000
	s_nop 0
	v_addc_co_u32_e32 v11, vcc, 0, v5, vcc
	global_load_dword v23, v[10:11], off nt
	v_add_co_u32_e32 v10, vcc, s4, v4
	s_mov_b32 s4, 0x465000
	s_nop 0
	v_addc_co_u32_e32 v11, vcc, 0, v5, vcc
	v_add_co_u32_e32 v42, vcc, s4, v4
	s_mov_b32 s4, 0x46e000
	s_nop 0
	v_addc_co_u32_e32 v43, vcc, 0, v5, vcc
	global_load_dword v10, v[10:11], off nt
	ds_read_b128 v[46:49], v9 offset:4480
	global_load_dword v11, v[42:43], off nt
	v_add_co_u32_e32 v42, vcc, s4, v4
	s_mov_b32 s4, 0x477000
	s_nop 0
	v_addc_co_u32_e32 v43, vcc, 0, v5, vcc
	v_add_co_u32_e32 v4, vcc, s4, v4
	global_load_dword v12, v[42:43], off nt
	s_nop 0
	v_addc_co_u32_e32 v5, vcc, 0, v5, vcc
	global_load_dword v4, v[4:5], off nt
	ds_read_b128 v[42:45], v9 offset:384
	ds_read_b128 v[50:53], v9 offset:8576
	s_waitcnt vmcnt(31) lgkmcnt(2)
	v_fmac_f32_e32 v7, v37, v46
	s_waitcnt vmcnt(30)
	v_fmac_f32_e32 v7, v38, v47
	s_waitcnt vmcnt(29)
	v_fmac_f32_e32 v7, v39, v48
	s_waitcnt lgkmcnt(1)
	v_fmac_f32_e32 v0, v37, v42
	s_waitcnt vmcnt(28)
	v_fmac_f32_e32 v7, v40, v49
	ds_read_b128 v[46:49], v9 offset:8592
	s_waitcnt lgkmcnt(1)
	v_fmac_f32_e32 v8, v37, v50
	v_fmac_f32_e32 v0, v38, v43
	v_fmac_f32_e32 v8, v38, v51
	v_fmac_f32_e32 v0, v39, v44
	v_fmac_f32_e32 v8, v39, v52
	v_fmac_f32_e32 v0, v40, v45
	v_fmac_f32_e32 v8, v40, v53
	ds_read_b128 v[38:41], v9 offset:400
	ds_read_b128 v[42:45], v9 offset:4496
	s_waitcnt vmcnt(27) lgkmcnt(2)
	v_fmac_f32_e32 v8, v25, v46
	s_waitcnt vmcnt(26)
	v_fmac_f32_e32 v8, v26, v47
	s_waitcnt vmcnt(25)
	v_fmac_f32_e32 v8, v28, v48
	s_waitcnt lgkmcnt(1)
	v_fmac_f32_e32 v0, v25, v38
	s_waitcnt lgkmcnt(0)
	v_fmac_f32_e32 v7, v25, v42
	v_fmac_f32_e32 v0, v26, v39
	v_fmac_f32_e32 v7, v26, v43
	v_fmac_f32_e32 v0, v28, v40
	v_fmac_f32_e32 v7, v28, v44
	s_waitcnt vmcnt(24)
	v_fmac_f32_e32 v0, v30, v41
	v_fmac_f32_e32 v7, v30, v45
	ds_read_b128 v[38:41], v9 offset:416
	ds_read_b128 v[42:45], v9 offset:4512
	v_fmac_f32_e32 v8, v30, v49
	ds_read_b128 v[46:49], v9 offset:8608
	s_waitcnt vmcnt(23) lgkmcnt(2)
	v_fmac_f32_e32 v0, v24, v38
	s_waitcnt lgkmcnt(1)
	v_fmac_f32_e32 v7, v24, v42
	s_waitcnt vmcnt(22)
	v_fmac_f32_e32 v7, v27, v43
	s_waitcnt vmcnt(21)
	v_fmac_f32_e32 v7, v29, v44
	v_fmac_f32_e32 v0, v27, v39
	s_waitcnt vmcnt(20)
	v_fmac_f32_e32 v7, v32, v45
	ds_read_b128 v[42:45], v9 offset:8624
	s_waitcnt lgkmcnt(1)
	v_fmac_f32_e32 v8, v24, v46
	v_fmac_f32_e32 v8, v27, v47
	v_fmac_f32_e32 v0, v29, v40
	ds_read_b128 v[24:27], v9 offset:432
	v_fmac_f32_e32 v0, v32, v41
	ds_read_b128 v[38:41], v9 offset:4528
	v_fmac_f32_e32 v8, v29, v48
	v_fmac_f32_e32 v8, v32, v49
	s_waitcnt vmcnt(19) lgkmcnt(1)
	v_fmac_f32_e32 v0, v13, v24
	v_fmac_f32_e32 v8, v13, v42
	s_waitcnt lgkmcnt(0)
	v_fmac_f32_e32 v7, v13, v38
	s_waitcnt vmcnt(18)
	v_fmac_f32_e32 v0, v14, v25
	v_fmac_f32_e32 v7, v14, v39
	v_fmac_f32_e32 v8, v14, v43
	s_waitcnt vmcnt(17)
	v_fmac_f32_e32 v0, v15, v26
	v_fmac_f32_e32 v7, v15, v40
	v_fmac_f32_e32 v8, v15, v44
	s_waitcnt vmcnt(16)
	v_fmac_f32_e32 v0, v34, v27
	ds_read_b128 v[24:27], v9 offset:448
	v_fmac_f32_e32 v7, v34, v41
	v_fmac_f32_e32 v8, v34, v45
	ds_read_b128 v[38:41], v9 offset:4544
	ds_read_b128 v[42:45], v9 offset:8640
	s_waitcnt vmcnt(15) lgkmcnt(2)
	v_fmac_f32_e32 v0, v31, v24
	s_waitcnt vmcnt(14)
	v_fmac_f32_e32 v0, v33, v25
	s_waitcnt vmcnt(13)
	v_fmac_f32_e32 v0, v35, v26
	s_waitcnt lgkmcnt(1)
	v_fmac_f32_e32 v7, v31, v38
	s_waitcnt lgkmcnt(0)
	v_fmac_f32_e32 v8, v31, v42
	v_fmac_f32_e32 v7, v33, v39
	v_fmac_f32_e32 v8, v33, v43
	v_fmac_f32_e32 v7, v35, v40
	v_fmac_f32_e32 v8, v35, v44
	s_waitcnt vmcnt(12)
	v_fmac_f32_e32 v0, v36, v27
	ds_read_b128 v[24:27], v9 offset:464
	ds_read_b128 v[28:31], v9 offset:4560
	ds_read_b128 v[32:35], v9 offset:8656
	v_fmac_f32_e32 v7, v36, v41
	v_fmac_f32_e32 v8, v36, v45
	s_waitcnt vmcnt(11) lgkmcnt(2)
	v_fmac_f32_e32 v0, v17, v24
	s_waitcnt lgkmcnt(1)
	v_fmac_f32_e32 v7, v17, v28
	s_waitcnt lgkmcnt(0)
	v_fmac_f32_e32 v8, v17, v32
	s_waitcnt vmcnt(10)
	v_fmac_f32_e32 v0, v18, v25
	v_fmac_f32_e32 v7, v18, v29
	v_fmac_f32_e32 v8, v18, v33
	s_waitcnt vmcnt(9)
	v_fmac_f32_e32 v0, v20, v26
	v_fmac_f32_e32 v7, v20, v30
	v_fmac_f32_e32 v8, v20, v34
	s_waitcnt vmcnt(8)
	v_fmac_f32_e32 v0, v22, v27
	v_fmac_f32_e32 v7, v22, v31
	v_fmac_f32_e32 v8, v22, v35
	ds_read_b128 v[24:27], v9 offset:480
	ds_read_b128 v[28:31], v9 offset:4576
	ds_read_b128 v[32:35], v9 offset:8672
	s_waitcnt vmcnt(7) lgkmcnt(2)
	v_fmac_f32_e32 v0, v16, v24
	s_waitcnt lgkmcnt(1)
	v_fmac_f32_e32 v7, v16, v28
	s_waitcnt lgkmcnt(0)
	v_fmac_f32_e32 v8, v16, v32
	s_waitcnt vmcnt(6)
	v_fmac_f32_e32 v0, v19, v25
	v_fmac_f32_e32 v7, v19, v29
	v_fmac_f32_e32 v8, v19, v33
	s_waitcnt vmcnt(5)
	v_fmac_f32_e32 v0, v21, v26
	v_fmac_f32_e32 v7, v21, v30
	v_fmac_f32_e32 v8, v21, v34
	ds_read_b128 v[14:17], v9 offset:496
	ds_read_b128 v[18:21], v9 offset:4592
	s_waitcnt vmcnt(4)
	v_fmac_f32_e32 v0, v23, v27
	v_fmac_f32_e32 v7, v23, v31
	v_fmac_f32_e32 v8, v23, v35
	ds_read_b128 v[22:25], v9 offset:8688
	s_waitcnt vmcnt(3) lgkmcnt(2)
	v_fmac_f32_e32 v0, v10, v14
	s_waitcnt lgkmcnt(1)
	v_fmac_f32_e32 v7, v10, v18
	s_waitcnt vmcnt(2)
	v_fmac_f32_e32 v0, v11, v15
	v_fmac_f32_e32 v7, v11, v19
	s_waitcnt lgkmcnt(0)
	v_fmac_f32_e32 v8, v10, v22
	v_fmac_f32_e32 v8, v11, v23
	s_waitcnt vmcnt(1)
	v_fmac_f32_e32 v0, v12, v16
	v_fmac_f32_e32 v7, v12, v20
	v_fmac_f32_e32 v8, v12, v24
	s_waitcnt vmcnt(0)
	v_fmac_f32_e32 v0, v4, v17
	v_fmac_f32_e32 v7, v4, v21
	v_fmac_f32_e32 v8, v4, v25
	ds_write2st64_b32 v6, v0, v7 offset0:48 offset1:49
	ds_write_b32 v6, v8 offset:12800
	s_waitcnt lgkmcnt(0)
	s_barrier
	s_and_saveexec_b64 s[4:5], s[2:3]
	s_cbranch_execz .LBB0_1145
	s_mul_i32 s2, s6, 0x2400
	v_lshlrev_b32_e32 v0, 2, v3
	v_lshlrev_b32_e32 v6, 8, v2
	s_add_i32 s2, s2, s7
	v_add3_u32 v8, 0, v0, v6
	v_add_u32_e32 v6, s2, v3
	v_mov_b32_e32 v4, s10
	v_mov_b32_e32 v5, s11
	v_ashrrev_i32_e32 v7, 31, v6
	v_lshl_add_u64 v[4:5], v[6:7], 2, v[4:5]
	global_load_dword v3, v[4:5], off
	ds_read2st64_b32 v[4:5], v8 offset0:48 offset1:51
	s_waitcnt vmcnt(0) lgkmcnt(0)
	v_add_f32_e32 v3, v3, v4
	v_add_f32_e32 v3, v3, v5
	ds_read2st64_b32 v[4:5], v8 offset0:54 offset1:57
	s_waitcnt lgkmcnt(0)
	v_add_f32_e32 v3, v3, v4
	v_add_f32_e32 v3, v3, v5
	ds_read2st64_b32 v[4:5], v8 offset0:60 offset1:63
	s_waitcnt lgkmcnt(0)
	v_add_f32_e32 v3, v3, v4
	v_add_f32_e32 v3, v3, v5
	ds_read2st64_b32 v[4:5], v8 offset0:66 offset1:69
	s_waitcnt lgkmcnt(0)
	v_add_f32_e32 v3, v3, v4
	v_add_f32_e32 v6, v3, v5
	v_mad_u64_u32 v[2:3], s[2:3], s6, 3, v[2:3]
	v_mov_b64_e32 v[4:5], s[68:69]
	v_mad_i64_i32 v[2:3], s[2:3], v2, s87, v[4:5]
	v_lshl_add_u64 v[2:3], v[2:3], 0, s[80:81]
	v_lshl_add_u64 v[2:3], v[2:3], 0, v[0:1]
	global_store_dword v[2:3], v6, off

.LBB0_1178:
	v_mov_b32_e32 v2, v244
	s_cmpk_gt_i32 s8, 0x57f
	v_readfirstlane_b32 s4, v2
	s_cbranch_scc1 .LBB0_1193
	s_lshr_b32 s4, s4, 6
	s_mulk_i32 s4, 0x2100
	s_waitcnt vmcnt(0)
	v_bfe_u32 v20, v2, 5, 1
	v_lshlrev_b32_e32 v0, 2, v2
	s_add_i32 s12, s8, 0x1b80
	s_add_i32 s4, s4, 0
	v_and_b32_e32 v0, 0x7c, v0
	v_mul_u32_u24_e32 v4, 0x84, v20
	v_readlane_b32 s8, v255, 52
	v_readlane_b32 s9, v255, 53
	v_readlane_b32 s10, v255, 54
	v_readlane_b32 s11, v255, 55
	s_nop 4
	v_readlane_b32 s16, v255, 20
	v_readlane_b32 s17, v255, 21
	v_readlane_b32 s18, v255, 22
	v_readlane_b32 s19, v255, 23
	s_nop 4
	v_add3_u32 v21, s4, v0, v4
	v_lshlrev_b32_e32 v4, 3, v2
	v_bfe_u32 v22, v2, 3, 3
	v_and_b32_e32 v4, 56, v4
	v_and_b32_e32 v3, 63, v2
	v_mul_u32_u24_e32 v5, 0x84, v4
	v_lshlrev_b32_e32 v6, 2, v22
	v_or_b32_e32 v24, 8, v22
	v_lshrrev_b32_e32 v2, 2, v2
	v_add3_u32 v23, s4, v5, v6
	v_bfe_u32 v3, v3, 3, 2
	v_and_b32_e32 v2, 8, v2
	v_lshlrev_b32_e32 v5, 1, v24
	s_mul_i32 s13, s2, 0xb00000
	v_or_b32_e32 v26, 24, v22
	v_or_b32_e32 v27, v2, v3
	v_and_or_b32 v28, v5, 24, v3
	v_or_b32_e32 v3, 4, v22
	s_waitcnt lgkmcnt(0)
	s_add_u32 s4, s10, s13
	s_mul_hi_i32 s10, s2, 0xb00000
	v_or_b32_e32 v29, v2, v3
	v_lshlrev_b32_e32 v2, 1, v26
	s_addc_u32 s5, s11, s10
	v_and_or_b32 v30, v2, 24, v3
	v_lshl_add_u64 v[2:3], s[4:5], 0, v[0:1]
	v_readlane_b32 s4, v254, 47
	v_lshlrev_b32_e32 v16, 1, v4
	v_mov_b32_e32 v17, v1
	v_readlane_b32 s5, v254, 48
	v_or_b32_e32 v25, 16, v22
	s_nop 0
	v_lshl_add_u64 v[4:5], s[4:5], 0, v[16:17]
	s_add_u32 s4, s18, s13
	s_addc_u32 s5, s19, s10
	v_lshl_add_u64 v[6:7], s[4:5], 0, v[0:1]
	v_readlane_b32 s4, v254, 51
	v_readlane_b32 s5, v254, 52
	s_mul_i32 s10, s2, 0x1600000
	s_nop 0
	v_lshl_add_u64 v[8:9], s[4:5], 0, v[16:17]
	s_add_u32 s4, s8, s10
	s_mul_hi_i32 s8, s2, 0x1600000
	s_addc_u32 s5, s9, s8
	v_lshl_add_u64 v[10:11], s[4:5], 0, v[0:1]
	v_readlane_b32 s4, v254, 45
	v_readlane_b32 s5, v254, 46
	s_nop 1
	v_lshl_add_u64 v[12:13], s[4:5], 0, v[16:17]
	s_add_u32 s4, s16, s10
	s_addc_u32 s5, s17, s8
	v_lshl_add_u64 v[14:15], s[4:5], 0, v[0:1]
	v_readlane_b32 s4, v254, 49
	v_readlane_b32 s5, v254, 50
	s_lshl_b32 s8, s12, 5
	s_lshl_b32 s9, s7, 5
	v_lshl_add_u64 v[16:17], s[4:5], 0, v[16:17]
	s_lshl_b32 s4, s12, 1
	s_add_i32 s10, s4, 0x1d400
	s_lshl_b32 s11, s7, 1
	s_branch .LBB0_1181

.LBB0_1193:
	v_readlane_b32 s4, v254, 39
	v_readlane_b32 s5, v254, 40
	s_andn2_b64 vcc, exec, s[4:5]
	s_cbranch_vccnz .LBB0_716
	s_cmpk_lt_i32 s6, 0x6c
	s_waitcnt vmcnt(0) lgkmcnt(0)
	s_barrier
	s_cbranch_scc0 .LBB0_716
	v_readlane_b32 s4, v254, 41
	s_add_i32 s4, s6, s4
	v_mov_b32_e32 v4, v244
	s_add_i32 s12, s4, 0x154
	s_addk_i32 s4, 0x155
	s_cmp_lt_i32 s12, s4
	v_ashrrev_i32_e32 v2, 6, v4
	v_readlane_b32 s5, v254, 42
	v_readfirstlane_b32 s13, v2
	s_cbranch_scc0 .LBB0_716
	s_movk_i32 s4, 0xc00
	v_cmp_gt_i32_e32 vcc, s4, v4
	s_barrier
	s_and_saveexec_b64 s[4:5], vcc
	s_cbranch_execz .LBB0_1199
	v_readlane_b32 s10, v255, 8
	v_readlane_b32 s11, v255, 9
	s_nop 4
	v_readlane_b32 s8, v255, 12
	v_readlane_b32 s9, v255, 13
	s_nop 4
	v_lshlrev_b32_e32 v3, 2, v4
	s_waitcnt lgkmcnt(0)
	s_add_u32 s98, s10, 0x1000
	s_addc_u32 s99, s11, 0
	global_load_dword v0, v3, s[10:11]
	global_load_dword v5, v3, s[10:11] offset:2048
	global_load_dword v6, v3, s[98:99]
	global_load_dword v7, v3, s[98:99] offset:2048
	global_load_dword v34, v3, s[8:9]
	global_load_dword v35, v3, s[8:9] offset:2048
	s_waitcnt vmcnt(0)
	v_mul_f32_e32 v8, 0xbfb8aa3b, v0
	v_exp_f32_e32 v8, v8
	s_nop 0
	v_add_f32_e32 v8, 1.0, v8
	v_div_scale_f32 v9, s[8:9], v8, v8, v0
	v_rcp_f32_e32 v10, v9
	v_div_scale_f32 v11, vcc, v0, v8, v0
	v_fma_f32 v12, -v9, v10, 1.0
	v_fmac_f32_e32 v10, v12, v10
	v_mul_f32_e32 v12, v11, v10
	v_fma_f32 v13, -v9, v12, v11
	v_fmac_f32_e32 v12, v13, v10
	v_fma_f32 v9, -v9, v12, v11
	v_div_fmas_f32 v9, v9, v10, v12
	v_div_fixup_f32 v0, v9, v8, v0
	ds_write_b32 v3, v0
	v_mul_f32_e32 v8, 0xbfb8aa3b, v5
	v_exp_f32_e32 v8, v8
	s_nop 0
	v_add_f32_e32 v8, 1.0, v8
	v_div_scale_f32 v9, s[8:9], v8, v8, v5
	v_rcp_f32_e32 v10, v9
	v_div_scale_f32 v11, vcc, v5, v8, v5
	v_fma_f32 v12, -v9, v10, 1.0
	v_fmac_f32_e32 v10, v12, v10
	v_mul_f32_e32 v12, v11, v10
	v_fma_f32 v13, -v9, v12, v11
	v_fmac_f32_e32 v12, v13, v10
	v_fma_f32 v9, -v9, v12, v11
	v_div_fmas_f32 v9, v9, v10, v12
	v_div_fixup_f32 v5, v9, v8, v5
	ds_write_b32 v3, v5 offset:2048
	v_mul_f32_e32 v8, 0xbfb8aa3b, v6
	v_exp_f32_e32 v8, v8
	s_nop 0
	v_add_f32_e32 v8, 1.0, v8
	v_div_scale_f32 v9, s[8:9], v8, v8, v6
	v_rcp_f32_e32 v10, v9
	v_div_scale_f32 v11, vcc, v6, v8, v6
	v_fma_f32 v12, -v9, v10, 1.0
	v_fmac_f32_e32 v10, v12, v10
	v_mul_f32_e32 v12, v11, v10
	v_fma_f32 v13, -v9, v12, v11
	v_fmac_f32_e32 v12, v13, v10
	v_fma_f32 v9, -v9, v12, v11
	v_div_fmas_f32 v9, v9, v10, v12
	v_div_fixup_f32 v6, v9, v8, v6
	ds_write_b32 v3, v6 offset:4096
	v_mul_f32_e32 v8, 0xbfb8aa3b, v7
	v_exp_f32_e32 v8, v8
	s_nop 0
	v_add_f32_e32 v8, 1.0, v8
	v_div_scale_f32 v9, s[8:9], v8, v8, v7
	v_rcp_f32_e32 v10, v9
	v_div_scale_f32 v11, vcc, v7, v8, v7
	v_fma_f32 v12, -v9, v10, 1.0
	v_fmac_f32_e32 v10, v12, v10
	v_mul_f32_e32 v12, v11, v10
	v_fma_f32 v13, -v9, v12, v11
	v_fmac_f32_e32 v12, v13, v10
	v_fma_f32 v9, -v9, v12, v11
	v_div_fmas_f32 v9, v9, v10, v12
	v_div_fixup_f32 v7, v9, v8, v7
	ds_write_b32 v3, v7 offset:6144
	v_mul_f32_e32 v8, 0xbfb8aa3b, v34
	v_exp_f32_e32 v8, v8
	s_nop 0
	v_add_f32_e32 v8, 1.0, v8
	v_div_scale_f32 v9, s[8:9], v8, v8, v34
	v_rcp_f32_e32 v10, v9
	v_div_scale_f32 v11, vcc, v34, v8, v34
	v_fma_f32 v12, -v9, v10, 1.0
	v_fmac_f32_e32 v10, v12, v10
	v_mul_f32_e32 v12, v11, v10
	v_fma_f32 v13, -v9, v12, v11
	v_fmac_f32_e32 v12, v13, v10
	v_fma_f32 v9, -v9, v12, v11
	v_div_fmas_f32 v9, v9, v10, v12
	v_div_fixup_f32 v34, v9, v8, v34
	ds_write_b32 v3, v34 offset:8192
	v_mul_f32_e32 v8, 0xbfb8aa3b, v35
	v_exp_f32_e32 v8, v8
	s_nop 0
	v_add_f32_e32 v8, 1.0, v8
	v_div_scale_f32 v9, s[8:9], v8, v8, v35
	v_rcp_f32_e32 v10, v9
	v_div_scale_f32 v11, vcc, v35, v8, v35
	v_fma_f32 v12, -v9, v10, 1.0
	v_fmac_f32_e32 v10, v12, v10
	v_mul_f32_e32 v12, v11, v10
	v_fma_f32 v13, -v9, v12, v11
	v_fmac_f32_e32 v12, v13, v10
	v_fma_f32 v9, -v9, v12, v11
	v_div_fmas_f32 v9, v9, v10, v12
	v_div_fixup_f32 v35, v9, v8, v35
	ds_write_b32 v3, v35 offset:10240
.LBB0_1199:
	s_or_b64 exec, exec, s[4:5]
	s_waitcnt lgkmcnt(0)
	s_barrier
	v_readlane_b32 s8, v255, 14
	v_readlane_b32 s9, v255, 15
	v_readlane_b32 s10, v255, 16
	v_readlane_b32 s11, v255, 17
	s_nop 4
	s_lshl_b32 s4, s13, 7
	s_mul_i32 s5, s13, 0x480000
	s_mul_hi_i32 s4, s4, 0x9000
	v_and_b32_e32 v3, 63, v4
	s_waitcnt lgkmcnt(0)
	s_add_u32 s5, s8, s5
	s_addc_u32 s14, s9, s4
	s_lshl_b32 s4, s13, 9
	s_mulk_i32 s13, 0x300
	s_add_i32 s6, s13, 0
	v_lshl_add_u32 v6, v3, 2, s6
	s_movk_i32 s6, 0xc0
	v_cmp_gt_u32_e32 vcc, 36, v3
	v_cmp_gt_i32_e64 s[6:7], s6, v4
	s_ashr_i32 s8, s12, 8
	s_add_i32 s4, s4, 0
	s_and_b64 s[6:7], s[6:7], vcc
	s_and_b32 s9, s12, 0xff
	s_mul_i32 s13, s8, 0x2400000
	s_mul_i32 s9, s9, 36
	s_mul_hi_i32 s12, s8, 0x2400000
	s_add_u32 s5, s5, s13
	s_addc_u32 s13, s14, s12
	s_lshl_b32 s80, s9, 2
	v_min_u32_e32 v0, 35, v3
	s_add_u32 s12, s5, s80
	s_addc_u32 s13, s13, 0
	v_lshlrev_b32_e32 v0, 2, v0
	v_lshl_add_u64 v[4:5], s[12:13], 0, v[0:1]
	v_add_co_u32_e32 v8, vcc, s87, v4
	global_load_dword v34, v0, s[12:13] nt
	s_nop 0
	v_addc_co_u32_e32 v9, vcc, 0, v5, vcc
	global_load_dword v35, v[8:9], off nt
	v_add_co_u32_e32 v8, vcc, s45, v4
	s_mov_b32 s5, 0x1b000
	s_nop 0
	v_addc_co_u32_e32 v9, vcc, 0, v5, vcc
	global_load_dword v36, v[8:9], off nt
	v_add_co_u32_e32 v8, vcc, s5, v4
	s_mov_b32 s5, 0x2d000
	s_nop 0
	v_addc_co_u32_e32 v9, vcc, 0, v5, vcc
	global_load_dword v37, v[8:9], off nt
	v_add_co_u32_e32 v8, vcc, s72, v4
	s_nop 1
	v_addc_co_u32_e32 v9, vcc, 0, v5, vcc
	global_load_dword v38, v[8:9], off nt
	v_add_co_u32_e32 v8, vcc, s5, v4
	s_mov_b32 s5, 0x36000
	s_nop 0
	v_addc_co_u32_e32 v9, vcc, 0, v5, vcc
	global_load_dword v39, v[8:9], off nt
	v_add_co_u32_e32 v8, vcc, s5, v4
	s_mov_b32 s5, 0x3f000
	s_nop 0
	v_addc_co_u32_e32 v9, vcc, 0, v5, vcc
	global_load_dword v40, v[8:9], off nt
	v_add_co_u32_e32 v8, vcc, s5, v4
	s_mov_b32 s5, 0x48000
	s_nop 0
	v_addc_co_u32_e32 v9, vcc, 0, v5, vcc
	global_load_dword v41, v[8:9], off nt
	v_add_co_u32_e32 v8, vcc, s5, v4
	s_mov_b32 s5, 0x51000
	s_nop 0
	v_addc_co_u32_e32 v9, vcc, 0, v5, vcc
	global_load_dword v42, v[8:9], off nt
	v_add_co_u32_e32 v8, vcc, s5, v4
	s_mov_b32 s5, 0x5a000
	s_nop 0
	v_addc_co_u32_e32 v9, vcc, 0, v5, vcc
	global_load_dword v43, v[8:9], off nt
	v_add_co_u32_e32 v8, vcc, s5, v4
	s_mov_b32 s5, 0x6c000
	s_nop 0
	v_addc_co_u32_e32 v9, vcc, 0, v5, vcc
	global_load_dword v44, v[8:9], off nt
	v_add_co_u32_e32 v8, vcc, s38, v4
	s_nop 1
	v_addc_co_u32_e32 v9, vcc, 0, v5, vcc
	global_load_dword v45, v[8:9], off nt
	v_add_co_u32_e32 v8, vcc, s5, v4
	s_mov_b32 s5, 0x75000
	s_nop 0
	v_addc_co_u32_e32 v9, vcc, 0, v5, vcc
	global_load_dword v46, v[8:9], off nt
	v_add_co_u32_e32 v8, vcc, s5, v4
	s_mov_b32 s5, 0x7e000
	s_nop 0
	v_addc_co_u32_e32 v9, vcc, 0, v5, vcc
	global_load_dword v47, v[8:9], off nt
	v_add_co_u32_e32 v8, vcc, s5, v4
	s_mov_b32 s5, 0x87000
	s_nop 0
	v_addc_co_u32_e32 v9, vcc, 0, v5, vcc
	global_load_dword v48, v[8:9], off nt
	v_add_co_u32_e32 v8, vcc, s5, v4
	s_mov_b32 s5, 0x90000
	s_nop 0
	v_addc_co_u32_e32 v9, vcc, 0, v5, vcc
	global_load_dword v49, v[8:9], off nt
	v_add_co_u32_e32 v8, vcc, s5, v4
	s_mov_b32 s5, 0x99000
	s_nop 0
	v_addc_co_u32_e32 v9, vcc, 0, v5, vcc
	global_load_dword v50, v[8:9], off nt
	v_add_co_u32_e32 v8, vcc, s5, v4
	s_mov_b32 s5, 0xa2000
	s_nop 0
	v_addc_co_u32_e32 v9, vcc, 0, v5, vcc
	global_load_dword v51, v[8:9], off nt
	v_add_co_u32_e32 v8, vcc, s5, v4
	s_mov_b32 s5, 0xab000
	s_nop 0
	v_addc_co_u32_e32 v9, vcc, 0, v5, vcc
	global_load_dword v52, v[8:9], off nt
	v_add_co_u32_e32 v8, vcc, s5, v4
	s_mov_b32 s5, 0xb4000
	s_nop 0
	v_addc_co_u32_e32 v9, vcc, 0, v5, vcc
	global_load_dword v53, v[8:9], off nt
	v_add_co_u32_e32 v8, vcc, s5, v4
	s_mov_b32 s5, 0xbd000
	s_nop 0
	v_addc_co_u32_e32 v9, vcc, 0, v5, vcc
	global_load_dword v54, v[8:9], off nt
	v_add_co_u32_e32 v8, vcc, s5, v4
	s_mov_b32 s5, 0xcf000
	s_nop 0
	v_addc_co_u32_e32 v9, vcc, 0, v5, vcc
	global_load_dword v55, v[8:9], off nt
	v_add_co_u32_e32 v8, vcc, s39, v4
	s_nop 1
	v_addc_co_u32_e32 v9, vcc, 0, v5, vcc
	global_load_dword v56, v[8:9], off nt
	v_add_co_u32_e32 v8, vcc, s5, v4
	s_mov_b32 s5, 0xd8000
	s_nop 0
	v_addc_co_u32_e32 v9, vcc, 0, v5, vcc
	global_load_dword v57, v[8:9], off nt
	v_add_co_u32_e32 v8, vcc, s5, v4
	s_mov_b32 s5, 0xe1000
	s_nop 0
	v_addc_co_u32_e32 v9, vcc, 0, v5, vcc
	global_load_dword v58, v[8:9], off nt
	v_add_co_u32_e32 v8, vcc, s5, v4
	s_mov_b32 s5, 0xea000
	s_nop 0
	v_addc_co_u32_e32 v9, vcc, 0, v5, vcc
	global_load_dword v59, v[8:9], off nt
	v_add_co_u32_e32 v8, vcc, s5, v4
	s_mov_b32 s5, 0xf3000
	s_nop 0
	v_addc_co_u32_e32 v9, vcc, 0, v5, vcc
	global_load_dword v60, v[8:9], off nt
	v_add_co_u32_e32 v8, vcc, s5, v4
	s_mov_b32 s5, 0xfc000
	s_nop 0
	v_addc_co_u32_e32 v9, vcc, 0, v5, vcc
	global_load_dword v61, v[8:9], off nt
	v_add_co_u32_e32 v8, vcc, s5, v4
	s_mov_b32 s5, 0x105000
	s_nop 0
	v_addc_co_u32_e32 v9, vcc, 0, v5, vcc
	global_load_dword v62, v[8:9], off nt
	v_add_co_u32_e32 v8, vcc, s5, v4
	s_mov_b32 s5, 0x10e000
	s_nop 0
	v_addc_co_u32_e32 v9, vcc, 0, v5, vcc
	global_load_dword v63, v[8:9], off nt
	v_add_co_u32_e32 v8, vcc, s5, v4
	s_mov_b32 s5, 0x117000
	s_nop 0
	v_addc_co_u32_e32 v9, vcc, 0, v5, vcc
	global_load_dword v64, v[8:9], off nt
	v_add_co_u32_e32 v8, vcc, s5, v4
	s_nop 1
	v_addc_co_u32_e32 v9, vcc, 0, v5, vcc
	global_load_dword v65, v[8:9], off nt
	v_mov_b32_e32 v9, s4
	ds_read_b128 v[10:13], v9
	ds_read_b128 v[14:17], v9 offset:16
	ds_read_b128 v[18:21], v9 offset:32
	ds_read_b128 v[22:25], v9 offset:48
	ds_read_b128 v[26:29], v9 offset:4096
	s_waitcnt vmcnt(31) lgkmcnt(4)
	v_fma_f32 v0, v34, v10, 0
	s_waitcnt vmcnt(30)
	v_fmac_f32_e32 v0, v35, v11
	s_waitcnt vmcnt(29)
	v_fmac_f32_e32 v0, v36, v12
	s_waitcnt vmcnt(28)
	v_fmac_f32_e32 v0, v37, v13
	ds_read_b128 v[10:13], v9 offset:4112
	s_waitcnt lgkmcnt(1)
	v_fma_f32 v7, v34, v26, 0
	v_fmac_f32_e32 v7, v35, v27
	v_fmac_f32_e32 v7, v36, v28
	v_fmac_f32_e32 v7, v37, v29
	s_waitcnt vmcnt(27) lgkmcnt(0)
	v_fmac_f32_e32 v7, v38, v10
	s_waitcnt vmcnt(26)
	v_fmac_f32_e32 v7, v39, v11
	ds_read_b128 v[30:33], v9 offset:8192
	s_waitcnt vmcnt(25)
	v_fmac_f32_e32 v7, v40, v12
	s_waitcnt vmcnt(24)
	v_fmac_f32_e32 v7, v41, v13
	ds_read_b128 v[10:13], v9 offset:4128
	ds_read_b128 v[26:29], v9 offset:8208
	s_waitcnt lgkmcnt(2)
	v_fma_f32 v8, v34, v30, 0
	v_fmac_f32_e32 v0, v38, v14
	v_fmac_f32_e32 v8, v35, v31
	v_fmac_f32_e32 v0, v39, v15
	s_waitcnt vmcnt(23) lgkmcnt(1)
	v_fmac_f32_e32 v7, v42, v10
	v_fmac_f32_e32 v8, v36, v32
	v_fmac_f32_e32 v0, v40, v16
	s_waitcnt vmcnt(22)
	v_fmac_f32_e32 v7, v43, v11
	v_fmac_f32_e32 v8, v37, v33
	v_fmac_f32_e32 v0, v41, v17
	ds_read_b128 v[14:17], v9 offset:8224
	s_waitcnt vmcnt(21)
	v_fmac_f32_e32 v7, v44, v12
	s_waitcnt vmcnt(20)
	v_fmac_f32_e32 v7, v45, v13
	ds_read_b128 v[10:13], v9 offset:4144
	s_waitcnt lgkmcnt(2)
	v_fmac_f32_e32 v8, v38, v26
	v_fmac_f32_e32 v8, v39, v27
	v_fmac_f32_e32 v0, v42, v18
	v_fmac_f32_e32 v8, v40, v28
	v_fmac_f32_e32 v0, v43, v19
	v_fmac_f32_e32 v8, v41, v29
	v_fmac_f32_e32 v0, v44, v20
	v_fmac_f32_e32 v0, v45, v21
	ds_read_b128 v[18:21], v9 offset:8256
	s_waitcnt lgkmcnt(2)
	v_fmac_f32_e32 v8, v42, v14
	v_fmac_f32_e32 v8, v43, v15
	v_fmac_f32_e32 v8, v44, v16
	v_fmac_f32_e32 v8, v45, v17
	s_waitcnt vmcnt(19) lgkmcnt(1)
	v_fmac_f32_e32 v7, v46, v10
	ds_read_b128 v[14:17], v9 offset:8240
	s_waitcnt vmcnt(18)
	v_fmac_f32_e32 v7, v47, v11
	s_waitcnt vmcnt(17)
	v_fmac_f32_e32 v7, v48, v12
	s_waitcnt vmcnt(16)
	v_fmac_f32_e32 v7, v49, v13
	ds_read_b128 v[10:13], v9 offset:64
	v_fmac_f32_e32 v0, v46, v22
	s_waitcnt lgkmcnt(1)
	v_fmac_f32_e32 v8, v46, v14
	v_fmac_f32_e32 v0, v47, v23
	v_fmac_f32_e32 v8, v47, v15
	v_fmac_f32_e32 v0, v48, v24
	v_fmac_f32_e32 v8, v48, v16
	v_fmac_f32_e32 v0, v49, v25
	v_fmac_f32_e32 v8, v49, v17
	ds_read_b128 v[14:17], v9 offset:4160
	s_waitcnt vmcnt(15) lgkmcnt(1)
	v_fmac_f32_e32 v0, v50, v10
	s_waitcnt vmcnt(14)
	v_fmac_f32_e32 v0, v51, v11
	s_waitcnt vmcnt(13)
	v_fmac_f32_e32 v0, v52, v12
	s_waitcnt vmcnt(12)
	v_fmac_f32_e32 v0, v53, v13
	ds_read_b128 v[10:13], v9 offset:80
	s_waitcnt lgkmcnt(1)
	v_fmac_f32_e32 v7, v50, v14
	v_fmac_f32_e32 v7, v51, v15
	v_fmac_f32_e32 v7, v52, v16
	v_fmac_f32_e32 v7, v53, v17
	ds_read_b128 v[14:17], v9 offset:4176
	s_waitcnt vmcnt(11) lgkmcnt(1)
	v_fmac_f32_e32 v0, v54, v10
	s_waitcnt vmcnt(10)
	v_fmac_f32_e32 v0, v55, v11
	s_waitcnt vmcnt(9)
	v_fmac_f32_e32 v0, v56, v12
	s_waitcnt vmcnt(8)
	v_fmac_f32_e32 v0, v57, v13
	ds_read_b128 v[10:13], v9 offset:96
	s_waitcnt lgkmcnt(1)
	v_fmac_f32_e32 v7, v54, v14
	v_fmac_f32_e32 v7, v55, v15
	v_fmac_f32_e32 v7, v56, v16
	v_fmac_f32_e32 v7, v57, v17
	ds_read_b128 v[14:17], v9 offset:4192
	s_waitcnt vmcnt(7) lgkmcnt(1)
	v_fmac_f32_e32 v0, v58, v10
	s_waitcnt vmcnt(6)
	v_fmac_f32_e32 v0, v59, v11
	s_waitcnt vmcnt(5)
	v_fmac_f32_e32 v0, v60, v12
	s_waitcnt vmcnt(4)
	v_fmac_f32_e32 v0, v61, v13
	ds_read_b128 v[10:13], v9 offset:112
	s_waitcnt lgkmcnt(1)
	v_fmac_f32_e32 v7, v58, v14
	v_fmac_f32_e32 v7, v59, v15
	v_fmac_f32_e32 v7, v60, v16
	s_mov_b32 s4, 0x120000
	v_fmac_f32_e32 v7, v61, v17
	ds_read_b128 v[14:17], v9 offset:4208
	s_waitcnt vmcnt(3) lgkmcnt(1)
	v_fmac_f32_e32 v0, v62, v10
	v_add_co_u32_e32 v10, vcc, s4, v4
	s_waitcnt vmcnt(2)
	v_fmac_f32_e32 v0, v63, v11
	v_addc_co_u32_e32 v11, vcc, 0, v5, vcc
	global_load_dword v22, v[10:11], off nt
	v_add_co_u32_e32 v10, vcc, s91, v4
	s_mov_b32 s4, 0x132000
	s_nop 0
	v_addc_co_u32_e32 v11, vcc, 0, v5, vcc
	global_load_dword v23, v[10:11], off nt
	v_add_co_u32_e32 v10, vcc, s4, v4
	s_mov_b32 s4, 0x13b000
	s_nop 0
	v_addc_co_u32_e32 v11, vcc, 0, v5, vcc
	global_load_dword v24, v[10:11], off nt
	v_add_co_u32_e32 v10, vcc, s4, v4
	s_mov_b32 s4, 0x144000
	s_nop 0
	v_addc_co_u32_e32 v11, vcc, 0, v5, vcc
	global_load_dword v25, v[10:11], off nt
	v_add_co_u32_e32 v10, vcc, s4, v4
	s_mov_b32 s4, 0x14d000
	s_nop 0
	v_addc_co_u32_e32 v11, vcc, 0, v5, vcc
	global_load_dword v26, v[10:11], off nt
	v_add_co_u32_e32 v10, vcc, s4, v4
	s_mov_b32 s4, 0x156000
	s_nop 0
	v_addc_co_u32_e32 v11, vcc, 0, v5, vcc
	global_load_dword v27, v[10:11], off nt
	v_add_co_u32_e32 v10, vcc, s4, v4
	s_mov_b32 s4, 0x15f000
	s_nop 0
	v_addc_co_u32_e32 v11, vcc, 0, v5, vcc
	global_load_dword v28, v[10:11], off nt
	v_add_co_u32_e32 v10, vcc, s4, v4
	s_mov_b32 s4, 0x168000
	s_nop 0
	v_addc_co_u32_e32 v11, vcc, 0, v5, vcc
	global_load_dword v29, v[10:11], off nt
	v_add_co_u32_e32 v10, vcc, s4, v4
	s_mov_b32 s4, 0x171000
	s_nop 0
	v_addc_co_u32_e32 v11, vcc, 0, v5, vcc
	global_load_dword v30, v[10:11], off nt
	v_add_co_u32_e32 v10, vcc, s4, v4
	s_mov_b32 s4, 0x17a000
	s_nop 0
	v_addc_co_u32_e32 v11, vcc, 0, v5, vcc
	global_load_dword v31, v[10:11], off nt
	v_add_co_u32_e32 v10, vcc, s4, v4
	s_mov_b32 s4, 0x183000
	s_nop 0
	v_addc_co_u32_e32 v11, vcc, 0, v5, vcc
	global_load_dword v32, v[10:11], off nt
	v_add_co_u32_e32 v10, vcc, s4, v4
	s_mov_b32 s4, 0x18c000
	s_nop 0
	v_addc_co_u32_e32 v11, vcc, 0, v5, vcc
	global_load_dword v33, v[10:11], off nt
	v_add_co_u32_e32 v10, vcc, s4, v4
	s_mov_b32 s4, 0x195000
	s_nop 0
	v_addc_co_u32_e32 v11, vcc, 0, v5, vcc
	global_load_dword v34, v[10:11], off nt
	v_add_co_u32_e32 v10, vcc, s4, v4
	s_mov_b32 s4, 0x19e000
	s_nop 0
	v_addc_co_u32_e32 v11, vcc, 0, v5, vcc
	global_load_dword v35, v[10:11], off nt
	v_add_co_u32_e32 v10, vcc, s4, v4
	s_mov_b32 s4, 0x1a7000
	s_nop 0
	v_addc_co_u32_e32 v11, vcc, 0, v5, vcc
	global_load_dword v36, v[10:11], off nt
	v_add_co_u32_e32 v10, vcc, s4, v4
	s_mov_b32 s4, 0x1b0000
	s_nop 0
	v_addc_co_u32_e32 v11, vcc, 0, v5, vcc
	global_load_dword v37, v[10:11], off nt
	v_add_co_u32_e32 v10, vcc, s4, v4
	s_mov_b32 s4, 0x1b9000
	s_nop 0
	v_addc_co_u32_e32 v11, vcc, 0, v5, vcc
	global_load_dword v38, v[10:11], off nt
	v_add_co_u32_e32 v10, vcc, s4, v4
	s_mov_b32 s4, 0x1c2000
	s_nop 0
	v_addc_co_u32_e32 v11, vcc, 0, v5, vcc
	global_load_dword v39, v[10:11], off nt
	v_add_co_u32_e32 v10, vcc, s4, v4
	s_mov_b32 s4, 0x1cb000
	s_nop 0
	v_addc_co_u32_e32 v11, vcc, 0, v5, vcc
	global_load_dword v40, v[10:11], off nt
	v_add_co_u32_e32 v10, vcc, s4, v4
	s_mov_b32 s4, 0x1d4000
	s_nop 0
	v_addc_co_u32_e32 v11, vcc, 0, v5, vcc
	global_load_dword v41, v[10:11], off nt
	v_add_co_u32_e32 v10, vcc, s4, v4
	s_mov_b32 s4, 0x1dd000
	s_nop 0
	v_addc_co_u32_e32 v11, vcc, 0, v5, vcc
	global_load_dword v42, v[10:11], off nt
	v_add_co_u32_e32 v10, vcc, s4, v4
	s_mov_b32 s4, 0x1e6000
	s_nop 0
	v_addc_co_u32_e32 v11, vcc, 0, v5, vcc
	global_load_dword v43, v[10:11], off nt
	v_add_co_u32_e32 v10, vcc, s4, v4
	s_mov_b32 s4, 0x1ef000
	s_nop 0
	v_addc_co_u32_e32 v11, vcc, 0, v5, vcc
	global_load_dword v44, v[10:11], off nt
	v_add_co_u32_e32 v10, vcc, s4, v4
	s_mov_b32 s4, 0x1f8000
	s_nop 0
	v_addc_co_u32_e32 v11, vcc, 0, v5, vcc
	global_load_dword v45, v[10:11], off nt
	v_add_co_u32_e32 v10, vcc, s4, v4
	s_mov_b32 s4, 0x201000
	s_nop 0
	v_addc_co_u32_e32 v11, vcc, 0, v5, vcc
	global_load_dword v46, v[10:11], off nt
	v_add_co_u32_e32 v10, vcc, s4, v4
	s_mov_b32 s4, 0x20a000
	s_nop 0
	v_addc_co_u32_e32 v11, vcc, 0, v5, vcc
	global_load_dword v47, v[10:11], off nt
	v_add_co_u32_e32 v10, vcc, s4, v4
	s_mov_b32 s4, 0x213000
	s_nop 0
	v_addc_co_u32_e32 v11, vcc, 0, v5, vcc
	global_load_dword v48, v[10:11], off nt
	v_add_co_u32_e32 v10, vcc, s4, v4
	s_mov_b32 s4, 0x21c000
	s_nop 0
	v_addc_co_u32_e32 v11, vcc, 0, v5, vcc
	global_load_dword v49, v[10:11], off nt
	v_add_co_u32_e32 v10, vcc, s4, v4
	s_mov_b32 s4, 0x225000
	s_nop 0
	v_addc_co_u32_e32 v11, vcc, 0, v5, vcc
	v_fmac_f32_e32 v8, v50, v18
	global_load_dword v50, v[10:11], off nt
	v_add_co_u32_e32 v10, vcc, s4, v4
	v_fmac_f32_e32 v8, v51, v19
	s_nop 0
	v_addc_co_u32_e32 v11, vcc, 0, v5, vcc
	global_load_dword v51, v[10:11], off nt
	s_mov_b32 s4, 0x22e000
	v_add_co_u32_e32 v10, vcc, s4, v4
	s_mov_b32 s4, 0x237000
	s_nop 0
	v_addc_co_u32_e32 v11, vcc, 0, v5, vcc
	v_fmac_f32_e32 v8, v52, v20
	global_load_dword v52, v[10:11], off nt
	v_add_co_u32_e32 v10, vcc, s4, v4
	s_waitcnt vmcnt(32)
	v_fmac_f32_e32 v0, v64, v12
	v_addc_co_u32_e32 v11, vcc, 0, v5, vcc
	v_fmac_f32_e32 v8, v53, v21
	s_waitcnt vmcnt(31)
	v_fmac_f32_e32 v0, v65, v13
	global_load_dword v53, v[10:11], off nt
	ds_read_b128 v[10:13], v9 offset:128
	s_waitcnt lgkmcnt(1)
	v_fmac_f32_e32 v7, v62, v14
	v_fmac_f32_e32 v7, v63, v15
	v_fmac_f32_e32 v7, v64, v16
	v_fmac_f32_e32 v7, v65, v17
	ds_read_b128 v[14:17], v9 offset:4224
	s_waitcnt vmcnt(31) lgkmcnt(1)
	v_fmac_f32_e32 v0, v22, v10
	s_waitcnt vmcnt(30)
	v_fmac_f32_e32 v0, v23, v11
	s_waitcnt vmcnt(29)
	v_fmac_f32_e32 v0, v24, v12
	s_waitcnt vmcnt(28)
	v_fmac_f32_e32 v0, v25, v13
	ds_read_b128 v[10:13], v9 offset:144
	s_waitcnt lgkmcnt(1)
	v_fmac_f32_e32 v7, v22, v14
	v_fmac_f32_e32 v7, v23, v15
	v_fmac_f32_e32 v7, v24, v16
	v_fmac_f32_e32 v7, v25, v17
	ds_read_b128 v[14:17], v9 offset:4240
	s_waitcnt vmcnt(27) lgkmcnt(1)
	v_fmac_f32_e32 v0, v26, v10
	s_waitcnt vmcnt(26)
	v_fmac_f32_e32 v0, v27, v11
	s_waitcnt vmcnt(25)
	v_fmac_f32_e32 v0, v28, v12
	s_waitcnt vmcnt(24)
	v_fmac_f32_e32 v0, v29, v13
	ds_read_b128 v[10:13], v9 offset:160
	s_waitcnt lgkmcnt(1)
	v_fmac_f32_e32 v7, v26, v14
	v_fmac_f32_e32 v7, v27, v15
	v_fmac_f32_e32 v7, v28, v16
	v_fmac_f32_e32 v7, v29, v17
	ds_read_b128 v[14:17], v9 offset:4256
	s_waitcnt vmcnt(23) lgkmcnt(1)
	v_fmac_f32_e32 v0, v30, v10
	s_waitcnt vmcnt(22)
	v_fmac_f32_e32 v0, v31, v11
	s_waitcnt vmcnt(21)
	v_fmac_f32_e32 v0, v32, v12
	s_waitcnt vmcnt(20)
	v_fmac_f32_e32 v0, v33, v13
	ds_read_b128 v[10:13], v9 offset:176
	s_waitcnt lgkmcnt(1)
	v_fmac_f32_e32 v7, v30, v14
	v_fmac_f32_e32 v7, v31, v15
	v_fmac_f32_e32 v7, v32, v16
	v_fmac_f32_e32 v7, v33, v17
	ds_read_b128 v[14:17], v9 offset:4272
	s_waitcnt vmcnt(19) lgkmcnt(1)
	v_fmac_f32_e32 v0, v34, v10
	s_waitcnt vmcnt(18)
	v_fmac_f32_e32 v0, v35, v11
	s_waitcnt vmcnt(17)
	v_fmac_f32_e32 v0, v36, v12
	s_waitcnt vmcnt(16)
	v_fmac_f32_e32 v0, v37, v13
	ds_read_b128 v[10:13], v9 offset:192
	ds_read_b128 v[18:21], v9 offset:8272
	s_waitcnt lgkmcnt(2)
	v_fmac_f32_e32 v7, v34, v14
	v_fmac_f32_e32 v7, v35, v15
	v_fmac_f32_e32 v7, v36, v16
	v_fmac_f32_e32 v7, v37, v17
	ds_read_b128 v[14:17], v9 offset:4288
	s_waitcnt vmcnt(15) lgkmcnt(2)
	v_fmac_f32_e32 v0, v38, v10
	s_waitcnt vmcnt(14)
	v_fmac_f32_e32 v0, v39, v11
	s_waitcnt lgkmcnt(1)
	v_fmac_f32_e32 v8, v54, v18
	s_waitcnt vmcnt(13)
	v_fmac_f32_e32 v0, v40, v12
	v_fmac_f32_e32 v8, v55, v19
	s_waitcnt vmcnt(12)
	v_fmac_f32_e32 v0, v41, v13
	ds_read_b128 v[10:13], v9 offset:208
	v_fmac_f32_e32 v8, v56, v20
	v_fmac_f32_e32 v8, v57, v21
	ds_read_b128 v[18:21], v9 offset:8288
	s_waitcnt lgkmcnt(2)
	v_fmac_f32_e32 v7, v38, v14
	v_fmac_f32_e32 v7, v39, v15
	v_fmac_f32_e32 v7, v40, v16
	v_fmac_f32_e32 v7, v41, v17
	ds_read_b128 v[14:17], v9 offset:4304
	s_waitcnt vmcnt(11) lgkmcnt(2)
	v_fmac_f32_e32 v0, v42, v10
	s_waitcnt vmcnt(10)
	v_fmac_f32_e32 v0, v43, v11
	s_waitcnt lgkmcnt(1)
	v_fmac_f32_e32 v8, v58, v18
	s_waitcnt vmcnt(9)
	v_fmac_f32_e32 v0, v44, v12
	v_fmac_f32_e32 v8, v59, v19
	s_waitcnt vmcnt(8)
	v_fmac_f32_e32 v0, v45, v13
	ds_read_b128 v[10:13], v9 offset:224
	v_fmac_f32_e32 v8, v60, v20
	v_fmac_f32_e32 v8, v61, v21
	ds_read_b128 v[18:21], v9 offset:8304
	s_waitcnt lgkmcnt(2)
	v_fmac_f32_e32 v7, v42, v14
	v_fmac_f32_e32 v7, v43, v15
	v_fmac_f32_e32 v7, v44, v16
	v_fmac_f32_e32 v7, v45, v17
	ds_read_b128 v[14:17], v9 offset:4320
	s_waitcnt vmcnt(7) lgkmcnt(2)
	v_fmac_f32_e32 v0, v46, v10
	s_waitcnt vmcnt(6)
	v_fmac_f32_e32 v0, v47, v11
	s_waitcnt lgkmcnt(1)
	v_fmac_f32_e32 v8, v62, v18
	s_waitcnt vmcnt(5)
	v_fmac_f32_e32 v0, v48, v12
	v_fmac_f32_e32 v8, v63, v19
	s_waitcnt vmcnt(4)
	v_fmac_f32_e32 v0, v49, v13
	ds_read_b128 v[10:13], v9 offset:240
	v_fmac_f32_e32 v8, v64, v20
	v_fmac_f32_e32 v8, v65, v21
	ds_read_b128 v[18:21], v9 offset:8320
	s_waitcnt lgkmcnt(2)
	v_fmac_f32_e32 v7, v46, v14
	v_fmac_f32_e32 v7, v47, v15
	v_fmac_f32_e32 v7, v48, v16
	s_mov_b32 s4, 0x240000
	v_fmac_f32_e32 v7, v49, v17
	ds_read_b128 v[14:17], v9 offset:4336
	s_waitcnt vmcnt(3) lgkmcnt(2)
	v_fmac_f32_e32 v0, v50, v10
	v_add_co_u32_e32 v10, vcc, s4, v4
	s_waitcnt vmcnt(2)
	v_fmac_f32_e32 v0, v51, v11
	v_addc_co_u32_e32 v11, vcc, 0, v5, vcc
	s_mov_b32 s4, 0x249000
	s_waitcnt lgkmcnt(1)
	v_fmac_f32_e32 v8, v22, v18
	global_load_dword v22, v[10:11], off nt
	v_add_co_u32_e32 v10, vcc, s4, v4
	v_fmac_f32_e32 v8, v23, v19
	s_nop 0
	v_addc_co_u32_e32 v11, vcc, 0, v5, vcc
	s_mov_b32 s4, 0x252000
	v_fmac_f32_e32 v8, v24, v20
	global_load_dword v23, v[10:11], off nt
	v_add_co_u32_e32 v10, vcc, s4, v4
	v_fmac_f32_e32 v8, v25, v21
	ds_read_b128 v[18:21], v9 offset:8336
	v_addc_co_u32_e32 v11, vcc, 0, v5, vcc
	s_mov_b32 s4, 0x25b000
	global_load_dword v24, v[10:11], off nt
	v_add_co_u32_e32 v10, vcc, s4, v4
	s_mov_b32 s4, 0x264000
	s_nop 0
	v_addc_co_u32_e32 v11, vcc, 0, v5, vcc
	global_load_dword v25, v[10:11], off nt
	v_add_co_u32_e32 v10, vcc, s4, v4
	s_mov_b32 s4, 0x26d000
	s_nop 0
	v_addc_co_u32_e32 v11, vcc, 0, v5, vcc
	s_waitcnt lgkmcnt(0)
	v_fmac_f32_e32 v8, v26, v18
	global_load_dword v26, v[10:11], off nt
	v_add_co_u32_e32 v10, vcc, s4, v4
	v_fmac_f32_e32 v8, v27, v19
	s_nop 0
	v_addc_co_u32_e32 v11, vcc, 0, v5, vcc
	s_mov_b32 s4, 0x276000
	v_fmac_f32_e32 v8, v28, v20
	global_load_dword v27, v[10:11], off nt
	v_add_co_u32_e32 v10, vcc, s4, v4
	v_fmac_f32_e32 v8, v29, v21
	ds_read_b128 v[18:21], v9 offset:8352
	v_addc_co_u32_e32 v11, vcc, 0, v5, vcc
	s_mov_b32 s4, 0x27f000
	global_load_dword v28, v[10:11], off nt
	v_add_co_u32_e32 v10, vcc, s4, v4
	s_mov_b32 s4, 0x288000
	s_nop 0
	v_addc_co_u32_e32 v11, vcc, 0, v5, vcc
	global_load_dword v29, v[10:11], off nt
	v_add_co_u32_e32 v10, vcc, s4, v4
	s_mov_b32 s4, 0x291000
	s_nop 0
	v_addc_co_u32_e32 v11, vcc, 0, v5, vcc
	s_waitcnt lgkmcnt(0)
	v_fmac_f32_e32 v8, v30, v18
	global_load_dword v30, v[10:11], off nt
	v_add_co_u32_e32 v10, vcc, s4, v4
	v_fmac_f32_e32 v8, v31, v19
	s_nop 0
	v_addc_co_u32_e32 v11, vcc, 0, v5, vcc
	s_mov_b32 s4, 0x29a000
	v_fmac_f32_e32 v8, v32, v20
	global_load_dword v31, v[10:11], off nt
	v_add_co_u32_e32 v10, vcc, s4, v4
	v_fmac_f32_e32 v8, v33, v21
	ds_read_b128 v[18:21], v9 offset:8368
	v_addc_co_u32_e32 v11, vcc, 0, v5, vcc
	s_mov_b32 s4, 0x2a3000
	global_load_dword v32, v[10:11], off nt
	v_add_co_u32_e32 v10, vcc, s4, v4
	s_mov_b32 s4, 0x2ac000
	s_nop 0
	v_addc_co_u32_e32 v11, vcc, 0, v5, vcc
	global_load_dword v33, v[10:11], off nt
	v_add_co_u32_e32 v10, vcc, s4, v4
	s_mov_b32 s4, 0x2b5000
	s_nop 0
	v_addc_co_u32_e32 v11, vcc, 0, v5, vcc
	s_waitcnt lgkmcnt(0)
	v_fmac_f32_e32 v8, v34, v18
	global_load_dword v34, v[10:11], off nt
	v_add_co_u32_e32 v10, vcc, s4, v4
	v_fmac_f32_e32 v8, v35, v19
	s_nop 0
	v_addc_co_u32_e32 v11, vcc, 0, v5, vcc
	s_mov_b32 s4, 0x2be000
	v_fmac_f32_e32 v8, v36, v20
	global_load_dword v35, v[10:11], off nt
	v_add_co_u32_e32 v10, vcc, s4, v4
	v_fmac_f32_e32 v8, v37, v21
	ds_read_b128 v[18:21], v9 offset:8384
	v_addc_co_u32_e32 v11, vcc, 0, v5, vcc
	s_mov_b32 s4, 0x2c7000
	global_load_dword v36, v[10:11], off nt
	v_add_co_u32_e32 v10, vcc, s4, v4
	s_mov_b32 s4, 0x2d0000
	s_nop 0
	v_addc_co_u32_e32 v11, vcc, 0, v5, vcc
	global_load_dword v37, v[10:11], off nt
	v_add_co_u32_e32 v10, vcc, s4, v4
	s_mov_b32 s4, 0x2d9000
	s_nop 0
	v_addc_co_u32_e32 v11, vcc, 0, v5, vcc
	s_waitcnt lgkmcnt(0)
	v_fmac_f32_e32 v8, v38, v18
	global_load_dword v38, v[10:11], off nt
	v_add_co_u32_e32 v10, vcc, s4, v4
	v_fmac_f32_e32 v8, v39, v19
	s_nop 0
	v_addc_co_u32_e32 v11, vcc, 0, v5, vcc
	s_mov_b32 s4, 0x2e2000
	v_fmac_f32_e32 v8, v40, v20
	global_load_dword v39, v[10:11], off nt
	v_add_co_u32_e32 v10, vcc, s4, v4
	v_fmac_f32_e32 v8, v41, v21
	ds_read_b128 v[18:21], v9 offset:8400
	v_addc_co_u32_e32 v11, vcc, 0, v5, vcc
	s_mov_b32 s4, 0x2eb000
	global_load_dword v40, v[10:11], off nt
	v_add_co_u32_e32 v10, vcc, s4, v4
	s_mov_b32 s4, 0x2f4000
	s_nop 0
	v_addc_co_u32_e32 v11, vcc, 0, v5, vcc
	global_load_dword v41, v[10:11], off nt
	v_add_co_u32_e32 v10, vcc, s4, v4
	s_mov_b32 s4, 0x2fd000
	s_nop 0
	v_addc_co_u32_e32 v11, vcc, 0, v5, vcc
	s_waitcnt lgkmcnt(0)
	v_fmac_f32_e32 v8, v42, v18
	global_load_dword v42, v[10:11], off nt
	v_add_co_u32_e32 v10, vcc, s4, v4
	v_fmac_f32_e32 v8, v43, v19
	s_nop 0
	v_addc_co_u32_e32 v11, vcc, 0, v5, vcc
	s_mov_b32 s4, 0x306000
	v_fmac_f32_e32 v8, v44, v20
	global_load_dword v43, v[10:11], off nt
	v_add_co_u32_e32 v10, vcc, s4, v4
	v_fmac_f32_e32 v8, v45, v21
	ds_read_b128 v[18:21], v9 offset:8416
	v_addc_co_u32_e32 v11, vcc, 0, v5, vcc
	s_mov_b32 s4, 0x30f000
	global_load_dword v44, v[10:11], off nt
	v_add_co_u32_e32 v10, vcc, s4, v4
	s_mov_b32 s4, 0x318000
	s_nop 0
	v_addc_co_u32_e32 v11, vcc, 0, v5, vcc
	global_load_dword v45, v[10:11], off nt
	v_add_co_u32_e32 v10, vcc, s4, v4
	s_mov_b32 s4, 0x321000
	s_nop 0
	v_addc_co_u32_e32 v11, vcc, 0, v5, vcc
	s_waitcnt lgkmcnt(0)
	v_fmac_f32_e32 v8, v46, v18
	global_load_dword v46, v[10:11], off nt
	v_add_co_u32_e32 v10, vcc, s4, v4
	s_mov_b32 s4, 0x32a000
	s_nop 0
	v_addc_co_u32_e32 v11, vcc, 0, v5, vcc
	v_fmac_f32_e32 v8, v47, v19
	global_load_dword v47, v[10:11], off nt
	v_add_co_u32_e32 v10, vcc, s4, v4
	s_mov_b32 s4, 0x333000
	s_nop 0
	v_addc_co_u32_e32 v11, vcc, 0, v5, vcc
	v_fmac_f32_e32 v8, v48, v20
	global_load_dword v48, v[10:11], off nt
	v_add_co_u32_e32 v10, vcc, s4, v4
	v_fmac_f32_e32 v8, v49, v21
	ds_read_b128 v[18:21], v9 offset:8432
	v_addc_co_u32_e32 v11, vcc, 0, v5, vcc
	global_load_dword v49, v[10:11], off nt
	s_mov_b32 s4, 0x33c000
	v_add_co_u32_e32 v10, vcc, s4, v4
	s_mov_b32 s4, 0x345000
	s_nop 0
	v_addc_co_u32_e32 v11, vcc, 0, v5, vcc
	v_fmac_f32_e32 v7, v50, v14
	s_waitcnt lgkmcnt(0)
	v_fmac_f32_e32 v8, v50, v18
	global_load_dword v50, v[10:11], off nt
	v_add_co_u32_e32 v10, vcc, s4, v4
	v_fmac_f32_e32 v7, v51, v15
	s_nop 0
	v_addc_co_u32_e32 v11, vcc, 0, v5, vcc
	v_fmac_f32_e32 v8, v51, v19
	global_load_dword v51, v[10:11], off nt
	s_mov_b32 s4, 0x34e000
	v_add_co_u32_e32 v10, vcc, s4, v4
	s_mov_b32 s4, 0x357000
	s_nop 0
	v_addc_co_u32_e32 v11, vcc, 0, v5, vcc
	s_waitcnt vmcnt(31)
	v_fmac_f32_e32 v0, v52, v12
	v_fmac_f32_e32 v7, v52, v16
	v_fmac_f32_e32 v8, v52, v20
	global_load_dword v52, v[10:11], off nt
	v_add_co_u32_e32 v10, vcc, s4, v4
	s_waitcnt vmcnt(31)
	v_fmac_f32_e32 v0, v53, v13
	v_addc_co_u32_e32 v11, vcc, 0, v5, vcc
	v_fmac_f32_e32 v7, v53, v17
	v_fmac_f32_e32 v8, v53, v21
	global_load_dword v53, v[10:11], off nt
	ds_read_b128 v[10:13], v9 offset:256
	ds_read_b128 v[14:17], v9 offset:4352
	ds_read_b128 v[18:21], v9 offset:8448
	s_mov_b32 s4, 0x360000
	s_waitcnt vmcnt(31) lgkmcnt(2)
	v_fmac_f32_e32 v0, v22, v10
	s_waitcnt vmcnt(30)
	v_fmac_f32_e32 v0, v23, v11
	s_waitcnt vmcnt(29)
	v_fmac_f32_e32 v0, v24, v12
	s_waitcnt vmcnt(28)
	v_fmac_f32_e32 v0, v25, v13
	ds_read_b128 v[10:13], v9 offset:272
	s_waitcnt lgkmcnt(2)
	v_fmac_f32_e32 v7, v22, v14
	v_fmac_f32_e32 v7, v23, v15
	v_fmac_f32_e32 v7, v24, v16
	v_fmac_f32_e32 v7, v25, v17
	ds_read_b128 v[14:17], v9 offset:4368
	s_waitcnt vmcnt(27) lgkmcnt(1)
	v_fmac_f32_e32 v0, v26, v10
	s_waitcnt vmcnt(26)
	v_fmac_f32_e32 v0, v27, v11
	s_waitcnt vmcnt(25)
	v_fmac_f32_e32 v0, v28, v12
	s_waitcnt vmcnt(24)
	v_fmac_f32_e32 v0, v29, v13
	ds_read_b128 v[10:13], v9 offset:288
	s_waitcnt lgkmcnt(1)
	v_fmac_f32_e32 v7, v26, v14
	v_fmac_f32_e32 v7, v27, v15
	v_fmac_f32_e32 v7, v28, v16
	v_fmac_f32_e32 v7, v29, v17
	ds_read_b128 v[14:17], v9 offset:4384
	s_waitcnt vmcnt(23) lgkmcnt(1)
	v_fmac_f32_e32 v0, v30, v10
	s_waitcnt vmcnt(22)
	v_fmac_f32_e32 v0, v31, v11
	s_waitcnt vmcnt(21)
	v_fmac_f32_e32 v0, v32, v12
	s_waitcnt vmcnt(20)
	v_fmac_f32_e32 v0, v33, v13
	ds_read_b128 v[10:13], v9 offset:304
	s_waitcnt lgkmcnt(1)
	v_fmac_f32_e32 v7, v30, v14
	v_fmac_f32_e32 v7, v31, v15
	v_fmac_f32_e32 v7, v32, v16
	v_fmac_f32_e32 v7, v33, v17
	ds_read_b128 v[14:17], v9 offset:4400
	s_waitcnt vmcnt(19) lgkmcnt(1)
	v_fmac_f32_e32 v0, v34, v10
	s_waitcnt vmcnt(18)
	v_fmac_f32_e32 v0, v35, v11
	s_waitcnt vmcnt(17)
	v_fmac_f32_e32 v0, v36, v12
	s_waitcnt vmcnt(16)
	v_fmac_f32_e32 v0, v37, v13
	ds_read_b128 v[10:13], v9 offset:320
	v_fmac_f32_e32 v8, v22, v18
	v_fmac_f32_e32 v8, v23, v19
	s_waitcnt lgkmcnt(1)
	v_fmac_f32_e32 v7, v34, v14
	v_fmac_f32_e32 v8, v24, v20
	v_fmac_f32_e32 v7, v35, v15
	v_fmac_f32_e32 v8, v25, v21
	ds_read_b128 v[18:21], v9 offset:8464
	v_fmac_f32_e32 v7, v36, v16
	v_fmac_f32_e32 v7, v37, v17
	ds_read_b128 v[14:17], v9 offset:4416
	s_waitcnt vmcnt(15) lgkmcnt(2)
	v_fmac_f32_e32 v0, v38, v10
	s_waitcnt vmcnt(14)
	v_fmac_f32_e32 v0, v39, v11
	s_waitcnt vmcnt(13)
	v_fmac_f32_e32 v0, v40, v12
	s_waitcnt vmcnt(12)
	v_fmac_f32_e32 v0, v41, v13
	ds_read_b128 v[10:13], v9 offset:336
	s_waitcnt lgkmcnt(2)
	v_fmac_f32_e32 v8, v26, v18
	v_fmac_f32_e32 v8, v27, v19
	s_waitcnt lgkmcnt(1)
	v_fmac_f32_e32 v7, v38, v14
	v_fmac_f32_e32 v8, v28, v20
	v_fmac_f32_e32 v7, v39, v15
	v_fmac_f32_e32 v8, v29, v21
	ds_read_b128 v[18:21], v9 offset:8480
	v_fmac_f32_e32 v7, v40, v16
	v_fmac_f32_e32 v7, v41, v17
	ds_read_b128 v[14:17], v9 offset:4432
	s_waitcnt vmcnt(11) lgkmcnt(2)
	v_fmac_f32_e32 v0, v42, v10
	s_waitcnt vmcnt(10)
	v_fmac_f32_e32 v0, v43, v11
	s_waitcnt vmcnt(9)
	v_fmac_f32_e32 v0, v44, v12
	s_waitcnt vmcnt(8)
	v_fmac_f32_e32 v0, v45, v13
	ds_read_b128 v[10:13], v9 offset:352
	s_waitcnt lgkmcnt(2)
	v_fmac_f32_e32 v8, v30, v18
	v_fmac_f32_e32 v8, v31, v19
	s_waitcnt lgkmcnt(1)
	v_fmac_f32_e32 v7, v42, v14
	v_fmac_f32_e32 v8, v32, v20
	v_fmac_f32_e32 v7, v43, v15
	v_fmac_f32_e32 v8, v33, v21
	ds_read_b128 v[18:21], v9 offset:8496
	v_fmac_f32_e32 v7, v44, v16
	v_fmac_f32_e32 v7, v45, v17
	ds_read_b128 v[14:17], v9 offset:4448
	s_waitcnt vmcnt(7) lgkmcnt(2)
	v_fmac_f32_e32 v0, v46, v10
	s_waitcnt vmcnt(6)
	v_fmac_f32_e32 v0, v47, v11
	s_waitcnt vmcnt(5)
	v_fmac_f32_e32 v0, v48, v12
	s_waitcnt vmcnt(4)
	v_fmac_f32_e32 v0, v49, v13
	ds_read_b128 v[10:13], v9 offset:368
	s_waitcnt lgkmcnt(2)
	v_fmac_f32_e32 v8, v34, v18
	v_fmac_f32_e32 v8, v35, v19
	s_waitcnt lgkmcnt(1)
	v_fmac_f32_e32 v7, v46, v14
	v_fmac_f32_e32 v8, v36, v20
	v_fmac_f32_e32 v7, v47, v15
	v_fmac_f32_e32 v8, v37, v21
	ds_read_b128 v[18:21], v9 offset:8512
	v_fmac_f32_e32 v7, v48, v16
	v_fmac_f32_e32 v7, v49, v17
	ds_read_b128 v[14:17], v9 offset:4464
	s_waitcnt vmcnt(3) lgkmcnt(2)
	v_fmac_f32_e32 v0, v50, v10
	v_add_co_u32_e32 v10, vcc, s4, v4
	s_waitcnt vmcnt(2)
	v_fmac_f32_e32 v0, v51, v11
	v_addc_co_u32_e32 v11, vcc, 0, v5, vcc
	s_mov_b32 s4, 0x369000
	global_load_dword v37, v[10:11], off nt
	v_add_co_u32_e32 v10, vcc, s4, v4
	s_mov_b32 s4, 0x372000
	s_nop 0
	v_addc_co_u32_e32 v11, vcc, 0, v5, vcc
	s_waitcnt lgkmcnt(1)
	v_fmac_f32_e32 v8, v38, v18
	global_load_dword v38, v[10:11], off nt
	v_add_co_u32_e32 v10, vcc, s4, v4
	s_mov_b32 s4, 0x37b000
	s_nop 0
	v_addc_co_u32_e32 v11, vcc, 0, v5, vcc
	v_fmac_f32_e32 v8, v39, v19
	global_load_dword v39, v[10:11], off nt
	v_add_co_u32_e32 v10, vcc, s4, v4
	v_fmac_f32_e32 v8, v40, v20
	s_nop 0
	v_addc_co_u32_e32 v11, vcc, 0, v5, vcc
	global_load_dword v40, v[10:11], off nt
	s_mov_b32 s4, 0x384000
	v_add_co_u32_e32 v10, vcc, s4, v4
	s_mov_b32 s4, 0x38d000
	s_nop 0
	v_addc_co_u32_e32 v11, vcc, 0, v5, vcc
	global_load_dword v25, v[10:11], off nt
	v_add_co_u32_e32 v10, vcc, s4, v4
	s_mov_b32 s4, 0x396000
	s_nop 0
	v_addc_co_u32_e32 v11, vcc, 0, v5, vcc
	global_load_dword v26, v[10:11], off nt
	v_add_co_u32_e32 v10, vcc, s4, v4
	s_mov_b32 s4, 0x39f000
	s_nop 0
	v_addc_co_u32_e32 v11, vcc, 0, v5, vcc
	global_load_dword v28, v[10:11], off nt
	v_add_co_u32_e32 v10, vcc, s4, v4
	s_mov_b32 s4, 0x3a8000
	s_nop 0
	v_addc_co_u32_e32 v11, vcc, 0, v5, vcc
	global_load_dword v30, v[10:11], off nt
	v_add_co_u32_e32 v10, vcc, s4, v4
	s_mov_b32 s4, 0x3b1000
	s_nop 0
	v_addc_co_u32_e32 v11, vcc, 0, v5, vcc
	global_load_dword v24, v[10:11], off nt
	v_add_co_u32_e32 v10, vcc, s4, v4
	s_mov_b32 s4, 0x3ba000
	s_nop 0
	v_addc_co_u32_e32 v11, vcc, 0, v5, vcc
	global_load_dword v27, v[10:11], off nt
	v_add_co_u32_e32 v10, vcc, s4, v4
	s_mov_b32 s4, 0x3c3000
	s_nop 0
	v_addc_co_u32_e32 v11, vcc, 0, v5, vcc
	global_load_dword v29, v[10:11], off nt
	v_add_co_u32_e32 v10, vcc, s4, v4
	v_fmac_f32_e32 v8, v41, v21
	ds_read_b128 v[18:21], v9 offset:8528
	v_addc_co_u32_e32 v11, vcc, 0, v5, vcc
	s_mov_b32 s4, 0x3cc000
	global_load_dword v32, v[10:11], off nt
	v_add_co_u32_e32 v10, vcc, s4, v4
	s_waitcnt vmcnt(13)
	v_fmac_f32_e32 v0, v52, v12
	v_addc_co_u32_e32 v11, vcc, 0, v5, vcc
	s_mov_b32 s4, 0x3d5000
	s_waitcnt vmcnt(12)
	v_fmac_f32_e32 v0, v53, v13
	global_load_dword v13, v[10:11], off nt
	v_add_co_u32_e32 v10, vcc, s4, v4
	s_mov_b32 s4, 0x3de000
	s_nop 0
	v_addc_co_u32_e32 v11, vcc, 0, v5, vcc
	s_waitcnt lgkmcnt(0)
	v_fmac_f32_e32 v8, v42, v18
	v_fmac_f32_e32 v7, v50, v14
	global_load_dword v14, v[10:11], off nt
	v_add_co_u32_e32 v10, vcc, s4, v4
	v_fmac_f32_e32 v8, v43, v19
	s_nop 0
	v_addc_co_u32_e32 v11, vcc, 0, v5, vcc
	s_mov_b32 s4, 0x3e7000
	v_fmac_f32_e32 v8, v44, v20
	v_fmac_f32_e32 v7, v51, v15
	global_load_dword v15, v[10:11], off nt
	v_add_co_u32_e32 v10, vcc, s4, v4
	v_fmac_f32_e32 v8, v45, v21
	ds_read_b128 v[18:21], v9 offset:8544
	v_addc_co_u32_e32 v11, vcc, 0, v5, vcc
	s_mov_b32 s4, 0x3f0000
	global_load_dword v34, v[10:11], off nt
	v_add_co_u32_e32 v10, vcc, s4, v4
	s_mov_b32 s4, 0x3f9000
	s_nop 0
	v_addc_co_u32_e32 v11, vcc, 0, v5, vcc
	global_load_dword v31, v[10:11], off nt
	v_add_co_u32_e32 v10, vcc, s4, v4
	s_mov_b32 s4, 0x402000
	s_nop 0
	v_addc_co_u32_e32 v11, vcc, 0, v5, vcc
	s_waitcnt lgkmcnt(0)
	v_fmac_f32_e32 v8, v46, v18
	global_load_dword v33, v[10:11], off nt
	v_add_co_u32_e32 v10, vcc, s4, v4
	v_fmac_f32_e32 v8, v47, v19
	s_nop 0
	v_addc_co_u32_e32 v11, vcc, 0, v5, vcc
	s_mov_b32 s4, 0x40b000
	v_fmac_f32_e32 v8, v48, v20
	global_load_dword v35, v[10:11], off nt
	v_add_co_u32_e32 v10, vcc, s4, v4
	v_fmac_f32_e32 v8, v49, v21
	ds_read_b128 v[18:21], v9 offset:8560
	v_addc_co_u32_e32 v11, vcc, 0, v5, vcc
	s_mov_b32 s4, 0x414000
	global_load_dword v36, v[10:11], off nt
	v_add_co_u32_e32 v10, vcc, s4, v4
	v_fmac_f32_e32 v7, v52, v16
	s_nop 0
	v_addc_co_u32_e32 v11, vcc, 0, v5, vcc
	s_mov_b32 s4, 0x41d000
	v_fmac_f32_e32 v7, v53, v17
	global_load_dword v17, v[10:11], off nt
	v_add_co_u32_e32 v10, vcc, s4, v4
	s_mov_b32 s4, 0x426000
	s_nop 0
	v_addc_co_u32_e32 v11, vcc, 0, v5, vcc
	s_waitcnt lgkmcnt(0)
	v_fmac_f32_e32 v8, v50, v18
	global_load_dword v18, v[10:11], off nt
	v_add_co_u32_e32 v10, vcc, s4, v4
	v_fmac_f32_e32 v8, v51, v19
	s_nop 0
	v_addc_co_u32_e32 v11, vcc, 0, v5, vcc
	s_mov_b32 s4, 0x42f000
	v_fmac_f32_e32 v8, v52, v20
	global_load_dword v20, v[10:11], off nt
	v_add_co_u32_e32 v10, vcc, s4, v4
	s_mov_b32 s4, 0x438000
	s_nop 0
	v_addc_co_u32_e32 v11, vcc, 0, v5, vcc
	global_load_dword v22, v[10:11], off nt
	v_add_co_u32_e32 v10, vcc, s4, v4
	s_mov_b32 s4, 0x441000
	s_nop 0
	v_addc_co_u32_e32 v11, vcc, 0, v5, vcc
	global_load_dword v16, v[10:11], off nt
	v_add_co_u32_e32 v10, vcc, s4, v4
	s_mov_b32 s4, 0x44a000
	s_nop 0
	v_addc_co_u32_e32 v11, vcc, 0, v5, vcc
	global_load_dword v19, v[10:11], off nt
	v_add_co_u32_e32 v10, vcc, s4, v4
	s_mov_b32 s4, 0x453000
	s_nop 0
	v_addc_co_u32_e32 v11, vcc, 0, v5, vcc
	v_fmac_f32_e32 v8, v53, v21
	global_load_dword v21, v[10:11], off nt
	v_add_co_u32_e32 v10, vcc, s4, v4
	s_mov_b32 s4, 0x45c000
	s_nop 0
	v_addc_co_u32_e32 v11, vcc, 0, v5, vcc
	global_load_dword v23, v[10:11], off nt
	v_add_co_u32_e32 v10, vcc, s4, v4
	s_mov_b32 s4, 0x465000
	s_nop 0
	v_addc_co_u32_e32 v11, vcc, 0, v5, vcc
	v_add_co_u32_e32 v42, vcc, s4, v4
	s_mov_b32 s4, 0x46e000
	s_nop 0
	v_addc_co_u32_e32 v43, vcc, 0, v5, vcc
	global_load_dword v10, v[10:11], off nt
	ds_read_b128 v[46:49], v9 offset:4480
	global_load_dword v11, v[42:43], off nt
	v_add_co_u32_e32 v42, vcc, s4, v4
	s_mov_b32 s4, 0x477000
	s_nop 0
	v_addc_co_u32_e32 v43, vcc, 0, v5, vcc
	v_add_co_u32_e32 v4, vcc, s4, v4
	global_load_dword v12, v[42:43], off nt
	s_nop 0
	v_addc_co_u32_e32 v5, vcc, 0, v5, vcc
	global_load_dword v4, v[4:5], off nt
	ds_read_b128 v[42:45], v9 offset:384
	ds_read_b128 v[50:53], v9 offset:8576
	s_waitcnt vmcnt(31) lgkmcnt(2)
	v_fmac_f32_e32 v7, v37, v46
	s_waitcnt vmcnt(30)
	v_fmac_f32_e32 v7, v38, v47
	s_waitcnt vmcnt(29)
	v_fmac_f32_e32 v7, v39, v48
	s_waitcnt lgkmcnt(1)
	v_fmac_f32_e32 v0, v37, v42
	s_waitcnt vmcnt(28)
	v_fmac_f32_e32 v7, v40, v49
	ds_read_b128 v[46:49], v9 offset:8592
	s_waitcnt lgkmcnt(1)
	v_fmac_f32_e32 v8, v37, v50
	v_fmac_f32_e32 v0, v38, v43
	v_fmac_f32_e32 v8, v38, v51
	v_fmac_f32_e32 v0, v39, v44
	v_fmac_f32_e32 v8, v39, v52
	v_fmac_f32_e32 v0, v40, v45
	v_fmac_f32_e32 v8, v40, v53
	ds_read_b128 v[38:41], v9 offset:400
	ds_read_b128 v[42:45], v9 offset:4496
	s_waitcnt vmcnt(27) lgkmcnt(2)
	v_fmac_f32_e32 v8, v25, v46
	s_waitcnt vmcnt(26)
	v_fmac_f32_e32 v8, v26, v47
	s_waitcnt vmcnt(25)
	v_fmac_f32_e32 v8, v28, v48
	s_waitcnt lgkmcnt(1)
	v_fmac_f32_e32 v0, v25, v38
	s_waitcnt lgkmcnt(0)
	v_fmac_f32_e32 v7, v25, v42
	v_fmac_f32_e32 v0, v26, v39
	v_fmac_f32_e32 v7, v26, v43
	v_fmac_f32_e32 v0, v28, v40
	v_fmac_f32_e32 v7, v28, v44
	s_waitcnt vmcnt(24)
	v_fmac_f32_e32 v0, v30, v41
	v_fmac_f32_e32 v7, v30, v45
	ds_read_b128 v[38:41], v9 offset:416
	ds_read_b128 v[42:45], v9 offset:4512
	v_fmac_f32_e32 v8, v30, v49
	ds_read_b128 v[46:49], v9 offset:8608
	s_waitcnt vmcnt(23) lgkmcnt(2)
	v_fmac_f32_e32 v0, v24, v38
	s_waitcnt lgkmcnt(1)
	v_fmac_f32_e32 v7, v24, v42
	s_waitcnt vmcnt(22)
	v_fmac_f32_e32 v7, v27, v43
	s_waitcnt vmcnt(21)
	v_fmac_f32_e32 v7, v29, v44
	v_fmac_f32_e32 v0, v27, v39
	s_waitcnt vmcnt(20)
	v_fmac_f32_e32 v7, v32, v45
	ds_read_b128 v[42:45], v9 offset:8624
	s_waitcnt lgkmcnt(1)
	v_fmac_f32_e32 v8, v24, v46
	v_fmac_f32_e32 v8, v27, v47
	v_fmac_f32_e32 v0, v29, v40
	ds_read_b128 v[24:27], v9 offset:432
	v_fmac_f32_e32 v0, v32, v41
	ds_read_b128 v[38:41], v9 offset:4528
	v_fmac_f32_e32 v8, v29, v48
	v_fmac_f32_e32 v8, v32, v49
	s_waitcnt vmcnt(19) lgkmcnt(1)
	v_fmac_f32_e32 v0, v13, v24
	v_fmac_f32_e32 v8, v13, v42
	s_waitcnt lgkmcnt(0)
	v_fmac_f32_e32 v7, v13, v38
	s_waitcnt vmcnt(18)
	v_fmac_f32_e32 v0, v14, v25
	v_fmac_f32_e32 v7, v14, v39
	v_fmac_f32_e32 v8, v14, v43
	s_waitcnt vmcnt(17)
	v_fmac_f32_e32 v0, v15, v26
	v_fmac_f32_e32 v7, v15, v40
	v_fmac_f32_e32 v8, v15, v44
	s_waitcnt vmcnt(16)
	v_fmac_f32_e32 v0, v34, v27
	ds_read_b128 v[24:27], v9 offset:448
	v_fmac_f32_e32 v7, v34, v41
	v_fmac_f32_e32 v8, v34, v45
	ds_read_b128 v[38:41], v9 offset:4544
	ds_read_b128 v[42:45], v9 offset:8640
	s_waitcnt vmcnt(15) lgkmcnt(2)
	v_fmac_f32_e32 v0, v31, v24
	s_waitcnt vmcnt(14)
	v_fmac_f32_e32 v0, v33, v25
	s_waitcnt vmcnt(13)
	v_fmac_f32_e32 v0, v35, v26
	s_waitcnt lgkmcnt(1)
	v_fmac_f32_e32 v7, v31, v38
	s_waitcnt lgkmcnt(0)
	v_fmac_f32_e32 v8, v31, v42
	v_fmac_f32_e32 v7, v33, v39
	v_fmac_f32_e32 v8, v33, v43
	v_fmac_f32_e32 v7, v35, v40
	v_fmac_f32_e32 v8, v35, v44
	s_waitcnt vmcnt(12)
	v_fmac_f32_e32 v0, v36, v27
	ds_read_b128 v[24:27], v9 offset:464
	ds_read_b128 v[28:31], v9 offset:4560
	ds_read_b128 v[32:35], v9 offset:8656
	v_fmac_f32_e32 v7, v36, v41
	v_fmac_f32_e32 v8, v36, v45
	s_waitcnt vmcnt(11) lgkmcnt(2)
	v_fmac_f32_e32 v0, v17, v24
	s_waitcnt lgkmcnt(1)
	v_fmac_f32_e32 v7, v17, v28
	s_waitcnt lgkmcnt(0)
	v_fmac_f32_e32 v8, v17, v32
	s_waitcnt vmcnt(10)
	v_fmac_f32_e32 v0, v18, v25
	v_fmac_f32_e32 v7, v18, v29
	v_fmac_f32_e32 v8, v18, v33
	s_waitcnt vmcnt(9)
	v_fmac_f32_e32 v0, v20, v26
	v_fmac_f32_e32 v7, v20, v30
	v_fmac_f32_e32 v8, v20, v34
	s_waitcnt vmcnt(8)
	v_fmac_f32_e32 v0, v22, v27
	v_fmac_f32_e32 v7, v22, v31
	v_fmac_f32_e32 v8, v22, v35
	ds_read_b128 v[24:27], v9 offset:480
	ds_read_b128 v[28:31], v9 offset:4576
	ds_read_b128 v[32:35], v9 offset:8672
	s_waitcnt vmcnt(7) lgkmcnt(2)
	v_fmac_f32_e32 v0, v16, v24
	s_waitcnt lgkmcnt(1)
	v_fmac_f32_e32 v7, v16, v28
	s_waitcnt lgkmcnt(0)
	v_fmac_f32_e32 v8, v16, v32
	s_waitcnt vmcnt(6)
	v_fmac_f32_e32 v0, v19, v25
	v_fmac_f32_e32 v7, v19, v29
	v_fmac_f32_e32 v8, v19, v33
	s_waitcnt vmcnt(5)
	v_fmac_f32_e32 v0, v21, v26
	v_fmac_f32_e32 v7, v21, v30
	v_fmac_f32_e32 v8, v21, v34
	ds_read_b128 v[14:17], v9 offset:496
	ds_read_b128 v[18:21], v9 offset:4592
	s_waitcnt vmcnt(4)
	v_fmac_f32_e32 v0, v23, v27
	v_fmac_f32_e32 v7, v23, v31
	v_fmac_f32_e32 v8, v23, v35
	ds_read_b128 v[22:25], v9 offset:8688
	s_waitcnt vmcnt(3) lgkmcnt(2)
	v_fmac_f32_e32 v0, v10, v14
	s_waitcnt lgkmcnt(1)
	v_fmac_f32_e32 v7, v10, v18
	s_waitcnt vmcnt(2)
	v_fmac_f32_e32 v0, v11, v15
	v_fmac_f32_e32 v7, v11, v19
	s_waitcnt lgkmcnt(0)
	v_fmac_f32_e32 v8, v10, v22
	v_fmac_f32_e32 v8, v11, v23
	s_waitcnt vmcnt(1)
	v_fmac_f32_e32 v0, v12, v16
	v_fmac_f32_e32 v7, v12, v20
	v_fmac_f32_e32 v8, v12, v24
	s_waitcnt vmcnt(0)
	v_fmac_f32_e32 v0, v4, v17
	v_fmac_f32_e32 v7, v4, v21
	v_fmac_f32_e32 v8, v4, v25
	ds_write2st64_b32 v6, v0, v7 offset0:48 offset1:49
	ds_write_b32 v6, v8 offset:12800
	s_waitcnt lgkmcnt(0)
	s_barrier
	s_and_saveexec_b64 s[4:5], s[6:7]
	s_cbranch_execz .LBB0_1201
	s_mul_i32 s6, s8, 0x2400
	v_lshlrev_b32_e32 v0, 2, v3
	v_lshlrev_b32_e32 v6, 8, v2
	s_add_i32 s6, s6, s9
	v_add3_u32 v8, 0, v0, v6
	v_add_u32_e32 v6, s6, v3
	v_mov_b32_e32 v4, s10
	v_mov_b32_e32 v5, s11
	v_ashrrev_i32_e32 v7, 31, v6
	v_lshl_add_u64 v[4:5], v[6:7], 2, v[4:5]
	global_load_dword v3, v[4:5], off
	ds_read2st64_b32 v[4:5], v8 offset0:48 offset1:51
	s_waitcnt vmcnt(0) lgkmcnt(0)
	v_add_f32_e32 v3, v3, v4
	v_add_f32_e32 v3, v3, v5
	ds_read2st64_b32 v[4:5], v8 offset0:54 offset1:57
	s_waitcnt lgkmcnt(0)
	v_add_f32_e32 v3, v3, v4
	v_add_f32_e32 v3, v3, v5
	ds_read2st64_b32 v[4:5], v8 offset0:60 offset1:63
	s_waitcnt lgkmcnt(0)
	v_add_f32_e32 v3, v3, v4
	v_add_f32_e32 v3, v3, v5
	ds_read2st64_b32 v[4:5], v8 offset0:66 offset1:69
	s_waitcnt lgkmcnt(0)
	v_add_f32_e32 v3, v3, v4
	v_add_f32_e32 v6, v3, v5
	v_mad_u64_u32 v[2:3], s[6:7], s8, 3, v[2:3]
	v_mov_b64_e32 v[4:5], s[68:69]
	v_mad_i64_i32 v[2:3], s[6:7], v2, s87, v[4:5]
	v_lshl_add_u64 v[2:3], v[2:3], 0, s[80:81]
	v_lshl_add_u64 v[2:3], v[2:3], 0, v[0:1]
	global_store_dword v[2:3], v6, off
